# GEMM K loops: s_setprio 1 from the k-tile barrier to the 8th MFMA, 0 for the LDS-store half
# speedup vs baseline: 1.0038x; 1.0038x over previous
; #define MFMA(a, b, c) __builtin_amdgcn_mfma_f32_32x32x16_bf16((a), (b), (c), 0, 0, 0)
; template <class Epi, class ColV>
; DI void gemm_tile(const bf16_t* __restrict__ A, int lda, const bf16_t* __restrict__ Bt, int ldb, int K, int m0, int n0, unsigned char* smem, Epi epi, ColV colv, const bf16_t* __restrict__ HYT = nullptr) {
;     ...
;     auto gload = [&](u32x4 (&r)[8], int kt) {
; #pragma unroll
;         for (int i = 0; i < 4; ++i) { int id = tid + 256 * i, row = id >> 3, kc = id & 7;
;             if (HYT && kt >= 12) r[i] = *(const u32x4*)(HYT + (size_t)((kt - 12) * 64 + (id >> 4)) * NT + m0 + (id & 15) * 8);
;             else r[i] = *(const u32x4*)(A + (size_t)(m0 + row) * lda + kt * 64 + kc * 8);
;             r[4 + i] = *(const u32x4*)(Bt + (size_t)(n0 + row) * ldb + kt * 64 + kc * 8); }
;     };
;     auto sstore = [&](const u32x4 (&r)[8], int buf, int kt) {
; #pragma unroll
;         for (int i = 0; i < 4; ++i) { int id = tid + 256 * i, row = id >> 3, kc = id & 7;
;             if (HYT && kt >= 12) { const int kk = id >> 4, rr = (id & 15) * 8; bf16_t* d = As + (buf * 128 + rr) * LS + kk; const bf16x8 v = __builtin_bit_cast(bf16x8, r[i]);
; #pragma unroll
;                 for (int e = 0; e < 8; ++e) d[e * LS] = (bf16_t)v[e]; }
;             else *(u32x4*)(As + (buf * 128 + row) * LS + kc * 8) = r[i];
;             *(u32x4*)(Bs + (buf * 128 + row) * LS + kc * 8) = r[4 + i]; }
;     };
;     auto step = [&](int kt, u32x4 (&ldset)[8], const u32x4 (&stset)[8]) {
;         const int buf = kt & 1;
;         if (kt + 2 < nk) gload(ldset, kt + 2);
;         const bf16_t* Ab = As + (buf * 128 + 64 * wr + li) * LS + 8 * lh;
;         const bf16_t* Bb = Bs + (buf * 128 + 64 * wc + li) * LS + 8 * lh;
;         bf16x8 fa[2][2], fb[2][2], ga[2][2], gb[2][2];
; #pragma unroll
;         for (int k2 = 0; k2 < 2; ++k2) { fa[k2][0] = ld8(Ab + 16 * k2); fa[k2][1] = ld8(Ab + 32 * LS + 16 * k2); fb[k2][0] = ld8(Bb + 16 * k2); fb[k2][1] = ld8(Bb + 32 * LS + 16 * k2); }
;         __builtin_amdgcn_sched_barrier(0);
; #pragma unroll
;         for (int k2 = 0; k2 < 2; ++k2) {
;             acc[0][0] = MFMA(fa[k2][0], fb[k2][0], acc[0][0]); acc[0][1] = MFMA(fa[k2][0], fb[k2][1], acc[0][1]);
;             acc[1][0] = MFMA(fa[k2][1], fb[k2][0], acc[1][0]); acc[1][1] = MFMA(fa[k2][1], fb[k2][1], acc[1][1]);
;         }
; #pragma unroll
.Lg3_phase11:
	ds_read_b128 v[174:177], v194
	ds_read_b128 v[210:213], v195 offset:36864
	ds_read_b128 v[218:221], v195 offset:41472
	ds_read_b128 v[202:205], v194 offset:4608
	ds_read_b128 v[178:181], v194 offset:32
	ds_read_b128 v[222:225], v195 offset:41504
	ds_read_b128 v[206:209], v194 offset:4640
	ds_read_b128 v[214:217], v195 offset:36896
	s_waitcnt lgkmcnt(6)
	v_mfma_f32_32x32x16_bf16 v[52:67], v[174:177], v[210:213], v[52:67]
	global_load_dwordx4 v[68:71], v[164:165], off offset:384
	s_waitcnt lgkmcnt(5)
	v_mfma_f32_32x32x16_bf16 v[36:51], v[174:177], v[218:221], v[36:51]
	global_load_dwordx4 v[72:75], v[162:163], off offset:384
	s_waitcnt lgkmcnt(4)
	v_mfma_f32_32x32x16_bf16 v[4:19], v[202:205], v[218:221], v[4:19]
	global_load_dwordx4 v[76:79], v[160:161], off offset:384
	s_waitcnt lgkmcnt(2)
	v_mfma_f32_32x32x16_bf16 v[36:51], v[178:181], v[222:225], v[36:51]
	global_load_dwordx4 v[80:83], v[158:159], off offset:384
	s_waitcnt lgkmcnt(1)
	v_mfma_f32_32x32x16_bf16 v[4:19], v[206:209], v[222:225], v[4:19]
	global_load_dwordx4 v[84:87], v[156:157], off offset:384
	ds_read_b128 v[222:225], v195 offset:41568
	ds_read_b128 v[174:177], v194 offset:4672
	v_mfma_f32_32x32x16_bf16 v[20:35], v[202:205], v[210:213], v[20:35]
	global_load_dwordx4 v[92:95], v[154:155], off offset:384
	ds_read_b128 v[210:213], v194 offset:4704
	ds_read_b128 v[202:205], v194 offset:64
	s_waitcnt lgkmcnt(4)
	v_mfma_f32_32x32x16_bf16 v[52:67], v[178:181], v[214:217], v[52:67]
	global_load_dwordx4 v[104:107], v[152:153], off offset:384
	ds_read_b128 v[218:221], v195 offset:36960
	ds_read_b128 v[178:181], v195 offset:41536
	v_mfma_f32_32x32x16_bf16 v[20:35], v[206:209], v[214:217], v[20:35]
	s_setprio 0
	global_load_dwordx4 v[112:115], v[146:147], off offset:384
	ds_read_b128 v[214:217], v195 offset:36928
	ds_read_b128 v[206:209], v194 offset:96
	s_waitcnt lgkmcnt(1)
	v_mfma_f32_32x32x16_bf16 v[52:67], v[202:205], v[214:217], v[52:67]
	s_waitcnt vmcnt(23)
	ds_write_b128 v190, v[88:91] offset:18432
	v_mfma_f32_32x32x16_bf16 v[36:51], v[202:205], v[178:181], v[36:51]
	s_waitcnt vmcnt(22)
	ds_write_b128 v190, v[96:99] offset:55296
	v_mfma_f32_32x32x16_bf16 v[20:35], v[174:177], v[214:217], v[20:35]
	s_waitcnt vmcnt(21)
	ds_write_b128 v191, v[100:103] offset:18432
	v_mfma_f32_32x32x16_bf16 v[4:19], v[174:177], v[178:181], v[4:19]
	s_waitcnt vmcnt(20)
	ds_write_b128 v191, v[108:111] offset:55296
	s_waitcnt lgkmcnt(4)
	v_mfma_f32_32x32x16_bf16 v[52:67], v[206:209], v[218:221], v[52:67]
	s_waitcnt vmcnt(19)
	ds_write_b128 v192, v[116:119] offset:18432
	v_mfma_f32_32x32x16_bf16 v[36:51], v[206:209], v[222:225], v[36:51]
	s_waitcnt vmcnt(18)
	ds_write_b128 v192, v[120:123] offset:55296
	v_mfma_f32_32x32x16_bf16 v[20:35], v[210:213], v[218:221], v[20:35]
	s_waitcnt vmcnt(17)
	ds_write_b128 v193, v[124:127] offset:18432
	v_mfma_f32_32x32x16_bf16 v[4:19], v[210:213], v[222:225], v[4:19]
	s_waitcnt vmcnt(16)
	ds_write_b128 v193, v[128:131] offset:55296
	s_waitcnt lgkmcnt(0)
	s_barrier
	s_setprio 1
	ds_read_b128 v[174:177], v196
	ds_read_b128 v[210:213], v197 offset:36864
	ds_read_b128 v[218:221], v197 offset:41472
	ds_read_b128 v[202:205], v196 offset:4608
	ds_read_b128 v[178:181], v196 offset:32
	ds_read_b128 v[222:225], v197 offset:41504
	ds_read_b128 v[206:209], v196 offset:4640
	ds_read_b128 v[214:217], v197 offset:36896
	s_waitcnt lgkmcnt(6)
	v_mfma_f32_32x32x16_bf16 v[52:67], v[174:177], v[210:213], v[52:67]
	global_load_dwordx4 v[88:91], v[164:165], off offset:512
	s_waitcnt lgkmcnt(5)
	v_mfma_f32_32x32x16_bf16 v[36:51], v[174:177], v[218:221], v[36:51]
	global_load_dwordx4 v[96:99], v[162:163], off offset:512
	s_waitcnt lgkmcnt(4)
	v_mfma_f32_32x32x16_bf16 v[4:19], v[202:205], v[218:221], v[4:19]
	global_load_dwordx4 v[100:103], v[160:161], off offset:512
	s_waitcnt lgkmcnt(2)
	v_mfma_f32_32x32x16_bf16 v[36:51], v[178:181], v[222:225], v[36:51]
	global_load_dwordx4 v[108:111], v[158:159], off offset:512
	s_waitcnt lgkmcnt(1)
	v_mfma_f32_32x32x16_bf16 v[4:19], v[206:209], v[222:225], v[4:19]
	global_load_dwordx4 v[116:119], v[156:157], off offset:512
	ds_read_b128 v[222:225], v197 offset:41568
	ds_read_b128 v[174:177], v196 offset:4672
	v_mfma_f32_32x32x16_bf16 v[20:35], v[202:205], v[210:213], v[20:35]
	global_load_dwordx4 v[120:123], v[154:155], off offset:512
	ds_read_b128 v[210:213], v196 offset:4704
	ds_read_b128 v[202:205], v196 offset:64
	s_waitcnt lgkmcnt(4)
	v_mfma_f32_32x32x16_bf16 v[52:67], v[178:181], v[214:217], v[52:67]
	global_load_dwordx4 v[124:127], v[152:153], off offset:512
	ds_read_b128 v[218:221], v197 offset:36960
	ds_read_b128 v[178:181], v197 offset:41536
	v_mfma_f32_32x32x16_bf16 v[20:35], v[206:209], v[214:217], v[20:35]
	s_setprio 0
	global_load_dwordx4 v[128:131], v[146:147], off offset:512
	ds_read_b128 v[214:217], v197 offset:36928
	ds_read_b128 v[206:209], v196 offset:96
	s_waitcnt lgkmcnt(1)
	v_mfma_f32_32x32x16_bf16 v[52:67], v[202:205], v[214:217], v[52:67]
	s_waitcnt vmcnt(23)
	ds_write_b128 v190, v[132:135]
	v_mfma_f32_32x32x16_bf16 v[36:51], v[202:205], v[178:181], v[36:51]
	s_waitcnt vmcnt(22)
	ds_write_b128 v190, v[136:139] offset:36864
	v_mfma_f32_32x32x16_bf16 v[20:35], v[174:177], v[214:217], v[20:35]
	s_waitcnt vmcnt(21)
	ds_write_b128 v191, v[140:143]
	v_mfma_f32_32x32x16_bf16 v[4:19], v[174:177], v[178:181], v[4:19]
	s_waitcnt vmcnt(20)
	ds_write_b128 v191, v[198:201] offset:36864
	s_waitcnt lgkmcnt(4)
	v_mfma_f32_32x32x16_bf16 v[52:67], v[206:209], v[218:221], v[52:67]
	s_waitcnt vmcnt(19)
	ds_write_b128 v192, v[226:229]
	v_mfma_f32_32x32x16_bf16 v[36:51], v[206:209], v[222:225], v[36:51]
	s_waitcnt vmcnt(18)
	ds_write_b128 v192, v[230:233] offset:36864
	v_mfma_f32_32x32x16_bf16 v[20:35], v[210:213], v[218:221], v[20:35]
	s_waitcnt vmcnt(17)
	ds_write_b128 v193, v[242:245]
	v_mfma_f32_32x32x16_bf16 v[4:19], v[210:213], v[222:225], v[4:19]
	s_waitcnt vmcnt(16)
	ds_write_b128 v193, v[246:249] offset:36864
	s_waitcnt lgkmcnt(0)
	s_barrier
; #define MFMA(a, b, c) __builtin_amdgcn_mfma_f32_32x32x16_bf16((a), (b), (c), 0, 0, 0)
; template <class Epi, class ColV>
; DI void gemm_tile(const bf16_t* __restrict__ A, int lda, const bf16_t* __restrict__ Bt, int ldb, int K, int m0, int n0, unsigned char* smem, Epi epi, ColV colv, const bf16_t* __restrict__ HYT = nullptr) {
;     ...
;     auto gload = [&](u32x4 (&r)[8], int kt) {
; #pragma unroll
;         for (int i = 0; i < 4; ++i) { int id = tid + 256 * i, row = id >> 3, kc = id & 7;
;             if (HYT && kt >= 12) r[i] = *(const u32x4*)(HYT + (size_t)((kt - 12) * 64 + (id >> 4)) * NT + m0 + (id & 15) * 8);
;             else r[i] = *(const u32x4*)(A + (size_t)(m0 + row) * lda + kt * 64 + kc * 8);
;             r[4 + i] = *(const u32x4*)(Bt + (size_t)(n0 + row) * ldb + kt * 64 + kc * 8); }
;     };
;     auto sstore = [&](const u32x4 (&r)[8], int buf, int kt) {
; #pragma unroll
;         for (int i = 0; i < 4; ++i) { int id = tid + 256 * i, row = id >> 3, kc = id & 7;
;             if (HYT && kt >= 12) { const int kk = id >> 4, rr = (id & 15) * 8; bf16_t* d = As + (buf * 128 + rr) * LS + kk; const bf16x8 v = __builtin_bit_cast(bf16x8, r[i]);
; #pragma unroll
;                 for (int e = 0; e < 8; ++e) d[e * LS] = (bf16_t)v[e]; }
;             else *(u32x4*)(As + (buf * 128 + row) * LS + kc * 8) = r[i];
;             *(u32x4*)(Bs + (buf * 128 + row) * LS + kc * 8) = r[4 + i]; }
;     };
;     auto step = [&](int kt, u32x4 (&ldset)[8], const u32x4 (&stset)[8]) {
;         const int buf = kt & 1;
;         if (kt + 2 < nk) gload(ldset, kt + 2);
;         const bf16_t* Ab = As + (buf * 128 + 64 * wr + li) * LS + 8 * lh;
;         const bf16_t* Bb = Bs + (buf * 128 + 64 * wc + li) * LS + 8 * lh;
;         bf16x8 fa[2][2], fb[2][2], ga[2][2], gb[2][2];
; #pragma unroll
;         for (int k2 = 0; k2 < 2; ++k2) { fa[k2][0] = ld8(Ab + 16 * k2); fa[k2][1] = ld8(Ab + 32 * LS + 16 * k2); fb[k2][0] = ld8(Bb + 16 * k2); fb[k2][1] = ld8(Bb + 32 * LS + 16 * k2); }
;         __builtin_amdgcn_sched_barrier(0);
; #pragma unroll
;         for (int k2 = 0; k2 < 2; ++k2) {
;             acc[0][0] = MFMA(fa[k2][0], fb[k2][0], acc[0][0]); acc[0][1] = MFMA(fa[k2][0], fb[k2][1], acc[0][1]);
;             acc[1][0] = MFMA(fa[k2][1], fb[k2][0], acc[1][0]); acc[1][1] = MFMA(fa[k2][1], fb[k2][1], acc[1][1]);
;         }
; #pragma unroll
	s_setprio 1
	ds_read_b128 v[174:177], v194
	ds_read_b128 v[210:213], v195 offset:36864
	ds_read_b128 v[218:221], v195 offset:41472
	ds_read_b128 v[202:205], v194 offset:4608
	ds_read_b128 v[178:181], v194 offset:32
	ds_read_b128 v[222:225], v195 offset:41504
	ds_read_b128 v[206:209], v194 offset:4640
	ds_read_b128 v[214:217], v195 offset:36896
	s_waitcnt lgkmcnt(6)
	v_mfma_f32_32x32x16_bf16 v[52:67], v[174:177], v[210:213], v[52:67]
	global_load_dwordx4 v[132:135], v[164:165], off offset:640
	s_waitcnt lgkmcnt(5)
	v_mfma_f32_32x32x16_bf16 v[36:51], v[174:177], v[218:221], v[36:51]
	global_load_dwordx4 v[136:139], v[162:163], off offset:640
	s_waitcnt lgkmcnt(4)
	v_mfma_f32_32x32x16_bf16 v[4:19], v[202:205], v[218:221], v[4:19]
	global_load_dwordx4 v[140:143], v[160:161], off offset:640
	s_waitcnt lgkmcnt(2)
	v_mfma_f32_32x32x16_bf16 v[36:51], v[178:181], v[222:225], v[36:51]
	global_load_dwordx4 v[198:201], v[158:159], off offset:640
	s_waitcnt lgkmcnt(1)
	v_mfma_f32_32x32x16_bf16 v[4:19], v[206:209], v[222:225], v[4:19]
	global_load_dwordx4 v[226:229], v[156:157], off offset:640
	ds_read_b128 v[222:225], v195 offset:41568
	ds_read_b128 v[174:177], v194 offset:4672
	v_mfma_f32_32x32x16_bf16 v[20:35], v[202:205], v[210:213], v[20:35]
	global_load_dwordx4 v[230:233], v[154:155], off offset:640
	ds_read_b128 v[210:213], v194 offset:4704
	ds_read_b128 v[202:205], v194 offset:64
	s_waitcnt lgkmcnt(4)
	v_mfma_f32_32x32x16_bf16 v[52:67], v[178:181], v[214:217], v[52:67]
	global_load_dwordx4 v[242:245], v[152:153], off offset:640
	ds_read_b128 v[218:221], v195 offset:36960
	ds_read_b128 v[178:181], v195 offset:41536
	v_mfma_f32_32x32x16_bf16 v[20:35], v[206:209], v[214:217], v[20:35]
	s_setprio 0
	global_load_dwordx4 v[246:249], v[146:147], off offset:640
	ds_read_b128 v[214:217], v195 offset:36928
	ds_read_b128 v[206:209], v194 offset:96
	s_waitcnt lgkmcnt(1)
	v_mfma_f32_32x32x16_bf16 v[52:67], v[202:205], v[214:217], v[52:67]
	s_waitcnt vmcnt(23)
	ds_write_b128 v190, v[68:71] offset:18432
	v_mfma_f32_32x32x16_bf16 v[36:51], v[202:205], v[178:181], v[36:51]
	s_waitcnt vmcnt(22)
	ds_write_b128 v190, v[72:75] offset:55296
	v_mfma_f32_32x32x16_bf16 v[20:35], v[174:177], v[214:217], v[20:35]
	s_waitcnt vmcnt(21)
	ds_write_b128 v191, v[76:79] offset:18432
	v_mfma_f32_32x32x16_bf16 v[4:19], v[174:177], v[178:181], v[4:19]
	s_waitcnt vmcnt(20)
	ds_write_b128 v191, v[80:83] offset:55296
	s_waitcnt lgkmcnt(4)
	v_mfma_f32_32x32x16_bf16 v[52:67], v[206:209], v[218:221], v[52:67]
	s_waitcnt vmcnt(19)
	ds_write_b128 v192, v[84:87] offset:18432
	v_mfma_f32_32x32x16_bf16 v[36:51], v[206:209], v[222:225], v[36:51]
	s_waitcnt vmcnt(18)
	ds_write_b128 v192, v[92:95] offset:55296
	v_mfma_f32_32x32x16_bf16 v[20:35], v[210:213], v[218:221], v[20:35]
	s_waitcnt vmcnt(17)
	ds_write_b128 v193, v[104:107] offset:18432
	v_mfma_f32_32x32x16_bf16 v[4:19], v[210:213], v[222:225], v[4:19]
	s_waitcnt vmcnt(16)
	ds_write_b128 v193, v[112:115] offset:55296
	s_waitcnt lgkmcnt(0)
	s_barrier
	s_setprio 1
	ds_read_b128 v[174:177], v196
	ds_read_b128 v[210:213], v197 offset:36864
	ds_read_b128 v[218:221], v197 offset:41472
	ds_read_b128 v[202:205], v196 offset:4608
	ds_read_b128 v[178:181], v196 offset:32
	ds_read_b128 v[222:225], v197 offset:41504
	ds_read_b128 v[206:209], v196 offset:4640
	ds_read_b128 v[214:217], v197 offset:36896
	s_waitcnt lgkmcnt(6)
	v_mfma_f32_32x32x16_bf16 v[52:67], v[174:177], v[210:213], v[52:67]
	global_load_dwordx4 v[68:71], v[164:165], off offset:768
	s_waitcnt lgkmcnt(5)
	v_mfma_f32_32x32x16_bf16 v[36:51], v[174:177], v[218:221], v[36:51]
	global_load_dwordx4 v[72:75], v[162:163], off offset:768
	s_waitcnt lgkmcnt(4)
	v_mfma_f32_32x32x16_bf16 v[4:19], v[202:205], v[218:221], v[4:19]
	global_load_dwordx4 v[76:79], v[160:161], off offset:768
	s_waitcnt lgkmcnt(2)
	v_mfma_f32_32x32x16_bf16 v[36:51], v[178:181], v[222:225], v[36:51]
	global_load_dwordx4 v[80:83], v[158:159], off offset:768
	s_waitcnt lgkmcnt(1)
	v_mfma_f32_32x32x16_bf16 v[4:19], v[206:209], v[222:225], v[4:19]
	global_load_dwordx4 v[84:87], v[156:157], off offset:768
	ds_read_b128 v[222:225], v197 offset:41568
	ds_read_b128 v[174:177], v196 offset:4672
	v_mfma_f32_32x32x16_bf16 v[20:35], v[202:205], v[210:213], v[20:35]
	global_load_dwordx4 v[92:95], v[154:155], off offset:768
	ds_read_b128 v[210:213], v196 offset:4704
	ds_read_b128 v[202:205], v196 offset:64
	s_waitcnt lgkmcnt(4)
	v_mfma_f32_32x32x16_bf16 v[52:67], v[178:181], v[214:217], v[52:67]
	global_load_dwordx4 v[104:107], v[152:153], off offset:768
	ds_read_b128 v[218:221], v197 offset:36960
	ds_read_b128 v[178:181], v197 offset:41536
	v_mfma_f32_32x32x16_bf16 v[20:35], v[206:209], v[214:217], v[20:35]
	s_setprio 0
	global_load_dwordx4 v[112:115], v[146:147], off offset:768
	ds_read_b128 v[214:217], v197 offset:36928
	ds_read_b128 v[206:209], v196 offset:96
	s_waitcnt lgkmcnt(1)
	v_mfma_f32_32x32x16_bf16 v[52:67], v[202:205], v[214:217], v[52:67]
	s_waitcnt vmcnt(23)
	ds_write_b128 v190, v[88:91]
	v_mfma_f32_32x32x16_bf16 v[36:51], v[202:205], v[178:181], v[36:51]
	s_waitcnt vmcnt(22)
	ds_write_b128 v190, v[96:99] offset:36864
	v_mfma_f32_32x32x16_bf16 v[20:35], v[174:177], v[214:217], v[20:35]
	s_waitcnt vmcnt(21)
	ds_write_b128 v191, v[100:103]
	v_mfma_f32_32x32x16_bf16 v[4:19], v[174:177], v[178:181], v[4:19]
	s_waitcnt vmcnt(20)
	ds_write_b128 v191, v[108:111] offset:36864
	s_waitcnt lgkmcnt(4)
	v_mfma_f32_32x32x16_bf16 v[52:67], v[206:209], v[218:221], v[52:67]
	s_waitcnt vmcnt(19)
	ds_write_b128 v192, v[116:119]
	v_mfma_f32_32x32x16_bf16 v[36:51], v[206:209], v[222:225], v[36:51]
	s_waitcnt vmcnt(18)
	ds_write_b128 v192, v[120:123] offset:36864
	v_mfma_f32_32x32x16_bf16 v[20:35], v[210:213], v[218:221], v[20:35]
	s_waitcnt vmcnt(17)
	ds_write_b128 v193, v[124:127]
	v_mfma_f32_32x32x16_bf16 v[4:19], v[210:213], v[222:225], v[4:19]
	s_waitcnt vmcnt(16)
	ds_write_b128 v193, v[128:131] offset:36864
	s_waitcnt lgkmcnt(0)
	s_barrier
; #define MFMA(a, b, c) __builtin_amdgcn_mfma_f32_32x32x16_bf16((a), (b), (c), 0, 0, 0)
; template <class Epi, class ColV>
; DI void gemm_tile(const bf16_t* __restrict__ A, int lda, const bf16_t* __restrict__ Bt, int ldb, int K, int m0, int n0, unsigned char* smem, Epi epi, ColV colv, const bf16_t* __restrict__ HYT = nullptr) {
;     ...
;     auto gload = [&](u32x4 (&r)[8], int kt) {
; #pragma unroll
;         for (int i = 0; i < 4; ++i) { int id = tid + 256 * i, row = id >> 3, kc = id & 7;
;             if (HYT && kt >= 12) r[i] = *(const u32x4*)(HYT + (size_t)((kt - 12) * 64 + (id >> 4)) * NT + m0 + (id & 15) * 8);
;             else r[i] = *(const u32x4*)(A + (size_t)(m0 + row) * lda + kt * 64 + kc * 8);
;             r[4 + i] = *(const u32x4*)(Bt + (size_t)(n0 + row) * ldb + kt * 64 + kc * 8); }
;     };
;     auto sstore = [&](const u32x4 (&r)[8], int buf, int kt) {
; #pragma unroll
;         for (int i = 0; i < 4; ++i) { int id = tid + 256 * i, row = id >> 3, kc = id & 7;
;             if (HYT && kt >= 12) { const int kk = id >> 4, rr = (id & 15) * 8; bf16_t* d = As + (buf * 128 + rr) * LS + kk; const bf16x8 v = __builtin_bit_cast(bf16x8, r[i]);
; #pragma unroll
;                 for (int e = 0; e < 8; ++e) d[e * LS] = (bf16_t)v[e]; }
;             else *(u32x4*)(As + (buf * 128 + row) * LS + kc * 8) = r[i];
;             *(u32x4*)(Bs + (buf * 128 + row) * LS + kc * 8) = r[4 + i]; }
;     };
;     auto step = [&](int kt, u32x4 (&ldset)[8], const u32x4 (&stset)[8]) {
;         const int buf = kt & 1;
;         if (kt + 2 < nk) gload(ldset, kt + 2);
;         const bf16_t* Ab = As + (buf * 128 + 64 * wr + li) * LS + 8 * lh;
;         const bf16_t* Bb = Bs + (buf * 128 + 64 * wc + li) * LS + 8 * lh;
;         bf16x8 fa[2][2], fb[2][2], ga[2][2], gb[2][2];
; #pragma unroll
;         for (int k2 = 0; k2 < 2; ++k2) { fa[k2][0] = ld8(Ab + 16 * k2); fa[k2][1] = ld8(Ab + 32 * LS + 16 * k2); fb[k2][0] = ld8(Bb + 16 * k2); fb[k2][1] = ld8(Bb + 32 * LS + 16 * k2); }
;         __builtin_amdgcn_sched_barrier(0);
; #pragma unroll
;         for (int k2 = 0; k2 < 2; ++k2) {
;             acc[0][0] = MFMA(fa[k2][0], fb[k2][0], acc[0][0]); acc[0][1] = MFMA(fa[k2][0], fb[k2][1], acc[0][1]);
;             acc[1][0] = MFMA(fa[k2][1], fb[k2][0], acc[1][0]); acc[1][1] = MFMA(fa[k2][1], fb[k2][1], acc[1][1]);
;         }
; #pragma unroll
	s_setprio 1
	ds_read_b128 v[174:177], v194
	ds_read_b128 v[210:213], v195 offset:36864
	ds_read_b128 v[218:221], v195 offset:41472
	ds_read_b128 v[202:205], v194 offset:4608
	ds_read_b128 v[178:181], v194 offset:32
	ds_read_b128 v[222:225], v195 offset:41504
	ds_read_b128 v[206:209], v194 offset:4640
	ds_read_b128 v[214:217], v195 offset:36896
	s_waitcnt lgkmcnt(6)
	v_mfma_f32_32x32x16_bf16 v[52:67], v[174:177], v[210:213], v[52:67]
	global_load_dwordx4 v[88:91], v[164:165], off offset:896
	s_waitcnt lgkmcnt(5)
	v_mfma_f32_32x32x16_bf16 v[36:51], v[174:177], v[218:221], v[36:51]
	global_load_dwordx4 v[96:99], v[162:163], off offset:896
	s_waitcnt lgkmcnt(4)
	v_mfma_f32_32x32x16_bf16 v[4:19], v[202:205], v[218:221], v[4:19]
	global_load_dwordx4 v[100:103], v[160:161], off offset:896
	s_waitcnt lgkmcnt(2)
	v_mfma_f32_32x32x16_bf16 v[36:51], v[178:181], v[222:225], v[36:51]
	global_load_dwordx4 v[108:111], v[158:159], off offset:896
	s_waitcnt lgkmcnt(1)
	v_mfma_f32_32x32x16_bf16 v[4:19], v[206:209], v[222:225], v[4:19]
	global_load_dwordx4 v[116:119], v[156:157], off offset:896
	ds_read_b128 v[222:225], v195 offset:41568
	ds_read_b128 v[174:177], v194 offset:4672
	v_mfma_f32_32x32x16_bf16 v[20:35], v[202:205], v[210:213], v[20:35]
	global_load_dwordx4 v[120:123], v[154:155], off offset:896
	ds_read_b128 v[210:213], v194 offset:4704
	ds_read_b128 v[202:205], v194 offset:64
	s_waitcnt lgkmcnt(4)
	v_mfma_f32_32x32x16_bf16 v[52:67], v[178:181], v[214:217], v[52:67]
	global_load_dwordx4 v[124:127], v[152:153], off offset:896
	ds_read_b128 v[218:221], v195 offset:36960
	ds_read_b128 v[178:181], v195 offset:41536
	v_mfma_f32_32x32x16_bf16 v[20:35], v[206:209], v[214:217], v[20:35]
	s_setprio 0
	global_load_dwordx4 v[128:131], v[146:147], off offset:896
	ds_read_b128 v[214:217], v195 offset:36928
	ds_read_b128 v[206:209], v194 offset:96
	s_waitcnt lgkmcnt(1)
	v_mfma_f32_32x32x16_bf16 v[52:67], v[202:205], v[214:217], v[52:67]
	s_waitcnt vmcnt(23)
	ds_write_b128 v190, v[132:135] offset:18432
	v_mfma_f32_32x32x16_bf16 v[36:51], v[202:205], v[178:181], v[36:51]
	s_waitcnt vmcnt(22)
	ds_write_b128 v190, v[136:139] offset:55296
	v_mfma_f32_32x32x16_bf16 v[20:35], v[174:177], v[214:217], v[20:35]
	s_waitcnt vmcnt(21)
	ds_write_b128 v191, v[140:143] offset:18432
	v_mfma_f32_32x32x16_bf16 v[4:19], v[174:177], v[178:181], v[4:19]
	s_waitcnt vmcnt(20)
	ds_write_b128 v191, v[198:201] offset:55296
	s_waitcnt lgkmcnt(4)
	v_mfma_f32_32x32x16_bf16 v[52:67], v[206:209], v[218:221], v[52:67]
	s_waitcnt vmcnt(19)
	ds_write_b128 v192, v[226:229] offset:18432
	v_mfma_f32_32x32x16_bf16 v[36:51], v[206:209], v[222:225], v[36:51]
	s_waitcnt vmcnt(18)
	ds_write_b128 v192, v[230:233] offset:55296
	v_mfma_f32_32x32x16_bf16 v[20:35], v[210:213], v[218:221], v[20:35]
	s_waitcnt vmcnt(17)
	ds_write_b128 v193, v[242:245] offset:18432
	v_mfma_f32_32x32x16_bf16 v[4:19], v[210:213], v[222:225], v[4:19]
	s_waitcnt vmcnt(16)
	ds_write_b128 v193, v[246:249] offset:55296
	s_waitcnt lgkmcnt(0)
	s_barrier
	s_setprio 1
	ds_read_b128 v[174:177], v196
	ds_read_b128 v[210:213], v197 offset:36864
	ds_read_b128 v[218:221], v197 offset:41472
	ds_read_b128 v[202:205], v196 offset:4608
	ds_read_b128 v[178:181], v196 offset:32
	ds_read_b128 v[222:225], v197 offset:41504
	ds_read_b128 v[206:209], v196 offset:4640
	ds_read_b128 v[214:217], v197 offset:36896
	s_waitcnt lgkmcnt(6)
	v_mfma_f32_32x32x16_bf16 v[52:67], v[174:177], v[210:213], v[52:67]
	global_load_dwordx4 v[132:135], v[164:165], off offset:1024
	s_waitcnt lgkmcnt(5)
	v_mfma_f32_32x32x16_bf16 v[36:51], v[174:177], v[218:221], v[36:51]
	global_load_dwordx4 v[136:139], v[162:163], off offset:1024
	s_waitcnt lgkmcnt(4)
	v_mfma_f32_32x32x16_bf16 v[4:19], v[202:205], v[218:221], v[4:19]
	global_load_dwordx4 v[140:143], v[160:161], off offset:1024
	s_waitcnt lgkmcnt(2)
	v_mfma_f32_32x32x16_bf16 v[36:51], v[178:181], v[222:225], v[36:51]
	global_load_dwordx4 v[198:201], v[158:159], off offset:1024
	s_waitcnt lgkmcnt(1)
	v_mfma_f32_32x32x16_bf16 v[4:19], v[206:209], v[222:225], v[4:19]
	global_load_dwordx4 v[226:229], v[156:157], off offset:1024
	ds_read_b128 v[222:225], v197 offset:41568
	ds_read_b128 v[174:177], v196 offset:4672
	v_mfma_f32_32x32x16_bf16 v[20:35], v[202:205], v[210:213], v[20:35]
	global_load_dwordx4 v[230:233], v[154:155], off offset:1024
	ds_read_b128 v[210:213], v196 offset:4704
	ds_read_b128 v[202:205], v196 offset:64
	s_waitcnt lgkmcnt(4)
	v_mfma_f32_32x32x16_bf16 v[52:67], v[178:181], v[214:217], v[52:67]
	global_load_dwordx4 v[242:245], v[152:153], off offset:1024
	ds_read_b128 v[218:221], v197 offset:36960
	ds_read_b128 v[178:181], v197 offset:41536
	v_mfma_f32_32x32x16_bf16 v[20:35], v[206:209], v[214:217], v[20:35]
	s_setprio 0
	global_load_dwordx4 v[246:249], v[146:147], off offset:1024
	ds_read_b128 v[214:217], v197 offset:36928
	ds_read_b128 v[206:209], v196 offset:96
	s_waitcnt lgkmcnt(1)
	v_mfma_f32_32x32x16_bf16 v[52:67], v[202:205], v[214:217], v[52:67]
	s_waitcnt vmcnt(23)
	ds_write_b128 v190, v[68:71]
	v_mfma_f32_32x32x16_bf16 v[36:51], v[202:205], v[178:181], v[36:51]
	s_waitcnt vmcnt(22)
	ds_write_b128 v190, v[72:75] offset:36864
	v_mfma_f32_32x32x16_bf16 v[20:35], v[174:177], v[214:217], v[20:35]
	s_waitcnt vmcnt(21)
	ds_write_b128 v191, v[76:79]
	v_mfma_f32_32x32x16_bf16 v[4:19], v[174:177], v[178:181], v[4:19]
	s_waitcnt vmcnt(20)
	ds_write_b128 v191, v[80:83] offset:36864
	s_waitcnt lgkmcnt(4)
	v_mfma_f32_32x32x16_bf16 v[52:67], v[206:209], v[218:221], v[52:67]
	s_waitcnt vmcnt(19)
	ds_write_b128 v192, v[84:87]
	v_mfma_f32_32x32x16_bf16 v[36:51], v[206:209], v[222:225], v[36:51]
	s_waitcnt vmcnt(18)
	ds_write_b128 v192, v[92:95] offset:36864
	v_mfma_f32_32x32x16_bf16 v[20:35], v[210:213], v[218:221], v[20:35]
	s_waitcnt vmcnt(17)
	ds_write_b128 v193, v[104:107]
	v_mfma_f32_32x32x16_bf16 v[4:19], v[210:213], v[222:225], v[4:19]
	s_waitcnt vmcnt(16)
	ds_write_b128 v193, v[112:115] offset:36864
	s_waitcnt lgkmcnt(0)
	s_barrier
; #define MFMA(a, b, c) __builtin_amdgcn_mfma_f32_32x32x16_bf16((a), (b), (c), 0, 0, 0)
; template <class Epi, class ColV>
; DI void gemm_tile(const bf16_t* __restrict__ A, int lda, const bf16_t* __restrict__ Bt, int ldb, int K, int m0, int n0, unsigned char* smem, Epi epi, ColV colv, const bf16_t* __restrict__ HYT = nullptr) {
;     ...
;     auto gload = [&](u32x4 (&r)[8], int kt) {
; #pragma unroll
;         for (int i = 0; i < 4; ++i) { int id = tid + 256 * i, row = id >> 3, kc = id & 7;
;             if (HYT && kt >= 12) r[i] = *(const u32x4*)(HYT + (size_t)((kt - 12) * 64 + (id >> 4)) * NT + m0 + (id & 15) * 8);
;             else r[i] = *(const u32x4*)(A + (size_t)(m0 + row) * lda + kt * 64 + kc * 8);
;             r[4 + i] = *(const u32x4*)(Bt + (size_t)(n0 + row) * ldb + kt * 64 + kc * 8); }
;     };
;     auto sstore = [&](const u32x4 (&r)[8], int buf, int kt) {
; #pragma unroll
;         for (int i = 0; i < 4; ++i) { int id = tid + 256 * i, row = id >> 3, kc = id & 7;
;             if (HYT && kt >= 12) { const int kk = id >> 4, rr = (id & 15) * 8; bf16_t* d = As + (buf * 128 + rr) * LS + kk; const bf16x8 v = __builtin_bit_cast(bf16x8, r[i]);
; #pragma unroll
;                 for (int e = 0; e < 8; ++e) d[e * LS] = (bf16_t)v[e]; }
;             else *(u32x4*)(As + (buf * 128 + row) * LS + kc * 8) = r[i];
;             *(u32x4*)(Bs + (buf * 128 + row) * LS + kc * 8) = r[4 + i]; }
;     };
;     auto step = [&](int kt, u32x4 (&ldset)[8], const u32x4 (&stset)[8]) {
;         const int buf = kt & 1;
;         if (kt + 2 < nk) gload(ldset, kt + 2);
;         const bf16_t* Ab = As + (buf * 128 + 64 * wr + li) * LS + 8 * lh;
;         const bf16_t* Bb = Bs + (buf * 128 + 64 * wc + li) * LS + 8 * lh;
;         bf16x8 fa[2][2], fb[2][2], ga[2][2], gb[2][2];
; #pragma unroll
;         for (int k2 = 0; k2 < 2; ++k2) { fa[k2][0] = ld8(Ab + 16 * k2); fa[k2][1] = ld8(Ab + 32 * LS + 16 * k2); fb[k2][0] = ld8(Bb + 16 * k2); fb[k2][1] = ld8(Bb + 32 * LS + 16 * k2); }
;         __builtin_amdgcn_sched_barrier(0);
; #pragma unroll
;         for (int k2 = 0; k2 < 2; ++k2) {
;             acc[0][0] = MFMA(fa[k2][0], fb[k2][0], acc[0][0]); acc[0][1] = MFMA(fa[k2][0], fb[k2][1], acc[0][1]);
;             acc[1][0] = MFMA(fa[k2][1], fb[k2][0], acc[1][0]); acc[1][1] = MFMA(fa[k2][1], fb[k2][1], acc[1][1]);
;         }
; #pragma unroll
	s_setprio 1
	v_lshl_add_u64 v[164:165], v[164:165], 0, s[100:101]
	v_lshl_add_u64 v[162:163], v[162:163], 0, s[100:101]
	v_lshl_add_u64 v[160:161], v[160:161], 0, s[100:101]
	v_lshl_add_u64 v[158:159], v[158:159], 0, s[100:101]
	v_lshl_add_u64 v[156:157], v[156:157], 0, s[100:101]
	v_lshl_add_u64 v[154:155], v[154:155], 0, s[100:101]
	v_lshl_add_u64 v[152:153], v[152:153], 0, s[100:101]
	v_lshl_add_u64 v[146:147], v[146:147], 0, s[100:101]
	s_sub_u32 s41, s41, 1
	s_cmp_lg_u32 s41, 0
	s_cbranch_scc1 .Lg3_phase11
	ds_read_b128 v[174:177], v194
	ds_read_b128 v[210:213], v195 offset:36864
	ds_read_b128 v[218:221], v195 offset:41472
	ds_read_b128 v[202:205], v194 offset:4608
	ds_read_b128 v[178:181], v194 offset:32
	ds_read_b128 v[222:225], v195 offset:41504
	ds_read_b128 v[206:209], v194 offset:4640
	ds_read_b128 v[214:217], v195 offset:36896
	s_waitcnt lgkmcnt(6)
	v_mfma_f32_32x32x16_bf16 v[52:67], v[174:177], v[210:213], v[52:67]
	global_load_dwordx4 v[68:71], v[164:165], off offset:384
	s_waitcnt lgkmcnt(5)
	v_mfma_f32_32x32x16_bf16 v[36:51], v[174:177], v[218:221], v[36:51]
	global_load_dwordx4 v[72:75], v[162:163], off offset:384
	s_waitcnt lgkmcnt(4)
	v_mfma_f32_32x32x16_bf16 v[4:19], v[202:205], v[218:221], v[4:19]
	global_load_dwordx4 v[76:79], v[160:161], off offset:384
	s_waitcnt lgkmcnt(2)
	v_mfma_f32_32x32x16_bf16 v[36:51], v[178:181], v[222:225], v[36:51]
	global_load_dwordx4 v[80:83], v[158:159], off offset:384
	s_waitcnt lgkmcnt(1)
	v_mfma_f32_32x32x16_bf16 v[4:19], v[206:209], v[222:225], v[4:19]
	global_load_dwordx4 v[84:87], v[156:157], off offset:384
	ds_read_b128 v[222:225], v195 offset:41568
	ds_read_b128 v[174:177], v194 offset:4672
	v_mfma_f32_32x32x16_bf16 v[20:35], v[202:205], v[210:213], v[20:35]
	global_load_dwordx4 v[92:95], v[154:155], off offset:384
	ds_read_b128 v[210:213], v194 offset:4704
	ds_read_b128 v[202:205], v194 offset:64
	s_waitcnt lgkmcnt(4)
	v_mfma_f32_32x32x16_bf16 v[52:67], v[178:181], v[214:217], v[52:67]
	global_load_dwordx4 v[104:107], v[152:153], off offset:384
	ds_read_b128 v[218:221], v195 offset:36960
	ds_read_b128 v[178:181], v195 offset:41536
	v_mfma_f32_32x32x16_bf16 v[20:35], v[206:209], v[214:217], v[20:35]
	s_setprio 0
	global_load_dwordx4 v[112:115], v[146:147], off offset:384
	ds_read_b128 v[214:217], v195 offset:36928
	ds_read_b128 v[206:209], v194 offset:96
	s_waitcnt lgkmcnt(1)
	v_mfma_f32_32x32x16_bf16 v[52:67], v[202:205], v[214:217], v[52:67]
	s_waitcnt vmcnt(23)
	ds_write_b128 v190, v[88:91] offset:18432
	v_mfma_f32_32x32x16_bf16 v[36:51], v[202:205], v[178:181], v[36:51]
	s_waitcnt vmcnt(22)
	ds_write_b128 v190, v[96:99] offset:55296
	v_mfma_f32_32x32x16_bf16 v[20:35], v[174:177], v[214:217], v[20:35]
	s_waitcnt vmcnt(21)
	ds_write_b128 v191, v[100:103] offset:18432
	v_mfma_f32_32x32x16_bf16 v[4:19], v[174:177], v[178:181], v[4:19]
	s_waitcnt vmcnt(20)
	ds_write_b128 v191, v[108:111] offset:55296
	s_waitcnt lgkmcnt(4)
	v_mfma_f32_32x32x16_bf16 v[52:67], v[206:209], v[218:221], v[52:67]
	s_waitcnt vmcnt(19)
	ds_write_b128 v192, v[116:119] offset:18432
	v_mfma_f32_32x32x16_bf16 v[36:51], v[206:209], v[222:225], v[36:51]
	s_waitcnt vmcnt(18)
	ds_write_b128 v192, v[120:123] offset:55296
	v_mfma_f32_32x32x16_bf16 v[20:35], v[210:213], v[218:221], v[20:35]
	s_waitcnt vmcnt(17)
	ds_write_b128 v193, v[124:127] offset:18432
	v_mfma_f32_32x32x16_bf16 v[4:19], v[210:213], v[222:225], v[4:19]
	s_waitcnt vmcnt(16)
	ds_write_b128 v193, v[128:131] offset:55296
	s_waitcnt lgkmcnt(0)
	s_barrier
	s_setprio 1
	ds_read_b128 v[174:177], v196
	ds_read_b128 v[178:181], v196 offset:32
	ds_read_b128 v[202:205], v196 offset:4608
	ds_read_b128 v[206:209], v196 offset:4640
	ds_read_b128 v[210:213], v197 offset:36864
	ds_read_b128 v[214:217], v197 offset:36896
	ds_read_b128 v[218:221], v197 offset:41472
	ds_read_b128 v[222:225], v197 offset:41504
	s_waitcnt lgkmcnt(3)
	v_mfma_f32_32x32x16_bf16 v[52:67], v[174:177], v[210:213], v[52:67]
	s_waitcnt lgkmcnt(1)
	v_mfma_f32_32x32x16_bf16 v[36:51], v[174:177], v[218:221], v[36:51]
	v_mfma_f32_32x32x16_bf16 v[4:19], v[202:205], v[218:221], v[4:19]
	s_waitcnt lgkmcnt(0)
	v_mfma_f32_32x32x16_bf16 v[36:51], v[178:181], v[222:225], v[36:51]
	v_mfma_f32_32x32x16_bf16 v[4:19], v[206:209], v[222:225], v[4:19]
	ds_read_b128 v[222:225], v197 offset:41568
	ds_read_b128 v[174:177], v196 offset:4672
	v_mfma_f32_32x32x16_bf16 v[20:35], v[202:205], v[210:213], v[20:35]
	ds_read_b128 v[210:213], v196 offset:4704
	ds_read_b128 v[202:205], v196 offset:64
	v_mfma_f32_32x32x16_bf16 v[52:67], v[178:181], v[214:217], v[52:67]
	ds_read_b128 v[218:221], v197 offset:36960
	ds_read_b128 v[178:181], v197 offset:41536
	v_mfma_f32_32x32x16_bf16 v[20:35], v[206:209], v[214:217], v[20:35]
	s_setprio 0
	ds_read_b128 v[214:217], v197 offset:36928
	ds_read_b128 v[206:209], v196 offset:96
	s_waitcnt lgkmcnt(1)
	v_mfma_f32_32x32x16_bf16 v[52:67], v[202:205], v[214:217], v[52:67]
	s_waitcnt vmcnt(15)
	ds_write_b128 v190, v[132:135]
	v_mfma_f32_32x32x16_bf16 v[36:51], v[202:205], v[178:181], v[36:51]
	s_waitcnt vmcnt(14)
	ds_write_b128 v190, v[136:139] offset:36864
	v_mfma_f32_32x32x16_bf16 v[20:35], v[174:177], v[214:217], v[20:35]
	s_waitcnt vmcnt(13)
	ds_write_b128 v191, v[140:143]
	v_mfma_f32_32x32x16_bf16 v[4:19], v[174:177], v[178:181], v[4:19]
	s_waitcnt vmcnt(12)
	ds_write_b128 v191, v[198:201] offset:36864
	s_waitcnt lgkmcnt(4)
	v_mfma_f32_32x32x16_bf16 v[52:67], v[206:209], v[218:221], v[52:67]
	s_waitcnt vmcnt(11)
	ds_write_b128 v192, v[226:229]
	v_mfma_f32_32x32x16_bf16 v[36:51], v[206:209], v[222:225], v[36:51]
	s_waitcnt vmcnt(10)
	ds_write_b128 v192, v[230:233] offset:36864
	v_mfma_f32_32x32x16_bf16 v[20:35], v[210:213], v[218:221], v[20:35]
	s_waitcnt vmcnt(9)
	ds_write_b128 v193, v[242:245]
	v_mfma_f32_32x32x16_bf16 v[4:19], v[210:213], v[222:225], v[4:19]
	s_waitcnt vmcnt(8)
	ds_write_b128 v193, v[246:249] offset:36864
	s_waitcnt lgkmcnt(0)
	s_barrier
; template <class Epi, class ColV>
; DI void gemm_tile(const bf16_t* __restrict__ A, int lda, const bf16_t* __restrict__ Bt, int ldb, int K, int m0, int n0, unsigned char* smem, Epi epi, ColV colv, const bf16_t* __restrict__ HYT = nullptr) {
;     ...
;     auto step = [&](int kt, u32x4 (&ldset)[8], const u32x4 (&stset)[8]) {
;         const int buf = kt & 1;
;         if (kt + 2 < nk) gload(ldset, kt + 2);
;         const bf16_t* Ab = As + (buf * 128 + 64 * wr + li) * LS + 8 * lh;
;         const bf16_t* Bb = Bs + (buf * 128 + 64 * wc + li) * LS + 8 * lh;
;         bf16x8 fa[2][2], fb[2][2], ga[2][2], gb[2][2];
; #pragma unroll
;         for (int k2 = 0; k2 < 2; ++k2) { fa[k2][0] = ld8(Ab + 16 * k2); fa[k2][1] = ld8(Ab + 32 * LS + 16 * k2); fb[k2][0] = ld8(Bb + 16 * k2); fb[k2][1] = ld8(Bb + 32 * LS + 16 * k2); }
;         __builtin_amdgcn_sched_barrier(0);
; #pragma unroll
;         for (int k2 = 0; k2 < 2; ++k2) {
;             acc[0][0] = MFMA(fa[k2][0], fb[k2][0], acc[0][0]); acc[0][1] = MFMA(fa[k2][0], fb[k2][1], acc[0][1]);
;             acc[1][0] = MFMA(fa[k2][1], fb[k2][0], acc[1][0]); acc[1][1] = MFMA(fa[k2][1], fb[k2][1], acc[1][1]);
;         }
; #pragma unroll
;         for (int k2 = 0; k2 < 2; ++k2) { const int ks = 2 + k2; ga[k2][0] = ld8(Ab + 16 * ks); ga[k2][1] = ld8(Ab + 32 * LS + 16 * ks); gb[k2][0] = ld8(Bb + 16 * ks); gb[k2][1] = ld8(Bb + 32 * LS + 16 * ks); }
; #pragma unroll
;         for (int k2 = 0; k2 < 2; ++k2) {
;             acc[0][0] = MFMA(ga[k2][0], gb[k2][0], acc[0][0]); acc[0][1] = MFMA(ga[k2][0], gb[k2][1], acc[0][1]);
;             acc[1][0] = MFMA(ga[k2][1], gb[k2][0], acc[1][0]); acc[1][1] = MFMA(ga[k2][1], gb[k2][1], acc[1][1]);
;         }
;         if (kt + 1 < nk) sstore(stset, buf ^ 1, kt + 1);
; #pragma unroll
;         for (int i = 0; i < 8; ++i) { __builtin_amdgcn_sched_group_barrier(0x008, 1, 0); __builtin_amdgcn_sched_group_barrier(0x100, 1, 0); }
; #pragma unroll
;         for (int i = 0; i < 8; ++i) { __builtin_amdgcn_sched_group_barrier(0x008, 1, 0); __builtin_amdgcn_sched_group_barrier(0x200, 1, 0); }
;         __builtin_amdgcn_sched_barrier(0);
;         __syncthreads();
;     };
;     gload(R0, 0); gload(R1, 1);
;     sstore(R0, 0, 0); __syncthreads();
;     for (int kt = 0; kt < nk; kt += 2) {
;         step(kt, R0, R1);
;         if (kt + 1 < nk) step(kt + 1, R1, R0);
;     }
	s_setprio 1
	ds_read_b128 v[174:177], v194
	ds_read_b128 v[178:181], v194 offset:32
	ds_read_b128 v[202:205], v194 offset:4608
	ds_read_b128 v[206:209], v194 offset:4640
	ds_read_b128 v[210:213], v195 offset:36864
	ds_read_b128 v[214:217], v195 offset:36896
	ds_read_b128 v[218:221], v195 offset:41472
	ds_read_b128 v[222:225], v195 offset:41504
	s_waitcnt lgkmcnt(3)
	v_mfma_f32_32x32x16_bf16 v[52:67], v[174:177], v[210:213], v[52:67]
	s_waitcnt lgkmcnt(1)
	v_mfma_f32_32x32x16_bf16 v[36:51], v[174:177], v[218:221], v[36:51]
	v_mfma_f32_32x32x16_bf16 v[4:19], v[202:205], v[218:221], v[4:19]
	s_waitcnt lgkmcnt(0)
	v_mfma_f32_32x32x16_bf16 v[36:51], v[178:181], v[222:225], v[36:51]
	v_mfma_f32_32x32x16_bf16 v[4:19], v[206:209], v[222:225], v[4:19]
	ds_read_b128 v[222:225], v195 offset:41568
	ds_read_b128 v[174:177], v194 offset:4672
	v_mfma_f32_32x32x16_bf16 v[20:35], v[202:205], v[210:213], v[20:35]
	ds_read_b128 v[210:213], v194 offset:4704
	ds_read_b128 v[202:205], v194 offset:64
	v_mfma_f32_32x32x16_bf16 v[52:67], v[178:181], v[214:217], v[52:67]
	ds_read_b128 v[218:221], v195 offset:36960
	ds_read_b128 v[178:181], v195 offset:41536
	v_mfma_f32_32x32x16_bf16 v[20:35], v[206:209], v[214:217], v[20:35]
	s_setprio 0
	ds_read_b128 v[214:217], v195 offset:36928
	ds_read_b128 v[206:209], v194 offset:96
	s_waitcnt lgkmcnt(1)
	v_mfma_f32_32x32x16_bf16 v[52:67], v[202:205], v[214:217], v[52:67]
	s_waitcnt vmcnt(7)
	ds_write_b128 v190, v[68:71] offset:18432
	v_mfma_f32_32x32x16_bf16 v[36:51], v[202:205], v[178:181], v[36:51]
	s_waitcnt vmcnt(6)
	ds_write_b128 v190, v[72:75] offset:55296
	v_mfma_f32_32x32x16_bf16 v[20:35], v[174:177], v[214:217], v[20:35]
	s_waitcnt vmcnt(5)
	ds_write_b128 v191, v[76:79] offset:18432
	v_mfma_f32_32x32x16_bf16 v[4:19], v[174:177], v[178:181], v[4:19]
	s_waitcnt vmcnt(4)
	ds_write_b128 v191, v[80:83] offset:55296
	s_waitcnt lgkmcnt(4)
	v_mfma_f32_32x32x16_bf16 v[52:67], v[206:209], v[218:221], v[52:67]
	s_waitcnt vmcnt(3)
	ds_write_b128 v192, v[84:87] offset:18432
	v_mfma_f32_32x32x16_bf16 v[36:51], v[206:209], v[222:225], v[36:51]
	s_waitcnt vmcnt(2)
	ds_write_b128 v192, v[92:95] offset:55296
	v_mfma_f32_32x32x16_bf16 v[20:35], v[210:213], v[218:221], v[20:35]
	s_waitcnt vmcnt(1)
	ds_write_b128 v193, v[104:107] offset:18432
	v_mfma_f32_32x32x16_bf16 v[4:19], v[210:213], v[222:225], v[4:19]
	s_waitcnt vmcnt(0)
	ds_write_b128 v193, v[112:115] offset:55296
	s_waitcnt lgkmcnt(0)
	s_barrier
	s_setprio 1
	ds_read_b128 v[174:177], v196
	ds_read_b128 v[178:181], v196 offset:32
	ds_read_b128 v[202:205], v196 offset:4608
	ds_read_b128 v[206:209], v196 offset:4640
	ds_read_b128 v[210:213], v197 offset:36864
	ds_read_b128 v[214:217], v197 offset:36896
	ds_read_b128 v[218:221], v197 offset:41472
	ds_read_b128 v[222:225], v197 offset:41504
	s_waitcnt lgkmcnt(3)
	v_mfma_f32_32x32x16_bf16 v[52:67], v[174:177], v[210:213], v[52:67]
	s_waitcnt lgkmcnt(1)
	v_mfma_f32_32x32x16_bf16 v[36:51], v[174:177], v[218:221], v[36:51]
	v_mfma_f32_32x32x16_bf16 v[4:19], v[202:205], v[218:221], v[4:19]
	s_waitcnt lgkmcnt(0)
	v_mfma_f32_32x32x16_bf16 v[36:51], v[178:181], v[222:225], v[36:51]
	v_mfma_f32_32x32x16_bf16 v[4:19], v[206:209], v[222:225], v[4:19]
	ds_read_b128 v[222:225], v197 offset:41568
	ds_read_b128 v[174:177], v196 offset:4672
	v_mfma_f32_32x32x16_bf16 v[20:35], v[202:205], v[210:213], v[20:35]
	ds_read_b128 v[210:213], v196 offset:4704
	ds_read_b128 v[202:205], v196 offset:64
	v_mfma_f32_32x32x16_bf16 v[52:67], v[178:181], v[214:217], v[52:67]
	ds_read_b128 v[218:221], v197 offset:36960
	ds_read_b128 v[178:181], v197 offset:41536
	v_mfma_f32_32x32x16_bf16 v[20:35], v[206:209], v[214:217], v[20:35]
	s_setprio 0
	ds_read_b128 v[214:217], v197 offset:36928
	ds_read_b128 v[206:209], v196 offset:96
	s_waitcnt lgkmcnt(1)
	v_mfma_f32_32x32x16_bf16 v[52:67], v[202:205], v[214:217], v[52:67]
	v_mfma_f32_32x32x16_bf16 v[36:51], v[202:205], v[178:181], v[36:51]
	v_mfma_f32_32x32x16_bf16 v[20:35], v[174:177], v[214:217], v[20:35]
	v_mfma_f32_32x32x16_bf16 v[4:19], v[174:177], v[178:181], v[4:19]
	s_waitcnt lgkmcnt(0)
	v_mfma_f32_32x32x16_bf16 v[52:67], v[206:209], v[218:221], v[52:67]
	v_mfma_f32_32x32x16_bf16 v[36:51], v[206:209], v[222:225], v[36:51]
	v_mfma_f32_32x32x16_bf16 v[20:35], v[210:213], v[218:221], v[20:35]
	v_mfma_f32_32x32x16_bf16 v[4:19], v[210:213], v[222:225], v[4:19]
	s_waitcnt lgkmcnt(0)
	s_barrier
	s_setprio 1
	s_nop 7
	s_nop 3
	s_branch .LBB0_37

; template <class Epi, class ColV>
; DI void gemm_tile(const bf16_t* __restrict__ A, int lda, const bf16_t* __restrict__ Bt, int ldb, int K, int m0, int n0, unsigned char* smem, Epi epi, ColV colv, const bf16_t* __restrict__ HYT = nullptr) {
;     ...
;     auto step = [&](int kt, u32x4 (&ldset)[8], const u32x4 (&stset)[8]) {
;         const int buf = kt & 1;
;         if (kt + 2 < nk) gload(ldset, kt + 2);
;         const bf16_t* Ab = As + (buf * 128 + 64 * wr + li) * LS + 8 * lh;
;         const bf16_t* Bb = Bs + (buf * 128 + 64 * wc + li) * LS + 8 * lh;
;         bf16x8 fa[2][2], fb[2][2], ga[2][2], gb[2][2];
; #pragma unroll
;         for (int k2 = 0; k2 < 2; ++k2) { fa[k2][0] = ld8(Ab + 16 * k2); fa[k2][1] = ld8(Ab + 32 * LS + 16 * k2); fb[k2][0] = ld8(Bb + 16 * k2); fb[k2][1] = ld8(Bb + 32 * LS + 16 * k2); }
;         __builtin_amdgcn_sched_barrier(0);
; #pragma unroll
;         for (int k2 = 0; k2 < 2; ++k2) {
;             acc[0][0] = MFMA(fa[k2][0], fb[k2][0], acc[0][0]); acc[0][1] = MFMA(fa[k2][0], fb[k2][1], acc[0][1]);
;             acc[1][0] = MFMA(fa[k2][1], fb[k2][0], acc[1][0]); acc[1][1] = MFMA(fa[k2][1], fb[k2][1], acc[1][1]);
;         }
; #pragma unroll
;         for (int k2 = 0; k2 < 2; ++k2) { const int ks = 2 + k2; ga[k2][0] = ld8(Ab + 16 * ks); ga[k2][1] = ld8(Ab + 32 * LS + 16 * ks); gb[k2][0] = ld8(Bb + 16 * ks); gb[k2][1] = ld8(Bb + 32 * LS + 16 * ks); }
; #pragma unroll
;         for (int k2 = 0; k2 < 2; ++k2) {
;             acc[0][0] = MFMA(ga[k2][0], gb[k2][0], acc[0][0]); acc[0][1] = MFMA(ga[k2][0], gb[k2][1], acc[0][1]);
;             acc[1][0] = MFMA(ga[k2][1], gb[k2][0], acc[1][0]); acc[1][1] = MFMA(ga[k2][1], gb[k2][1], acc[1][1]);
;         }
;         if (kt + 1 < nk) sstore(stset, buf ^ 1, kt + 1);
; #pragma unroll
;         for (int i = 0; i < 8; ++i) { __builtin_amdgcn_sched_group_barrier(0x008, 1, 0); __builtin_amdgcn_sched_group_barrier(0x100, 1, 0); }
; #pragma unroll
;         for (int i = 0; i < 8; ++i) { __builtin_amdgcn_sched_group_barrier(0x008, 1, 0); __builtin_amdgcn_sched_group_barrier(0x200, 1, 0); }
;         __builtin_amdgcn_sched_barrier(0);
;         __syncthreads();
;     };
;     ...
;         XCD_TILE_LOOP((layer == 0 ? NT : NL) / 128, 32, tm, tn) gemm_tile((const bf16_t*)(p.ws + WS_H), 1024, (const bf16_t*)(p.ws + wbase(layer) + W_FF1), 1024, 1024, tm * 128, tn * 128, smem, epi, nocol);
.LBB0_56:
	s_cmp_lt_u32 s40, 14
	s_cselect_b64 s[18:19], -1, 0
	s_cmp_gt_u32 s40, 13
	s_cselect_b64 s[12:13], -1, 0
	s_and_b64 vcc, exec, s[12:13]
	v_lshl_add_u64 v[164:165], v[144:145], 0, v[2:3]
	v_lshl_add_u64 v[162:163], v[142:143], 0, v[2:3]
	v_lshl_add_u64 v[160:161], v[140:141], 0, v[2:3]
	v_lshl_add_u64 v[158:159], v[138:139], 0, v[2:3]
	v_lshl_add_u64 v[156:157], v[136:137], 0, v[2:3]
	v_lshl_add_u64 v[154:155], v[134:135], 0, v[2:3]
	v_lshl_add_u64 v[152:153], v[132:133], 0, v[2:3]
	v_lshl_add_u64 v[146:147], v[0:1], 0, v[2:3]
	s_mov_b32 s100, 0x26ca000
	s_mov_b32 s101, 0
	v_lshl_add_u64 v[164:165], v[164:165], 0, s[100:101]
	v_lshl_add_u64 v[160:161], v[160:161], 0, s[100:101]
	v_lshl_add_u64 v[156:157], v[156:157], 0, s[100:101]
	v_lshl_add_u64 v[152:153], v[152:153], 0, s[100:101]
	s_mov_b32 s100, 0x680000
	s_mov_b32 s101, 0
	v_lshl_add_u64 v[162:163], v[162:163], 0, s[100:101]
	v_lshl_add_u64 v[158:159], v[158:159], 0, s[100:101]
	v_lshl_add_u64 v[154:155], v[154:155], 0, s[100:101]
	v_lshl_add_u64 v[146:147], v[146:147], 0, s[100:101]
	ds_read_b128 v[174:177], v194
	ds_read_b128 v[210:213], v195 offset:36864
	ds_read_b128 v[218:221], v195 offset:41472
	ds_read_b128 v[202:205], v194 offset:4608
	ds_read_b128 v[178:181], v194 offset:32
	ds_read_b128 v[222:225], v195 offset:41504
	ds_read_b128 v[206:209], v194 offset:4640
	ds_read_b128 v[214:217], v195 offset:36896
	s_waitcnt lgkmcnt(6)
	v_mfma_f32_32x32x16_bf16 v[52:67], v[174:177], v[210:213], v[52:67]
	global_load_dwordx4 v[132:135], v[164:165], off offset:256
	global_load_dwordx4 v[136:139], v[162:163], off offset:256
	s_waitcnt lgkmcnt(5)
	v_mfma_f32_32x32x16_bf16 v[36:51], v[174:177], v[218:221], v[36:51]
	global_load_dwordx4 v[140:143], v[160:161], off offset:256
	global_load_dwordx4 v[198:201], v[158:159], off offset:256
	s_waitcnt lgkmcnt(4)
	v_mfma_f32_32x32x16_bf16 v[4:19], v[202:205], v[218:221], v[4:19]
	global_load_dwordx4 v[226:229], v[156:157], off offset:256
	global_load_dwordx4 v[230:233], v[154:155], off offset:256
	s_waitcnt lgkmcnt(2)
	v_mfma_f32_32x32x16_bf16 v[36:51], v[178:181], v[222:225], v[36:51]
	global_load_dwordx4 v[242:245], v[152:153], off offset:256
	global_load_dwordx4 v[246:249], v[146:147], off offset:256
	s_waitcnt lgkmcnt(1)
	v_mfma_f32_32x32x16_bf16 v[4:19], v[206:209], v[222:225], v[4:19]
	global_load_dwordx4 v[68:71], v[164:165], off offset:384
	global_load_dwordx4 v[72:75], v[162:163], off offset:384
	ds_read_b128 v[222:225], v195 offset:41568
	ds_read_b128 v[174:177], v194 offset:4672
	v_mfma_f32_32x32x16_bf16 v[20:35], v[202:205], v[210:213], v[20:35]
	global_load_dwordx4 v[76:79], v[160:161], off offset:384
	global_load_dwordx4 v[80:83], v[158:159], off offset:384
	ds_read_b128 v[210:213], v194 offset:4704
	ds_read_b128 v[202:205], v194 offset:64
	s_waitcnt lgkmcnt(4)
	v_mfma_f32_32x32x16_bf16 v[52:67], v[178:181], v[214:217], v[52:67]
	global_load_dwordx4 v[84:87], v[156:157], off offset:384
	global_load_dwordx4 v[92:95], v[154:155], off offset:384
	ds_read_b128 v[218:221], v195 offset:36960
	ds_read_b128 v[178:181], v195 offset:41536
	v_mfma_f32_32x32x16_bf16 v[20:35], v[206:209], v[214:217], v[20:35]
	s_setprio 0
	global_load_dwordx4 v[104:107], v[152:153], off offset:384
	global_load_dwordx4 v[112:115], v[146:147], off offset:384
	ds_read_b128 v[214:217], v195 offset:36928
	ds_read_b128 v[206:209], v194 offset:96
	s_waitcnt lgkmcnt(1)
	v_mfma_f32_32x32x16_bf16 v[52:67], v[202:205], v[214:217], v[52:67]
	s_waitcnt vmcnt(16)
	ds_write_b128 v167, v[88:91] offset:18432
	v_mfma_f32_32x32x16_bf16 v[36:51], v[202:205], v[178:181], v[36:51]
	ds_write_b128 v167, v[96:99] offset:55296
	v_mfma_f32_32x32x16_bf16 v[20:35], v[174:177], v[214:217], v[20:35]
	ds_write_b128 v190, v[100:103] offset:18432
	v_mfma_f32_32x32x16_bf16 v[4:19], v[174:177], v[178:181], v[4:19]
	ds_write_b128 v190, v[108:111] offset:55296
	s_waitcnt lgkmcnt(4)
	v_mfma_f32_32x32x16_bf16 v[52:67], v[206:209], v[218:221], v[52:67]
	ds_write_b128 v191, v[116:119] offset:18432
	v_mfma_f32_32x32x16_bf16 v[36:51], v[206:209], v[222:225], v[36:51]
	ds_write_b128 v191, v[120:123] offset:55296
	v_mfma_f32_32x32x16_bf16 v[20:35], v[210:213], v[218:221], v[20:35]
	ds_write_b128 v192, v[124:127] offset:18432
	v_mfma_f32_32x32x16_bf16 v[4:19], v[210:213], v[222:225], v[4:19]
	ds_write_b128 v192, v[128:131] offset:55296
	s_waitcnt lgkmcnt(0)
	s_barrier
; #define MFMA(a, b, c) __builtin_amdgcn_mfma_f32_32x32x16_bf16((a), (b), (c), 0, 0, 0)
; template <class Epi, class ColV>
; DI void gemm_tile(const bf16_t* __restrict__ A, int lda, const bf16_t* __restrict__ Bt, int ldb, int K, int m0, int n0, unsigned char* smem, Epi epi, ColV colv, const bf16_t* __restrict__ HYT = nullptr) {
;     ...
;     auto gload = [&](u32x4 (&r)[8], int kt) {
; #pragma unroll
;         for (int i = 0; i < 4; ++i) { int id = tid + 256 * i, row = id >> 3, kc = id & 7;
;             if (HYT && kt >= 12) r[i] = *(const u32x4*)(HYT + (size_t)((kt - 12) * 64 + (id >> 4)) * NT + m0 + (id & 15) * 8);
;             else r[i] = *(const u32x4*)(A + (size_t)(m0 + row) * lda + kt * 64 + kc * 8);
;             r[4 + i] = *(const u32x4*)(Bt + (size_t)(n0 + row) * ldb + kt * 64 + kc * 8); }
;     };
;     auto sstore = [&](const u32x4 (&r)[8], int buf, int kt) {
; #pragma unroll
;         for (int i = 0; i < 4; ++i) { int id = tid + 256 * i, row = id >> 3, kc = id & 7;
;             if (HYT && kt >= 12) { const int kk = id >> 4, rr = (id & 15) * 8; bf16_t* d = As + (buf * 128 + rr) * LS + kk; const bf16x8 v = __builtin_bit_cast(bf16x8, r[i]);
; #pragma unroll
;                 for (int e = 0; e < 8; ++e) d[e * LS] = (bf16_t)v[e]; }
;             else *(u32x4*)(As + (buf * 128 + row) * LS + kc * 8) = r[i];
;             *(u32x4*)(Bs + (buf * 128 + row) * LS + kc * 8) = r[4 + i]; }
;     };
;     auto step = [&](int kt, u32x4 (&ldset)[8], const u32x4 (&stset)[8]) {
;         const int buf = kt & 1;
;         if (kt + 2 < nk) gload(ldset, kt + 2);
;         const bf16_t* Ab = As + (buf * 128 + 64 * wr + li) * LS + 8 * lh;
;         const bf16_t* Bb = Bs + (buf * 128 + 64 * wc + li) * LS + 8 * lh;
;         bf16x8 fa[2][2], fb[2][2], ga[2][2], gb[2][2];
; #pragma unroll
;         for (int k2 = 0; k2 < 2; ++k2) { fa[k2][0] = ld8(Ab + 16 * k2); fa[k2][1] = ld8(Ab + 32 * LS + 16 * k2); fb[k2][0] = ld8(Bb + 16 * k2); fb[k2][1] = ld8(Bb + 32 * LS + 16 * k2); }
;         __builtin_amdgcn_sched_barrier(0);
; #pragma unroll
;         for (int k2 = 0; k2 < 2; ++k2) {
;             acc[0][0] = MFMA(fa[k2][0], fb[k2][0], acc[0][0]); acc[0][1] = MFMA(fa[k2][0], fb[k2][1], acc[0][1]);
;             acc[1][0] = MFMA(fa[k2][1], fb[k2][0], acc[1][0]); acc[1][1] = MFMA(fa[k2][1], fb[k2][1], acc[1][1]);
;         }
; #pragma unroll
	s_setprio 1
	ds_read_b128 v[174:177], v196
	ds_read_b128 v[210:213], v197 offset:36864
	ds_read_b128 v[218:221], v197 offset:41472
	ds_read_b128 v[202:205], v196 offset:4608
	ds_read_b128 v[178:181], v196 offset:32
	ds_read_b128 v[222:225], v197 offset:41504
	ds_read_b128 v[206:209], v196 offset:4640
	ds_read_b128 v[214:217], v197 offset:36896
	s_waitcnt lgkmcnt(6)
	v_mfma_f32_32x32x16_bf16 v[52:67], v[174:177], v[210:213], v[52:67]
	global_load_dwordx4 v[88:91], v[164:165], off offset:512
	s_waitcnt lgkmcnt(5)
	v_mfma_f32_32x32x16_bf16 v[36:51], v[174:177], v[218:221], v[36:51]
	global_load_dwordx4 v[96:99], v[162:163], off offset:512
	s_waitcnt lgkmcnt(4)
	v_mfma_f32_32x32x16_bf16 v[4:19], v[202:205], v[218:221], v[4:19]
	global_load_dwordx4 v[100:103], v[160:161], off offset:512
	s_waitcnt lgkmcnt(2)
	v_mfma_f32_32x32x16_bf16 v[36:51], v[178:181], v[222:225], v[36:51]
	global_load_dwordx4 v[108:111], v[158:159], off offset:512
	s_waitcnt lgkmcnt(1)
	v_mfma_f32_32x32x16_bf16 v[4:19], v[206:209], v[222:225], v[4:19]
	global_load_dwordx4 v[116:119], v[156:157], off offset:512
	ds_read_b128 v[222:225], v197 offset:41568
	ds_read_b128 v[174:177], v196 offset:4672
	v_mfma_f32_32x32x16_bf16 v[20:35], v[202:205], v[210:213], v[20:35]
	global_load_dwordx4 v[120:123], v[154:155], off offset:512
	ds_read_b128 v[210:213], v196 offset:4704
	ds_read_b128 v[202:205], v196 offset:64
	s_waitcnt lgkmcnt(4)
	v_mfma_f32_32x32x16_bf16 v[52:67], v[178:181], v[214:217], v[52:67]
	global_load_dwordx4 v[124:127], v[152:153], off offset:512
	ds_read_b128 v[218:221], v197 offset:36960
	ds_read_b128 v[178:181], v197 offset:41536
	v_mfma_f32_32x32x16_bf16 v[20:35], v[206:209], v[214:217], v[20:35]
	s_setprio 0
	global_load_dwordx4 v[128:131], v[146:147], off offset:512
	ds_read_b128 v[214:217], v197 offset:36928
	ds_read_b128 v[206:209], v196 offset:96
	s_waitcnt lgkmcnt(1)
	v_mfma_f32_32x32x16_bf16 v[52:67], v[202:205], v[214:217], v[52:67]
	s_waitcnt vmcnt(23)
	ds_write_b128 v167, v[132:135]
	v_mfma_f32_32x32x16_bf16 v[36:51], v[202:205], v[178:181], v[36:51]
	s_waitcnt vmcnt(22)
	ds_write_b128 v167, v[136:139] offset:36864
	v_mfma_f32_32x32x16_bf16 v[20:35], v[174:177], v[214:217], v[20:35]
	s_waitcnt vmcnt(21)
	ds_write_b128 v190, v[140:143]
	v_mfma_f32_32x32x16_bf16 v[4:19], v[174:177], v[178:181], v[4:19]
	s_waitcnt vmcnt(20)
	ds_write_b128 v190, v[198:201] offset:36864
	s_waitcnt lgkmcnt(4)
	v_mfma_f32_32x32x16_bf16 v[52:67], v[206:209], v[218:221], v[52:67]
	s_waitcnt vmcnt(19)
	ds_write_b128 v191, v[226:229]
	v_mfma_f32_32x32x16_bf16 v[36:51], v[206:209], v[222:225], v[36:51]
	s_waitcnt vmcnt(18)
	ds_write_b128 v191, v[230:233] offset:36864
	v_mfma_f32_32x32x16_bf16 v[20:35], v[210:213], v[218:221], v[20:35]
	s_waitcnt vmcnt(17)
	ds_write_b128 v192, v[242:245]
	v_mfma_f32_32x32x16_bf16 v[4:19], v[210:213], v[222:225], v[4:19]
	s_waitcnt vmcnt(16)
	ds_write_b128 v192, v[246:249] offset:36864
	s_waitcnt lgkmcnt(0)
	s_barrier
	s_setprio 1
	ds_read_b128 v[174:177], v194
	ds_read_b128 v[210:213], v195 offset:36864
	ds_read_b128 v[218:221], v195 offset:41472
	ds_read_b128 v[202:205], v194 offset:4608
	ds_read_b128 v[178:181], v194 offset:32
	ds_read_b128 v[222:225], v195 offset:41504
	ds_read_b128 v[206:209], v194 offset:4640
	ds_read_b128 v[214:217], v195 offset:36896
	s_waitcnt lgkmcnt(6)
	v_mfma_f32_32x32x16_bf16 v[52:67], v[174:177], v[210:213], v[52:67]
	global_load_dwordx4 v[132:135], v[164:165], off offset:640
	s_waitcnt lgkmcnt(5)
	v_mfma_f32_32x32x16_bf16 v[36:51], v[174:177], v[218:221], v[36:51]
	global_load_dwordx4 v[136:139], v[162:163], off offset:640
	s_waitcnt lgkmcnt(4)
	v_mfma_f32_32x32x16_bf16 v[4:19], v[202:205], v[218:221], v[4:19]
	global_load_dwordx4 v[140:143], v[160:161], off offset:640
	s_waitcnt lgkmcnt(2)
	v_mfma_f32_32x32x16_bf16 v[36:51], v[178:181], v[222:225], v[36:51]
	global_load_dwordx4 v[198:201], v[158:159], off offset:640
	s_waitcnt lgkmcnt(1)
	v_mfma_f32_32x32x16_bf16 v[4:19], v[206:209], v[222:225], v[4:19]
	global_load_dwordx4 v[226:229], v[156:157], off offset:640
	ds_read_b128 v[222:225], v195 offset:41568
	ds_read_b128 v[174:177], v194 offset:4672
	v_mfma_f32_32x32x16_bf16 v[20:35], v[202:205], v[210:213], v[20:35]
	global_load_dwordx4 v[230:233], v[154:155], off offset:640
	ds_read_b128 v[210:213], v194 offset:4704
	ds_read_b128 v[202:205], v194 offset:64
	s_waitcnt lgkmcnt(4)
	v_mfma_f32_32x32x16_bf16 v[52:67], v[178:181], v[214:217], v[52:67]
	global_load_dwordx4 v[242:245], v[152:153], off offset:640
	ds_read_b128 v[218:221], v195 offset:36960
	ds_read_b128 v[178:181], v195 offset:41536
	v_mfma_f32_32x32x16_bf16 v[20:35], v[206:209], v[214:217], v[20:35]
	s_setprio 0
	global_load_dwordx4 v[246:249], v[146:147], off offset:640
	ds_read_b128 v[214:217], v195 offset:36928
	ds_read_b128 v[206:209], v194 offset:96
	s_waitcnt lgkmcnt(1)
	v_mfma_f32_32x32x16_bf16 v[52:67], v[202:205], v[214:217], v[52:67]
	s_waitcnt vmcnt(23)
	ds_write_b128 v167, v[68:71] offset:18432
	v_mfma_f32_32x32x16_bf16 v[36:51], v[202:205], v[178:181], v[36:51]
	s_waitcnt vmcnt(22)
	ds_write_b128 v167, v[72:75] offset:55296
	v_mfma_f32_32x32x16_bf16 v[20:35], v[174:177], v[214:217], v[20:35]
	s_waitcnt vmcnt(21)
	ds_write_b128 v190, v[76:79] offset:18432
	v_mfma_f32_32x32x16_bf16 v[4:19], v[174:177], v[178:181], v[4:19]
	s_waitcnt vmcnt(20)
	ds_write_b128 v190, v[80:83] offset:55296
	s_waitcnt lgkmcnt(4)
	v_mfma_f32_32x32x16_bf16 v[52:67], v[206:209], v[218:221], v[52:67]
	s_waitcnt vmcnt(19)
	ds_write_b128 v191, v[84:87] offset:18432
	v_mfma_f32_32x32x16_bf16 v[36:51], v[206:209], v[222:225], v[36:51]
	s_waitcnt vmcnt(18)
	ds_write_b128 v191, v[92:95] offset:55296
	v_mfma_f32_32x32x16_bf16 v[20:35], v[210:213], v[218:221], v[20:35]
	s_waitcnt vmcnt(17)
	ds_write_b128 v192, v[104:107] offset:18432
	v_mfma_f32_32x32x16_bf16 v[4:19], v[210:213], v[222:225], v[4:19]
	s_waitcnt vmcnt(16)
	ds_write_b128 v192, v[112:115] offset:55296
	s_waitcnt lgkmcnt(0)
	s_barrier
; #define MFMA(a, b, c) __builtin_amdgcn_mfma_f32_32x32x16_bf16((a), (b), (c), 0, 0, 0)
; template <class Epi, class ColV>
; DI void gemm_tile(const bf16_t* __restrict__ A, int lda, const bf16_t* __restrict__ Bt, int ldb, int K, int m0, int n0, unsigned char* smem, Epi epi, ColV colv, const bf16_t* __restrict__ HYT = nullptr) {
;     ...
;     auto gload = [&](u32x4 (&r)[8], int kt) {
; #pragma unroll
;         for (int i = 0; i < 4; ++i) { int id = tid + 256 * i, row = id >> 3, kc = id & 7;
;             if (HYT && kt >= 12) r[i] = *(const u32x4*)(HYT + (size_t)((kt - 12) * 64 + (id >> 4)) * NT + m0 + (id & 15) * 8);
;             else r[i] = *(const u32x4*)(A + (size_t)(m0 + row) * lda + kt * 64 + kc * 8);
;             r[4 + i] = *(const u32x4*)(Bt + (size_t)(n0 + row) * ldb + kt * 64 + kc * 8); }
;     };
;     auto sstore = [&](const u32x4 (&r)[8], int buf, int kt) {
; #pragma unroll
;         for (int i = 0; i < 4; ++i) { int id = tid + 256 * i, row = id >> 3, kc = id & 7;
;             if (HYT && kt >= 12) { const int kk = id >> 4, rr = (id & 15) * 8; bf16_t* d = As + (buf * 128 + rr) * LS + kk; const bf16x8 v = __builtin_bit_cast(bf16x8, r[i]);
; #pragma unroll
;                 for (int e = 0; e < 8; ++e) d[e * LS] = (bf16_t)v[e]; }
;             else *(u32x4*)(As + (buf * 128 + row) * LS + kc * 8) = r[i];
;             *(u32x4*)(Bs + (buf * 128 + row) * LS + kc * 8) = r[4 + i]; }
;     };
;     auto step = [&](int kt, u32x4 (&ldset)[8], const u32x4 (&stset)[8]) {
;         const int buf = kt & 1;
;         if (kt + 2 < nk) gload(ldset, kt + 2);
;         const bf16_t* Ab = As + (buf * 128 + 64 * wr + li) * LS + 8 * lh;
;         const bf16_t* Bb = Bs + (buf * 128 + 64 * wc + li) * LS + 8 * lh;
;         bf16x8 fa[2][2], fb[2][2], ga[2][2], gb[2][2];
; #pragma unroll
;         for (int k2 = 0; k2 < 2; ++k2) { fa[k2][0] = ld8(Ab + 16 * k2); fa[k2][1] = ld8(Ab + 32 * LS + 16 * k2); fb[k2][0] = ld8(Bb + 16 * k2); fb[k2][1] = ld8(Bb + 32 * LS + 16 * k2); }
;         __builtin_amdgcn_sched_barrier(0);
; #pragma unroll
;         for (int k2 = 0; k2 < 2; ++k2) {
;             acc[0][0] = MFMA(fa[k2][0], fb[k2][0], acc[0][0]); acc[0][1] = MFMA(fa[k2][0], fb[k2][1], acc[0][1]);
;             acc[1][0] = MFMA(fa[k2][1], fb[k2][0], acc[1][0]); acc[1][1] = MFMA(fa[k2][1], fb[k2][1], acc[1][1]);
;         }
; #pragma unroll
	s_setprio 1
	ds_read_b128 v[174:177], v196
	ds_read_b128 v[210:213], v197 offset:36864
	ds_read_b128 v[218:221], v197 offset:41472
	ds_read_b128 v[202:205], v196 offset:4608
	ds_read_b128 v[178:181], v196 offset:32
	ds_read_b128 v[222:225], v197 offset:41504
	ds_read_b128 v[206:209], v196 offset:4640
	ds_read_b128 v[214:217], v197 offset:36896
	s_waitcnt lgkmcnt(6)
	v_mfma_f32_32x32x16_bf16 v[52:67], v[174:177], v[210:213], v[52:67]
	global_load_dwordx4 v[68:71], v[164:165], off offset:768
	s_waitcnt lgkmcnt(5)
	v_mfma_f32_32x32x16_bf16 v[36:51], v[174:177], v[218:221], v[36:51]
	global_load_dwordx4 v[72:75], v[162:163], off offset:768
	s_waitcnt lgkmcnt(4)
	v_mfma_f32_32x32x16_bf16 v[4:19], v[202:205], v[218:221], v[4:19]
	global_load_dwordx4 v[76:79], v[160:161], off offset:768
	s_waitcnt lgkmcnt(2)
	v_mfma_f32_32x32x16_bf16 v[36:51], v[178:181], v[222:225], v[36:51]
	global_load_dwordx4 v[80:83], v[158:159], off offset:768
	s_waitcnt lgkmcnt(1)
	v_mfma_f32_32x32x16_bf16 v[4:19], v[206:209], v[222:225], v[4:19]
	global_load_dwordx4 v[84:87], v[156:157], off offset:768
	ds_read_b128 v[222:225], v197 offset:41568
	ds_read_b128 v[174:177], v196 offset:4672
	v_mfma_f32_32x32x16_bf16 v[20:35], v[202:205], v[210:213], v[20:35]
	global_load_dwordx4 v[92:95], v[154:155], off offset:768
	ds_read_b128 v[210:213], v196 offset:4704
	ds_read_b128 v[202:205], v196 offset:64
	s_waitcnt lgkmcnt(4)
	v_mfma_f32_32x32x16_bf16 v[52:67], v[178:181], v[214:217], v[52:67]
	global_load_dwordx4 v[104:107], v[152:153], off offset:768
	ds_read_b128 v[218:221], v197 offset:36960
	ds_read_b128 v[178:181], v197 offset:41536
	v_mfma_f32_32x32x16_bf16 v[20:35], v[206:209], v[214:217], v[20:35]
	s_setprio 0
	global_load_dwordx4 v[112:115], v[146:147], off offset:768
	ds_read_b128 v[214:217], v197 offset:36928
	ds_read_b128 v[206:209], v196 offset:96
	s_waitcnt lgkmcnt(1)
	v_mfma_f32_32x32x16_bf16 v[52:67], v[202:205], v[214:217], v[52:67]
	s_waitcnt vmcnt(23)
	ds_write_b128 v167, v[88:91]
	v_mfma_f32_32x32x16_bf16 v[36:51], v[202:205], v[178:181], v[36:51]
	s_waitcnt vmcnt(22)
	ds_write_b128 v167, v[96:99] offset:36864
	v_mfma_f32_32x32x16_bf16 v[20:35], v[174:177], v[214:217], v[20:35]
	s_waitcnt vmcnt(21)
	ds_write_b128 v190, v[100:103]
	v_mfma_f32_32x32x16_bf16 v[4:19], v[174:177], v[178:181], v[4:19]
	s_waitcnt vmcnt(20)
	ds_write_b128 v190, v[108:111] offset:36864
	s_waitcnt lgkmcnt(4)
	v_mfma_f32_32x32x16_bf16 v[52:67], v[206:209], v[218:221], v[52:67]
	s_waitcnt vmcnt(19)
	ds_write_b128 v191, v[116:119]
	v_mfma_f32_32x32x16_bf16 v[36:51], v[206:209], v[222:225], v[36:51]
	s_waitcnt vmcnt(18)
	ds_write_b128 v191, v[120:123] offset:36864
	v_mfma_f32_32x32x16_bf16 v[20:35], v[210:213], v[218:221], v[20:35]
	s_waitcnt vmcnt(17)
	ds_write_b128 v192, v[124:127]
	v_mfma_f32_32x32x16_bf16 v[4:19], v[210:213], v[222:225], v[4:19]
	s_waitcnt vmcnt(16)
	ds_write_b128 v192, v[128:131] offset:36864
	s_waitcnt lgkmcnt(0)
	s_barrier
	s_setprio 1
	ds_read_b128 v[174:177], v194
	ds_read_b128 v[210:213], v195 offset:36864
	ds_read_b128 v[218:221], v195 offset:41472
	ds_read_b128 v[202:205], v194 offset:4608
	ds_read_b128 v[178:181], v194 offset:32
	ds_read_b128 v[222:225], v195 offset:41504
	ds_read_b128 v[206:209], v194 offset:4640
	ds_read_b128 v[214:217], v195 offset:36896
	s_waitcnt lgkmcnt(6)
	v_mfma_f32_32x32x16_bf16 v[52:67], v[174:177], v[210:213], v[52:67]
	global_load_dwordx4 v[88:91], v[164:165], off offset:896
	s_waitcnt lgkmcnt(5)
	v_mfma_f32_32x32x16_bf16 v[36:51], v[174:177], v[218:221], v[36:51]
	global_load_dwordx4 v[96:99], v[162:163], off offset:896
	s_waitcnt lgkmcnt(4)
	v_mfma_f32_32x32x16_bf16 v[4:19], v[202:205], v[218:221], v[4:19]
	global_load_dwordx4 v[100:103], v[160:161], off offset:896
	s_waitcnt lgkmcnt(2)
	v_mfma_f32_32x32x16_bf16 v[36:51], v[178:181], v[222:225], v[36:51]
	global_load_dwordx4 v[108:111], v[158:159], off offset:896
	s_waitcnt lgkmcnt(1)
	v_mfma_f32_32x32x16_bf16 v[4:19], v[206:209], v[222:225], v[4:19]
	global_load_dwordx4 v[116:119], v[156:157], off offset:896
	ds_read_b128 v[222:225], v195 offset:41568
	ds_read_b128 v[174:177], v194 offset:4672
	v_mfma_f32_32x32x16_bf16 v[20:35], v[202:205], v[210:213], v[20:35]
	global_load_dwordx4 v[120:123], v[154:155], off offset:896
	ds_read_b128 v[210:213], v194 offset:4704
	ds_read_b128 v[202:205], v194 offset:64
	s_waitcnt lgkmcnt(4)
	v_mfma_f32_32x32x16_bf16 v[52:67], v[178:181], v[214:217], v[52:67]
	global_load_dwordx4 v[124:127], v[152:153], off offset:896
	ds_read_b128 v[218:221], v195 offset:36960
	ds_read_b128 v[178:181], v195 offset:41536
	v_mfma_f32_32x32x16_bf16 v[20:35], v[206:209], v[214:217], v[20:35]
	s_setprio 0
	global_load_dwordx4 v[128:131], v[146:147], off offset:896
	ds_read_b128 v[214:217], v195 offset:36928
	ds_read_b128 v[206:209], v194 offset:96
	s_waitcnt lgkmcnt(1)
	v_mfma_f32_32x32x16_bf16 v[52:67], v[202:205], v[214:217], v[52:67]
	s_waitcnt vmcnt(23)
	ds_write_b128 v167, v[132:135] offset:18432
	v_mfma_f32_32x32x16_bf16 v[36:51], v[202:205], v[178:181], v[36:51]
	s_waitcnt vmcnt(22)
	ds_write_b128 v167, v[136:139] offset:55296
	v_mfma_f32_32x32x16_bf16 v[20:35], v[174:177], v[214:217], v[20:35]
	s_waitcnt vmcnt(21)
	ds_write_b128 v190, v[140:143] offset:18432
	v_mfma_f32_32x32x16_bf16 v[4:19], v[174:177], v[178:181], v[4:19]
	s_waitcnt vmcnt(20)
	ds_write_b128 v190, v[198:201] offset:55296
	s_waitcnt lgkmcnt(4)
	v_mfma_f32_32x32x16_bf16 v[52:67], v[206:209], v[218:221], v[52:67]
	s_waitcnt vmcnt(19)
	ds_write_b128 v191, v[226:229] offset:18432
	v_mfma_f32_32x32x16_bf16 v[36:51], v[206:209], v[222:225], v[36:51]
	s_waitcnt vmcnt(18)
	ds_write_b128 v191, v[230:233] offset:55296
	v_mfma_f32_32x32x16_bf16 v[20:35], v[210:213], v[218:221], v[20:35]
	s_waitcnt vmcnt(17)
	ds_write_b128 v192, v[242:245] offset:18432
	v_mfma_f32_32x32x16_bf16 v[4:19], v[210:213], v[222:225], v[4:19]
	s_waitcnt vmcnt(16)
	ds_write_b128 v192, v[246:249] offset:55296
	s_waitcnt lgkmcnt(0)
	s_barrier
; #define MFMA(a, b, c) __builtin_amdgcn_mfma_f32_32x32x16_bf16((a), (b), (c), 0, 0, 0)
; template <class Epi, class ColV>
; DI void gemm_tile(const bf16_t* __restrict__ A, int lda, const bf16_t* __restrict__ Bt, int ldb, int K, int m0, int n0, unsigned char* smem, Epi epi, ColV colv, const bf16_t* __restrict__ HYT = nullptr) {
;     ...
;     auto gload = [&](u32x4 (&r)[8], int kt) {
; #pragma unroll
;         for (int i = 0; i < 4; ++i) { int id = tid + 256 * i, row = id >> 3, kc = id & 7;
;             if (HYT && kt >= 12) r[i] = *(const u32x4*)(HYT + (size_t)((kt - 12) * 64 + (id >> 4)) * NT + m0 + (id & 15) * 8);
;             else r[i] = *(const u32x4*)(A + (size_t)(m0 + row) * lda + kt * 64 + kc * 8);
;             r[4 + i] = *(const u32x4*)(Bt + (size_t)(n0 + row) * ldb + kt * 64 + kc * 8); }
;     };
;     auto sstore = [&](const u32x4 (&r)[8], int buf, int kt) {
; #pragma unroll
;         for (int i = 0; i < 4; ++i) { int id = tid + 256 * i, row = id >> 3, kc = id & 7;
;             if (HYT && kt >= 12) { const int kk = id >> 4, rr = (id & 15) * 8; bf16_t* d = As + (buf * 128 + rr) * LS + kk; const bf16x8 v = __builtin_bit_cast(bf16x8, r[i]);
; #pragma unroll
;                 for (int e = 0; e < 8; ++e) d[e * LS] = (bf16_t)v[e]; }
;             else *(u32x4*)(As + (buf * 128 + row) * LS + kc * 8) = r[i];
;             *(u32x4*)(Bs + (buf * 128 + row) * LS + kc * 8) = r[4 + i]; }
;     };
;     auto step = [&](int kt, u32x4 (&ldset)[8], const u32x4 (&stset)[8]) {
;         const int buf = kt & 1;
;         if (kt + 2 < nk) gload(ldset, kt + 2);
;         const bf16_t* Ab = As + (buf * 128 + 64 * wr + li) * LS + 8 * lh;
;         const bf16_t* Bb = Bs + (buf * 128 + 64 * wc + li) * LS + 8 * lh;
;         bf16x8 fa[2][2], fb[2][2], ga[2][2], gb[2][2];
; #pragma unroll
;         for (int k2 = 0; k2 < 2; ++k2) { fa[k2][0] = ld8(Ab + 16 * k2); fa[k2][1] = ld8(Ab + 32 * LS + 16 * k2); fb[k2][0] = ld8(Bb + 16 * k2); fb[k2][1] = ld8(Bb + 32 * LS + 16 * k2); }
;         __builtin_amdgcn_sched_barrier(0);
; #pragma unroll
;         for (int k2 = 0; k2 < 2; ++k2) {
;             acc[0][0] = MFMA(fa[k2][0], fb[k2][0], acc[0][0]); acc[0][1] = MFMA(fa[k2][0], fb[k2][1], acc[0][1]);
;             acc[1][0] = MFMA(fa[k2][1], fb[k2][0], acc[1][0]); acc[1][1] = MFMA(fa[k2][1], fb[k2][1], acc[1][1]);
;         }
; #pragma unroll
	s_setprio 1
	ds_read_b128 v[174:177], v196
	ds_read_b128 v[210:213], v197 offset:36864
	ds_read_b128 v[218:221], v197 offset:41472
	ds_read_b128 v[202:205], v196 offset:4608
	ds_read_b128 v[178:181], v196 offset:32
	ds_read_b128 v[222:225], v197 offset:41504
	ds_read_b128 v[206:209], v196 offset:4640
	ds_read_b128 v[214:217], v197 offset:36896
	s_waitcnt lgkmcnt(6)
	v_mfma_f32_32x32x16_bf16 v[52:67], v[174:177], v[210:213], v[52:67]
	global_load_dwordx4 v[132:135], v[164:165], off offset:1024
	s_waitcnt lgkmcnt(5)
	v_mfma_f32_32x32x16_bf16 v[36:51], v[174:177], v[218:221], v[36:51]
	global_load_dwordx4 v[136:139], v[162:163], off offset:1024
	s_waitcnt lgkmcnt(4)
	v_mfma_f32_32x32x16_bf16 v[4:19], v[202:205], v[218:221], v[4:19]
	global_load_dwordx4 v[140:143], v[160:161], off offset:1024
	s_waitcnt lgkmcnt(2)
	v_mfma_f32_32x32x16_bf16 v[36:51], v[178:181], v[222:225], v[36:51]
	global_load_dwordx4 v[198:201], v[158:159], off offset:1024
	s_waitcnt lgkmcnt(1)
	v_mfma_f32_32x32x16_bf16 v[4:19], v[206:209], v[222:225], v[4:19]
	global_load_dwordx4 v[226:229], v[156:157], off offset:1024
	ds_read_b128 v[222:225], v197 offset:41568
	ds_read_b128 v[174:177], v196 offset:4672
	v_mfma_f32_32x32x16_bf16 v[20:35], v[202:205], v[210:213], v[20:35]
	global_load_dwordx4 v[230:233], v[154:155], off offset:1024
	ds_read_b128 v[210:213], v196 offset:4704
	ds_read_b128 v[202:205], v196 offset:64
	s_waitcnt lgkmcnt(4)
	v_mfma_f32_32x32x16_bf16 v[52:67], v[178:181], v[214:217], v[52:67]
	global_load_dwordx4 v[242:245], v[152:153], off offset:1024
	ds_read_b128 v[218:221], v197 offset:36960
	ds_read_b128 v[178:181], v197 offset:41536
	v_mfma_f32_32x32x16_bf16 v[20:35], v[206:209], v[214:217], v[20:35]
	s_setprio 0
	global_load_dwordx4 v[246:249], v[146:147], off offset:1024
	ds_read_b128 v[214:217], v197 offset:36928
	ds_read_b128 v[206:209], v196 offset:96
	s_waitcnt lgkmcnt(1)
	v_mfma_f32_32x32x16_bf16 v[52:67], v[202:205], v[214:217], v[52:67]
	s_waitcnt vmcnt(23)
	ds_write_b128 v167, v[68:71]
	v_mfma_f32_32x32x16_bf16 v[36:51], v[202:205], v[178:181], v[36:51]
	s_waitcnt vmcnt(22)
	ds_write_b128 v167, v[72:75] offset:36864
	v_mfma_f32_32x32x16_bf16 v[20:35], v[174:177], v[214:217], v[20:35]
	s_waitcnt vmcnt(21)
	ds_write_b128 v190, v[76:79]
	v_mfma_f32_32x32x16_bf16 v[4:19], v[174:177], v[178:181], v[4:19]
	s_waitcnt vmcnt(20)
	ds_write_b128 v190, v[80:83] offset:36864
	s_waitcnt lgkmcnt(4)
	v_mfma_f32_32x32x16_bf16 v[52:67], v[206:209], v[218:221], v[52:67]
	s_waitcnt vmcnt(19)
	ds_write_b128 v191, v[84:87]
	v_mfma_f32_32x32x16_bf16 v[36:51], v[206:209], v[222:225], v[36:51]
	s_waitcnt vmcnt(18)
	ds_write_b128 v191, v[92:95] offset:36864
	v_mfma_f32_32x32x16_bf16 v[20:35], v[210:213], v[218:221], v[20:35]
	s_waitcnt vmcnt(17)
	ds_write_b128 v192, v[104:107]
	v_mfma_f32_32x32x16_bf16 v[4:19], v[210:213], v[222:225], v[4:19]
	s_waitcnt vmcnt(16)
	ds_write_b128 v192, v[112:115] offset:36864
	s_waitcnt lgkmcnt(0)
	s_barrier
	s_setprio 1
	ds_read_b128 v[174:177], v194
	ds_read_b128 v[210:213], v195 offset:36864
	ds_read_b128 v[218:221], v195 offset:41472
	ds_read_b128 v[202:205], v194 offset:4608
	ds_read_b128 v[178:181], v194 offset:32
	ds_read_b128 v[222:225], v195 offset:41504
	ds_read_b128 v[206:209], v194 offset:4640
	ds_read_b128 v[214:217], v195 offset:36896
	s_waitcnt lgkmcnt(6)
	v_mfma_f32_32x32x16_bf16 v[52:67], v[174:177], v[210:213], v[52:67]
	global_load_dwordx4 v[68:71], v[164:165], off offset:1152
	s_waitcnt lgkmcnt(5)
	v_mfma_f32_32x32x16_bf16 v[36:51], v[174:177], v[218:221], v[36:51]
	global_load_dwordx4 v[72:75], v[162:163], off offset:1152
	s_waitcnt lgkmcnt(4)
	v_mfma_f32_32x32x16_bf16 v[4:19], v[202:205], v[218:221], v[4:19]
	global_load_dwordx4 v[76:79], v[160:161], off offset:1152
	s_waitcnt lgkmcnt(2)
	v_mfma_f32_32x32x16_bf16 v[36:51], v[178:181], v[222:225], v[36:51]
	global_load_dwordx4 v[80:83], v[158:159], off offset:1152
	s_waitcnt lgkmcnt(1)
	v_mfma_f32_32x32x16_bf16 v[4:19], v[206:209], v[222:225], v[4:19]
	global_load_dwordx4 v[84:87], v[156:157], off offset:1152
	ds_read_b128 v[222:225], v195 offset:41568
	ds_read_b128 v[174:177], v194 offset:4672
	v_mfma_f32_32x32x16_bf16 v[20:35], v[202:205], v[210:213], v[20:35]
	global_load_dwordx4 v[92:95], v[154:155], off offset:1152
	ds_read_b128 v[210:213], v194 offset:4704
	ds_read_b128 v[202:205], v194 offset:64
	s_waitcnt lgkmcnt(4)
	v_mfma_f32_32x32x16_bf16 v[52:67], v[178:181], v[214:217], v[52:67]
	global_load_dwordx4 v[104:107], v[152:153], off offset:1152
	ds_read_b128 v[218:221], v195 offset:36960
	ds_read_b128 v[178:181], v195 offset:41536
	v_mfma_f32_32x32x16_bf16 v[20:35], v[206:209], v[214:217], v[20:35]
	s_setprio 0
	global_load_dwordx4 v[112:115], v[146:147], off offset:1152
	ds_read_b128 v[214:217], v195 offset:36928
	ds_read_b128 v[206:209], v194 offset:96
	s_waitcnt lgkmcnt(1)
	v_mfma_f32_32x32x16_bf16 v[52:67], v[202:205], v[214:217], v[52:67]
	s_waitcnt vmcnt(23)
	ds_write_b128 v167, v[88:91] offset:18432
	v_mfma_f32_32x32x16_bf16 v[36:51], v[202:205], v[178:181], v[36:51]
	s_waitcnt vmcnt(22)
	ds_write_b128 v167, v[96:99] offset:55296
	v_mfma_f32_32x32x16_bf16 v[20:35], v[174:177], v[214:217], v[20:35]
	s_waitcnt vmcnt(21)
	ds_write_b128 v190, v[100:103] offset:18432
	v_mfma_f32_32x32x16_bf16 v[4:19], v[174:177], v[178:181], v[4:19]
	s_waitcnt vmcnt(20)
	ds_write_b128 v190, v[108:111] offset:55296
	s_waitcnt lgkmcnt(4)
	v_mfma_f32_32x32x16_bf16 v[52:67], v[206:209], v[218:221], v[52:67]
	s_waitcnt vmcnt(19)
	ds_write_b128 v191, v[116:119] offset:18432
	v_mfma_f32_32x32x16_bf16 v[36:51], v[206:209], v[222:225], v[36:51]
	s_waitcnt vmcnt(18)
	ds_write_b128 v191, v[120:123] offset:55296
	v_mfma_f32_32x32x16_bf16 v[20:35], v[210:213], v[218:221], v[20:35]
	s_waitcnt vmcnt(17)
	ds_write_b128 v192, v[124:127] offset:18432
	v_mfma_f32_32x32x16_bf16 v[4:19], v[210:213], v[222:225], v[4:19]
	s_waitcnt vmcnt(16)
	ds_write_b128 v192, v[128:131] offset:55296
	s_waitcnt lgkmcnt(0)
	s_barrier
; #define MFMA(a, b, c) __builtin_amdgcn_mfma_f32_32x32x16_bf16((a), (b), (c), 0, 0, 0)
; template <class Epi, class ColV>
; DI void gemm_tile(const bf16_t* __restrict__ A, int lda, const bf16_t* __restrict__ Bt, int ldb, int K, int m0, int n0, unsigned char* smem, Epi epi, ColV colv, const bf16_t* __restrict__ HYT = nullptr) {
;     ...
;     auto gload = [&](u32x4 (&r)[8], int kt) {
; #pragma unroll
;         for (int i = 0; i < 4; ++i) { int id = tid + 256 * i, row = id >> 3, kc = id & 7;
;             if (HYT && kt >= 12) r[i] = *(const u32x4*)(HYT + (size_t)((kt - 12) * 64 + (id >> 4)) * NT + m0 + (id & 15) * 8);
;             else r[i] = *(const u32x4*)(A + (size_t)(m0 + row) * lda + kt * 64 + kc * 8);
;             r[4 + i] = *(const u32x4*)(Bt + (size_t)(n0 + row) * ldb + kt * 64 + kc * 8); }
;     };
;     auto sstore = [&](const u32x4 (&r)[8], int buf, int kt) {
; #pragma unroll
;         for (int i = 0; i < 4; ++i) { int id = tid + 256 * i, row = id >> 3, kc = id & 7;
;             if (HYT && kt >= 12) { const int kk = id >> 4, rr = (id & 15) * 8; bf16_t* d = As + (buf * 128 + rr) * LS + kk; const bf16x8 v = __builtin_bit_cast(bf16x8, r[i]);
; #pragma unroll
;                 for (int e = 0; e < 8; ++e) d[e * LS] = (bf16_t)v[e]; }
;             else *(u32x4*)(As + (buf * 128 + row) * LS + kc * 8) = r[i];
;             *(u32x4*)(Bs + (buf * 128 + row) * LS + kc * 8) = r[4 + i]; }
;     };
;     auto step = [&](int kt, u32x4 (&ldset)[8], const u32x4 (&stset)[8]) {
;         const int buf = kt & 1;
;         if (kt + 2 < nk) gload(ldset, kt + 2);
;         const bf16_t* Ab = As + (buf * 128 + 64 * wr + li) * LS + 8 * lh;
;         const bf16_t* Bb = Bs + (buf * 128 + 64 * wc + li) * LS + 8 * lh;
;         bf16x8 fa[2][2], fb[2][2], ga[2][2], gb[2][2];
; #pragma unroll
;         for (int k2 = 0; k2 < 2; ++k2) { fa[k2][0] = ld8(Ab + 16 * k2); fa[k2][1] = ld8(Ab + 32 * LS + 16 * k2); fb[k2][0] = ld8(Bb + 16 * k2); fb[k2][1] = ld8(Bb + 32 * LS + 16 * k2); }
;         __builtin_amdgcn_sched_barrier(0);
; #pragma unroll
;         for (int k2 = 0; k2 < 2; ++k2) {
;             acc[0][0] = MFMA(fa[k2][0], fb[k2][0], acc[0][0]); acc[0][1] = MFMA(fa[k2][0], fb[k2][1], acc[0][1]);
;             acc[1][0] = MFMA(fa[k2][1], fb[k2][0], acc[1][0]); acc[1][1] = MFMA(fa[k2][1], fb[k2][1], acc[1][1]);
;         }
; #pragma unroll
	s_setprio 1
	ds_read_b128 v[174:177], v196
	ds_read_b128 v[210:213], v197 offset:36864
	ds_read_b128 v[218:221], v197 offset:41472
	ds_read_b128 v[202:205], v196 offset:4608
	ds_read_b128 v[178:181], v196 offset:32
	ds_read_b128 v[222:225], v197 offset:41504
	ds_read_b128 v[206:209], v196 offset:4640
	ds_read_b128 v[214:217], v197 offset:36896
	s_waitcnt lgkmcnt(6)
	v_mfma_f32_32x32x16_bf16 v[52:67], v[174:177], v[210:213], v[52:67]
	global_load_dwordx4 v[88:91], v[164:165], off offset:1280
	s_waitcnt lgkmcnt(5)
	v_mfma_f32_32x32x16_bf16 v[36:51], v[174:177], v[218:221], v[36:51]
	global_load_dwordx4 v[96:99], v[162:163], off offset:1280
	s_waitcnt lgkmcnt(4)
	v_mfma_f32_32x32x16_bf16 v[4:19], v[202:205], v[218:221], v[4:19]
	global_load_dwordx4 v[100:103], v[160:161], off offset:1280
	s_waitcnt lgkmcnt(2)
	v_mfma_f32_32x32x16_bf16 v[36:51], v[178:181], v[222:225], v[36:51]
	global_load_dwordx4 v[108:111], v[158:159], off offset:1280
	s_waitcnt lgkmcnt(1)
	v_mfma_f32_32x32x16_bf16 v[4:19], v[206:209], v[222:225], v[4:19]
	global_load_dwordx4 v[116:119], v[156:157], off offset:1280
	ds_read_b128 v[222:225], v197 offset:41568
	ds_read_b128 v[174:177], v196 offset:4672
	v_mfma_f32_32x32x16_bf16 v[20:35], v[202:205], v[210:213], v[20:35]
	global_load_dwordx4 v[120:123], v[154:155], off offset:1280
	ds_read_b128 v[210:213], v196 offset:4704
	ds_read_b128 v[202:205], v196 offset:64
	s_waitcnt lgkmcnt(4)
	v_mfma_f32_32x32x16_bf16 v[52:67], v[178:181], v[214:217], v[52:67]
	global_load_dwordx4 v[124:127], v[152:153], off offset:1280
	ds_read_b128 v[218:221], v197 offset:36960
	ds_read_b128 v[178:181], v197 offset:41536
	v_mfma_f32_32x32x16_bf16 v[20:35], v[206:209], v[214:217], v[20:35]
	s_setprio 0
	global_load_dwordx4 v[128:131], v[146:147], off offset:1280
	ds_read_b128 v[214:217], v197 offset:36928
	ds_read_b128 v[206:209], v196 offset:96
	s_waitcnt lgkmcnt(1)
	v_mfma_f32_32x32x16_bf16 v[52:67], v[202:205], v[214:217], v[52:67]
	s_waitcnt vmcnt(23)
	ds_write_b128 v167, v[132:135]
	v_mfma_f32_32x32x16_bf16 v[36:51], v[202:205], v[178:181], v[36:51]
	s_waitcnt vmcnt(22)
	ds_write_b128 v167, v[136:139] offset:36864
	v_mfma_f32_32x32x16_bf16 v[20:35], v[174:177], v[214:217], v[20:35]
	s_waitcnt vmcnt(21)
	ds_write_b128 v190, v[140:143]
	v_mfma_f32_32x32x16_bf16 v[4:19], v[174:177], v[178:181], v[4:19]
	s_waitcnt vmcnt(20)
	ds_write_b128 v190, v[198:201] offset:36864
	s_waitcnt lgkmcnt(4)
	v_mfma_f32_32x32x16_bf16 v[52:67], v[206:209], v[218:221], v[52:67]
	s_waitcnt vmcnt(19)
	ds_write_b128 v191, v[226:229]
	v_mfma_f32_32x32x16_bf16 v[36:51], v[206:209], v[222:225], v[36:51]
	s_waitcnt vmcnt(18)
	ds_write_b128 v191, v[230:233] offset:36864
	v_mfma_f32_32x32x16_bf16 v[20:35], v[210:213], v[218:221], v[20:35]
	s_waitcnt vmcnt(17)
	ds_write_b128 v192, v[242:245]
	v_mfma_f32_32x32x16_bf16 v[4:19], v[210:213], v[222:225], v[4:19]
	s_waitcnt vmcnt(16)
	ds_write_b128 v192, v[246:249] offset:36864
	s_waitcnt lgkmcnt(0)
	s_barrier
	s_setprio 1
	ds_read_b128 v[174:177], v194
	ds_read_b128 v[210:213], v195 offset:36864
	ds_read_b128 v[218:221], v195 offset:41472
	ds_read_b128 v[202:205], v194 offset:4608
	ds_read_b128 v[178:181], v194 offset:32
	ds_read_b128 v[222:225], v195 offset:41504
	ds_read_b128 v[206:209], v194 offset:4640
	ds_read_b128 v[214:217], v195 offset:36896
	s_waitcnt lgkmcnt(6)
	v_mfma_f32_32x32x16_bf16 v[52:67], v[174:177], v[210:213], v[52:67]
	global_load_dwordx4 v[132:135], v[164:165], off offset:1408
	s_waitcnt lgkmcnt(5)
	v_mfma_f32_32x32x16_bf16 v[36:51], v[174:177], v[218:221], v[36:51]
	global_load_dwordx4 v[136:139], v[162:163], off offset:1408
	s_waitcnt lgkmcnt(4)
	v_mfma_f32_32x32x16_bf16 v[4:19], v[202:205], v[218:221], v[4:19]
	global_load_dwordx4 v[140:143], v[160:161], off offset:1408
	s_waitcnt lgkmcnt(2)
	v_mfma_f32_32x32x16_bf16 v[36:51], v[178:181], v[222:225], v[36:51]
	global_load_dwordx4 v[198:201], v[158:159], off offset:1408
	s_waitcnt lgkmcnt(1)
	v_mfma_f32_32x32x16_bf16 v[4:19], v[206:209], v[222:225], v[4:19]
	global_load_dwordx4 v[226:229], v[156:157], off offset:1408
	ds_read_b128 v[222:225], v195 offset:41568
	ds_read_b128 v[174:177], v194 offset:4672
	v_mfma_f32_32x32x16_bf16 v[20:35], v[202:205], v[210:213], v[20:35]
	global_load_dwordx4 v[230:233], v[154:155], off offset:1408
	ds_read_b128 v[210:213], v194 offset:4704
	ds_read_b128 v[202:205], v194 offset:64
	s_waitcnt lgkmcnt(4)
	v_mfma_f32_32x32x16_bf16 v[52:67], v[178:181], v[214:217], v[52:67]
	global_load_dwordx4 v[242:245], v[152:153], off offset:1408
	ds_read_b128 v[218:221], v195 offset:36960
	ds_read_b128 v[178:181], v195 offset:41536
	v_mfma_f32_32x32x16_bf16 v[20:35], v[206:209], v[214:217], v[20:35]
	s_setprio 0
	global_load_dwordx4 v[246:249], v[146:147], off offset:1408
	ds_read_b128 v[214:217], v195 offset:36928
	ds_read_b128 v[206:209], v194 offset:96
	s_waitcnt lgkmcnt(1)
	v_mfma_f32_32x32x16_bf16 v[52:67], v[202:205], v[214:217], v[52:67]
	s_waitcnt vmcnt(23)
	ds_write_b128 v167, v[68:71] offset:18432
	v_mfma_f32_32x32x16_bf16 v[36:51], v[202:205], v[178:181], v[36:51]
	s_waitcnt vmcnt(22)
	ds_write_b128 v167, v[72:75] offset:55296
	v_mfma_f32_32x32x16_bf16 v[20:35], v[174:177], v[214:217], v[20:35]
	s_waitcnt vmcnt(21)
	ds_write_b128 v190, v[76:79] offset:18432
	v_mfma_f32_32x32x16_bf16 v[4:19], v[174:177], v[178:181], v[4:19]
	s_waitcnt vmcnt(20)
	ds_write_b128 v190, v[80:83] offset:55296
	s_waitcnt lgkmcnt(4)
	v_mfma_f32_32x32x16_bf16 v[52:67], v[206:209], v[218:221], v[52:67]
	s_waitcnt vmcnt(19)
	ds_write_b128 v191, v[84:87] offset:18432
	v_mfma_f32_32x32x16_bf16 v[36:51], v[206:209], v[222:225], v[36:51]
	s_waitcnt vmcnt(18)
	ds_write_b128 v191, v[92:95] offset:55296
	v_mfma_f32_32x32x16_bf16 v[20:35], v[210:213], v[218:221], v[20:35]
	s_waitcnt vmcnt(17)
	ds_write_b128 v192, v[104:107] offset:18432
	v_mfma_f32_32x32x16_bf16 v[4:19], v[210:213], v[222:225], v[4:19]
	s_waitcnt vmcnt(16)
	ds_write_b128 v192, v[112:115] offset:55296
	s_waitcnt lgkmcnt(0)
	s_barrier
; #define MFMA(a, b, c) __builtin_amdgcn_mfma_f32_32x32x16_bf16((a), (b), (c), 0, 0, 0)
; template <class Epi, class ColV>
; DI void gemm_tile(const bf16_t* __restrict__ A, int lda, const bf16_t* __restrict__ Bt, int ldb, int K, int m0, int n0, unsigned char* smem, Epi epi, ColV colv, const bf16_t* __restrict__ HYT = nullptr) {
;     ...
;     auto gload = [&](u32x4 (&r)[8], int kt) {
; #pragma unroll
;         for (int i = 0; i < 4; ++i) { int id = tid + 256 * i, row = id >> 3, kc = id & 7;
;             if (HYT && kt >= 12) r[i] = *(const u32x4*)(HYT + (size_t)((kt - 12) * 64 + (id >> 4)) * NT + m0 + (id & 15) * 8);
;             else r[i] = *(const u32x4*)(A + (size_t)(m0 + row) * lda + kt * 64 + kc * 8);
;             r[4 + i] = *(const u32x4*)(Bt + (size_t)(n0 + row) * ldb + kt * 64 + kc * 8); }
;     };
;     auto sstore = [&](const u32x4 (&r)[8], int buf, int kt) {
; #pragma unroll
;         for (int i = 0; i < 4; ++i) { int id = tid + 256 * i, row = id >> 3, kc = id & 7;
;             if (HYT && kt >= 12) { const int kk = id >> 4, rr = (id & 15) * 8; bf16_t* d = As + (buf * 128 + rr) * LS + kk; const bf16x8 v = __builtin_bit_cast(bf16x8, r[i]);
; #pragma unroll
;                 for (int e = 0; e < 8; ++e) d[e * LS] = (bf16_t)v[e]; }
;             else *(u32x4*)(As + (buf * 128 + row) * LS + kc * 8) = r[i];
;             *(u32x4*)(Bs + (buf * 128 + row) * LS + kc * 8) = r[4 + i]; }
;     };
;     auto step = [&](int kt, u32x4 (&ldset)[8], const u32x4 (&stset)[8]) {
;         const int buf = kt & 1;
;         if (kt + 2 < nk) gload(ldset, kt + 2);
;         const bf16_t* Ab = As + (buf * 128 + 64 * wr + li) * LS + 8 * lh;
;         const bf16_t* Bb = Bs + (buf * 128 + 64 * wc + li) * LS + 8 * lh;
;         bf16x8 fa[2][2], fb[2][2], ga[2][2], gb[2][2];
; #pragma unroll
;         for (int k2 = 0; k2 < 2; ++k2) { fa[k2][0] = ld8(Ab + 16 * k2); fa[k2][1] = ld8(Ab + 32 * LS + 16 * k2); fb[k2][0] = ld8(Bb + 16 * k2); fb[k2][1] = ld8(Bb + 32 * LS + 16 * k2); }
;         __builtin_amdgcn_sched_barrier(0);
; #pragma unroll
;         for (int k2 = 0; k2 < 2; ++k2) {
;             acc[0][0] = MFMA(fa[k2][0], fb[k2][0], acc[0][0]); acc[0][1] = MFMA(fa[k2][0], fb[k2][1], acc[0][1]);
;             acc[1][0] = MFMA(fa[k2][1], fb[k2][0], acc[1][0]); acc[1][1] = MFMA(fa[k2][1], fb[k2][1], acc[1][1]);
;         }
; #pragma unroll
	s_setprio 1
	ds_read_b128 v[174:177], v196
	ds_read_b128 v[210:213], v197 offset:36864
	ds_read_b128 v[218:221], v197 offset:41472
	ds_read_b128 v[202:205], v196 offset:4608
	ds_read_b128 v[178:181], v196 offset:32
	ds_read_b128 v[222:225], v197 offset:41504
	ds_read_b128 v[206:209], v196 offset:4640
	ds_read_b128 v[214:217], v197 offset:36896
	s_waitcnt lgkmcnt(6)
	v_mfma_f32_32x32x16_bf16 v[52:67], v[174:177], v[210:213], v[52:67]
	global_load_dwordx4 v[68:71], v[164:165], off offset:1536
	s_waitcnt lgkmcnt(5)
	v_mfma_f32_32x32x16_bf16 v[36:51], v[174:177], v[218:221], v[36:51]
	global_load_dwordx4 v[72:75], v[162:163], off offset:1536
	s_waitcnt lgkmcnt(4)
	v_mfma_f32_32x32x16_bf16 v[4:19], v[202:205], v[218:221], v[4:19]
	global_load_dwordx4 v[76:79], v[160:161], off offset:1536
	s_waitcnt lgkmcnt(2)
	v_mfma_f32_32x32x16_bf16 v[36:51], v[178:181], v[222:225], v[36:51]
	global_load_dwordx4 v[80:83], v[158:159], off offset:1536
	s_waitcnt lgkmcnt(1)
	v_mfma_f32_32x32x16_bf16 v[4:19], v[206:209], v[222:225], v[4:19]
	global_load_dwordx4 v[84:87], v[156:157], off offset:1536
	ds_read_b128 v[222:225], v197 offset:41568
	ds_read_b128 v[174:177], v196 offset:4672
	v_mfma_f32_32x32x16_bf16 v[20:35], v[202:205], v[210:213], v[20:35]
	global_load_dwordx4 v[92:95], v[154:155], off offset:1536
	ds_read_b128 v[210:213], v196 offset:4704
	ds_read_b128 v[202:205], v196 offset:64
	s_waitcnt lgkmcnt(4)
	v_mfma_f32_32x32x16_bf16 v[52:67], v[178:181], v[214:217], v[52:67]
	global_load_dwordx4 v[104:107], v[152:153], off offset:1536
	ds_read_b128 v[218:221], v197 offset:36960
	ds_read_b128 v[178:181], v197 offset:41536
	v_mfma_f32_32x32x16_bf16 v[20:35], v[206:209], v[214:217], v[20:35]
	s_setprio 0
	global_load_dwordx4 v[112:115], v[146:147], off offset:1536
	ds_read_b128 v[214:217], v197 offset:36928
	ds_read_b128 v[206:209], v196 offset:96
	s_waitcnt lgkmcnt(1)
	v_mfma_f32_32x32x16_bf16 v[52:67], v[202:205], v[214:217], v[52:67]
	s_waitcnt vmcnt(23)
	ds_write_b128 v167, v[88:91]
	v_mfma_f32_32x32x16_bf16 v[36:51], v[202:205], v[178:181], v[36:51]
	s_waitcnt vmcnt(22)
	ds_write_b128 v167, v[96:99] offset:36864
	v_mfma_f32_32x32x16_bf16 v[20:35], v[174:177], v[214:217], v[20:35]
	s_waitcnt vmcnt(21)
	ds_write_b128 v190, v[100:103]
	v_mfma_f32_32x32x16_bf16 v[4:19], v[174:177], v[178:181], v[4:19]
	s_waitcnt vmcnt(20)
	ds_write_b128 v190, v[108:111] offset:36864
	s_waitcnt lgkmcnt(4)
	v_mfma_f32_32x32x16_bf16 v[52:67], v[206:209], v[218:221], v[52:67]
	s_waitcnt vmcnt(19)
	ds_write_b128 v191, v[116:119]
	v_mfma_f32_32x32x16_bf16 v[36:51], v[206:209], v[222:225], v[36:51]
	s_waitcnt vmcnt(18)
	ds_write_b128 v191, v[120:123] offset:36864
	v_mfma_f32_32x32x16_bf16 v[20:35], v[210:213], v[218:221], v[20:35]
	s_waitcnt vmcnt(17)
	ds_write_b128 v192, v[124:127]
	v_mfma_f32_32x32x16_bf16 v[4:19], v[210:213], v[222:225], v[4:19]
	s_waitcnt vmcnt(16)
	ds_write_b128 v192, v[128:131] offset:36864
	s_waitcnt lgkmcnt(0)
	s_barrier
	s_setprio 1
	ds_read_b128 v[174:177], v194
	ds_read_b128 v[210:213], v195 offset:36864
	ds_read_b128 v[218:221], v195 offset:41472
	ds_read_b128 v[202:205], v194 offset:4608
	ds_read_b128 v[178:181], v194 offset:32
	ds_read_b128 v[222:225], v195 offset:41504
	ds_read_b128 v[206:209], v194 offset:4640
	ds_read_b128 v[214:217], v195 offset:36896
	s_waitcnt lgkmcnt(6)
	v_mfma_f32_32x32x16_bf16 v[52:67], v[174:177], v[210:213], v[52:67]
	global_load_dwordx4 v[88:91], v[164:165], off offset:1664
	s_waitcnt lgkmcnt(5)
	v_mfma_f32_32x32x16_bf16 v[36:51], v[174:177], v[218:221], v[36:51]
	global_load_dwordx4 v[96:99], v[162:163], off offset:1664
	s_waitcnt lgkmcnt(4)
	v_mfma_f32_32x32x16_bf16 v[4:19], v[202:205], v[218:221], v[4:19]
	global_load_dwordx4 v[100:103], v[160:161], off offset:1664
	s_waitcnt lgkmcnt(2)
	v_mfma_f32_32x32x16_bf16 v[36:51], v[178:181], v[222:225], v[36:51]
	global_load_dwordx4 v[108:111], v[158:159], off offset:1664
	s_waitcnt lgkmcnt(1)
	v_mfma_f32_32x32x16_bf16 v[4:19], v[206:209], v[222:225], v[4:19]
	global_load_dwordx4 v[116:119], v[156:157], off offset:1664
	ds_read_b128 v[222:225], v195 offset:41568
	ds_read_b128 v[174:177], v194 offset:4672
	v_mfma_f32_32x32x16_bf16 v[20:35], v[202:205], v[210:213], v[20:35]
	global_load_dwordx4 v[120:123], v[154:155], off offset:1664
	ds_read_b128 v[210:213], v194 offset:4704
	ds_read_b128 v[202:205], v194 offset:64
	s_waitcnt lgkmcnt(4)
	v_mfma_f32_32x32x16_bf16 v[52:67], v[178:181], v[214:217], v[52:67]
	global_load_dwordx4 v[124:127], v[152:153], off offset:1664
	ds_read_b128 v[218:221], v195 offset:36960
	ds_read_b128 v[178:181], v195 offset:41536
	v_mfma_f32_32x32x16_bf16 v[20:35], v[206:209], v[214:217], v[20:35]
	s_setprio 0
	global_load_dwordx4 v[128:131], v[146:147], off offset:1664
	ds_read_b128 v[214:217], v195 offset:36928
	ds_read_b128 v[206:209], v194 offset:96
	s_waitcnt lgkmcnt(1)
	v_mfma_f32_32x32x16_bf16 v[52:67], v[202:205], v[214:217], v[52:67]
	s_waitcnt vmcnt(23)
	ds_write_b128 v167, v[132:135] offset:18432
	v_mfma_f32_32x32x16_bf16 v[36:51], v[202:205], v[178:181], v[36:51]
	s_waitcnt vmcnt(22)
	ds_write_b128 v167, v[136:139] offset:55296
	v_mfma_f32_32x32x16_bf16 v[20:35], v[174:177], v[214:217], v[20:35]
	s_waitcnt vmcnt(21)
	ds_write_b128 v190, v[140:143] offset:18432
	v_mfma_f32_32x32x16_bf16 v[4:19], v[174:177], v[178:181], v[4:19]
	s_waitcnt vmcnt(20)
	ds_write_b128 v190, v[198:201] offset:55296
	s_waitcnt lgkmcnt(4)
	v_mfma_f32_32x32x16_bf16 v[52:67], v[206:209], v[218:221], v[52:67]
	s_waitcnt vmcnt(19)
	ds_write_b128 v191, v[226:229] offset:18432
	v_mfma_f32_32x32x16_bf16 v[36:51], v[206:209], v[222:225], v[36:51]
	s_waitcnt vmcnt(18)
	ds_write_b128 v191, v[230:233] offset:55296
	v_mfma_f32_32x32x16_bf16 v[20:35], v[210:213], v[218:221], v[20:35]
	s_waitcnt vmcnt(17)
	ds_write_b128 v192, v[242:245] offset:18432
	v_mfma_f32_32x32x16_bf16 v[4:19], v[210:213], v[222:225], v[4:19]
	s_waitcnt vmcnt(16)
	ds_write_b128 v192, v[246:249] offset:55296
	s_waitcnt lgkmcnt(0)
	s_barrier
; #define MFMA(a, b, c) __builtin_amdgcn_mfma_f32_32x32x16_bf16((a), (b), (c), 0, 0, 0)
; template <class Epi, class ColV>
; DI void gemm_tile(const bf16_t* __restrict__ A, int lda, const bf16_t* __restrict__ Bt, int ldb, int K, int m0, int n0, unsigned char* smem, Epi epi, ColV colv, const bf16_t* __restrict__ HYT = nullptr) {
;     ...
;     auto gload = [&](u32x4 (&r)[8], int kt) {
; #pragma unroll
;         for (int i = 0; i < 4; ++i) { int id = tid + 256 * i, row = id >> 3, kc = id & 7;
;             if (HYT && kt >= 12) r[i] = *(const u32x4*)(HYT + (size_t)((kt - 12) * 64 + (id >> 4)) * NT + m0 + (id & 15) * 8);
;             else r[i] = *(const u32x4*)(A + (size_t)(m0 + row) * lda + kt * 64 + kc * 8);
;             r[4 + i] = *(const u32x4*)(Bt + (size_t)(n0 + row) * ldb + kt * 64 + kc * 8); }
;     };
;     auto sstore = [&](const u32x4 (&r)[8], int buf, int kt) {
; #pragma unroll
;         for (int i = 0; i < 4; ++i) { int id = tid + 256 * i, row = id >> 3, kc = id & 7;
;             if (HYT && kt >= 12) { const int kk = id >> 4, rr = (id & 15) * 8; bf16_t* d = As + (buf * 128 + rr) * LS + kk; const bf16x8 v = __builtin_bit_cast(bf16x8, r[i]);
; #pragma unroll
;                 for (int e = 0; e < 8; ++e) d[e * LS] = (bf16_t)v[e]; }
;             else *(u32x4*)(As + (buf * 128 + row) * LS + kc * 8) = r[i];
;             *(u32x4*)(Bs + (buf * 128 + row) * LS + kc * 8) = r[4 + i]; }
;     };
;     auto step = [&](int kt, u32x4 (&ldset)[8], const u32x4 (&stset)[8]) {
;         const int buf = kt & 1;
;         if (kt + 2 < nk) gload(ldset, kt + 2);
;         const bf16_t* Ab = As + (buf * 128 + 64 * wr + li) * LS + 8 * lh;
;         const bf16_t* Bb = Bs + (buf * 128 + 64 * wc + li) * LS + 8 * lh;
;         bf16x8 fa[2][2], fb[2][2], ga[2][2], gb[2][2];
; #pragma unroll
;         for (int k2 = 0; k2 < 2; ++k2) { fa[k2][0] = ld8(Ab + 16 * k2); fa[k2][1] = ld8(Ab + 32 * LS + 16 * k2); fb[k2][0] = ld8(Bb + 16 * k2); fb[k2][1] = ld8(Bb + 32 * LS + 16 * k2); }
;         __builtin_amdgcn_sched_barrier(0);
; #pragma unroll
;         for (int k2 = 0; k2 < 2; ++k2) {
;             acc[0][0] = MFMA(fa[k2][0], fb[k2][0], acc[0][0]); acc[0][1] = MFMA(fa[k2][0], fb[k2][1], acc[0][1]);
;             acc[1][0] = MFMA(fa[k2][1], fb[k2][0], acc[1][0]); acc[1][1] = MFMA(fa[k2][1], fb[k2][1], acc[1][1]);
;         }
; #pragma unroll
	s_setprio 1
	ds_read_b128 v[174:177], v196
	ds_read_b128 v[210:213], v197 offset:36864
	ds_read_b128 v[218:221], v197 offset:41472
	ds_read_b128 v[202:205], v196 offset:4608
	ds_read_b128 v[178:181], v196 offset:32
	ds_read_b128 v[222:225], v197 offset:41504
	ds_read_b128 v[206:209], v196 offset:4640
	ds_read_b128 v[214:217], v197 offset:36896
	s_waitcnt lgkmcnt(6)
	v_mfma_f32_32x32x16_bf16 v[52:67], v[174:177], v[210:213], v[52:67]
	global_load_dwordx4 v[132:135], v[164:165], off offset:1792
	s_waitcnt lgkmcnt(5)
	v_mfma_f32_32x32x16_bf16 v[36:51], v[174:177], v[218:221], v[36:51]
	global_load_dwordx4 v[136:139], v[162:163], off offset:1792
	s_waitcnt lgkmcnt(4)
	v_mfma_f32_32x32x16_bf16 v[4:19], v[202:205], v[218:221], v[4:19]
	global_load_dwordx4 v[140:143], v[160:161], off offset:1792
	s_waitcnt lgkmcnt(2)
	v_mfma_f32_32x32x16_bf16 v[36:51], v[178:181], v[222:225], v[36:51]
	global_load_dwordx4 v[198:201], v[158:159], off offset:1792
	s_waitcnt lgkmcnt(1)
	v_mfma_f32_32x32x16_bf16 v[4:19], v[206:209], v[222:225], v[4:19]
	global_load_dwordx4 v[226:229], v[156:157], off offset:1792
	ds_read_b128 v[222:225], v197 offset:41568
	ds_read_b128 v[174:177], v196 offset:4672
	v_mfma_f32_32x32x16_bf16 v[20:35], v[202:205], v[210:213], v[20:35]
	global_load_dwordx4 v[230:233], v[154:155], off offset:1792
	ds_read_b128 v[210:213], v196 offset:4704
	ds_read_b128 v[202:205], v196 offset:64
	s_waitcnt lgkmcnt(4)
	v_mfma_f32_32x32x16_bf16 v[52:67], v[178:181], v[214:217], v[52:67]
	global_load_dwordx4 v[242:245], v[152:153], off offset:1792
	ds_read_b128 v[218:221], v197 offset:36960
	ds_read_b128 v[178:181], v197 offset:41536
	v_mfma_f32_32x32x16_bf16 v[20:35], v[206:209], v[214:217], v[20:35]
	s_setprio 0
	global_load_dwordx4 v[246:249], v[146:147], off offset:1792
	ds_read_b128 v[214:217], v197 offset:36928
	ds_read_b128 v[206:209], v196 offset:96
	s_waitcnt lgkmcnt(1)
	v_mfma_f32_32x32x16_bf16 v[52:67], v[202:205], v[214:217], v[52:67]
	s_waitcnt vmcnt(23)
	ds_write_b128 v167, v[68:71]
	v_mfma_f32_32x32x16_bf16 v[36:51], v[202:205], v[178:181], v[36:51]
	s_waitcnt vmcnt(22)
	ds_write_b128 v167, v[72:75] offset:36864
	v_mfma_f32_32x32x16_bf16 v[20:35], v[174:177], v[214:217], v[20:35]
	s_waitcnt vmcnt(21)
	ds_write_b128 v190, v[76:79]
	v_mfma_f32_32x32x16_bf16 v[4:19], v[174:177], v[178:181], v[4:19]
	s_waitcnt vmcnt(20)
	ds_write_b128 v190, v[80:83] offset:36864
	s_waitcnt lgkmcnt(4)
	v_mfma_f32_32x32x16_bf16 v[52:67], v[206:209], v[218:221], v[52:67]
	s_waitcnt vmcnt(19)
	ds_write_b128 v191, v[84:87]
	v_mfma_f32_32x32x16_bf16 v[36:51], v[206:209], v[222:225], v[36:51]
	s_waitcnt vmcnt(18)
	ds_write_b128 v191, v[92:95] offset:36864
	v_mfma_f32_32x32x16_bf16 v[20:35], v[210:213], v[218:221], v[20:35]
	s_waitcnt vmcnt(17)
	ds_write_b128 v192, v[104:107]
	v_mfma_f32_32x32x16_bf16 v[4:19], v[210:213], v[222:225], v[4:19]
	s_waitcnt vmcnt(16)
	ds_write_b128 v192, v[112:115] offset:36864
	s_waitcnt lgkmcnt(0)
	s_barrier
	s_setprio 1
	ds_read_b128 v[174:177], v194
	ds_read_b128 v[210:213], v195 offset:36864
	ds_read_b128 v[218:221], v195 offset:41472
	ds_read_b128 v[202:205], v194 offset:4608
	ds_read_b128 v[178:181], v194 offset:32
	ds_read_b128 v[222:225], v195 offset:41504
	ds_read_b128 v[206:209], v194 offset:4640
	ds_read_b128 v[214:217], v195 offset:36896
	s_waitcnt lgkmcnt(6)
	v_mfma_f32_32x32x16_bf16 v[52:67], v[174:177], v[210:213], v[52:67]
	global_load_dwordx4 v[68:71], v[164:165], off offset:1920
	s_waitcnt lgkmcnt(5)
	v_mfma_f32_32x32x16_bf16 v[36:51], v[174:177], v[218:221], v[36:51]
	global_load_dwordx4 v[72:75], v[162:163], off offset:1920
	s_waitcnt lgkmcnt(4)
	v_mfma_f32_32x32x16_bf16 v[4:19], v[202:205], v[218:221], v[4:19]
	global_load_dwordx4 v[76:79], v[160:161], off offset:1920
	s_waitcnt lgkmcnt(2)
	v_mfma_f32_32x32x16_bf16 v[36:51], v[178:181], v[222:225], v[36:51]
	global_load_dwordx4 v[80:83], v[158:159], off offset:1920
	s_waitcnt lgkmcnt(1)
	v_mfma_f32_32x32x16_bf16 v[4:19], v[206:209], v[222:225], v[4:19]
	global_load_dwordx4 v[84:87], v[156:157], off offset:1920
	ds_read_b128 v[222:225], v195 offset:41568
	ds_read_b128 v[174:177], v194 offset:4672
	v_mfma_f32_32x32x16_bf16 v[20:35], v[202:205], v[210:213], v[20:35]
	global_load_dwordx4 v[92:95], v[154:155], off offset:1920
	ds_read_b128 v[210:213], v194 offset:4704
	ds_read_b128 v[202:205], v194 offset:64
	s_waitcnt lgkmcnt(4)
	v_mfma_f32_32x32x16_bf16 v[52:67], v[178:181], v[214:217], v[52:67]
	global_load_dwordx4 v[104:107], v[152:153], off offset:1920
	ds_read_b128 v[218:221], v195 offset:36960
	ds_read_b128 v[178:181], v195 offset:41536
	v_mfma_f32_32x32x16_bf16 v[20:35], v[206:209], v[214:217], v[20:35]
	s_setprio 0
	global_load_dwordx4 v[112:115], v[146:147], off offset:1920
	ds_read_b128 v[214:217], v195 offset:36928
	ds_read_b128 v[206:209], v194 offset:96
	s_waitcnt lgkmcnt(1)
	v_mfma_f32_32x32x16_bf16 v[52:67], v[202:205], v[214:217], v[52:67]
	s_waitcnt vmcnt(23)
	ds_write_b128 v167, v[88:91] offset:18432
	v_mfma_f32_32x32x16_bf16 v[36:51], v[202:205], v[178:181], v[36:51]
	s_waitcnt vmcnt(22)
	ds_write_b128 v167, v[96:99] offset:55296
	v_mfma_f32_32x32x16_bf16 v[20:35], v[174:177], v[214:217], v[20:35]
	s_waitcnt vmcnt(21)
	ds_write_b128 v190, v[100:103] offset:18432
	v_mfma_f32_32x32x16_bf16 v[4:19], v[174:177], v[178:181], v[4:19]
	s_waitcnt vmcnt(20)
	ds_write_b128 v190, v[108:111] offset:55296
	s_waitcnt lgkmcnt(4)
	v_mfma_f32_32x32x16_bf16 v[52:67], v[206:209], v[218:221], v[52:67]
	s_waitcnt vmcnt(19)
	ds_write_b128 v191, v[116:119] offset:18432
	v_mfma_f32_32x32x16_bf16 v[36:51], v[206:209], v[222:225], v[36:51]
	s_waitcnt vmcnt(18)
	ds_write_b128 v191, v[120:123] offset:55296
	v_mfma_f32_32x32x16_bf16 v[20:35], v[210:213], v[218:221], v[20:35]
	s_waitcnt vmcnt(17)
	ds_write_b128 v192, v[124:127] offset:18432
	v_mfma_f32_32x32x16_bf16 v[4:19], v[210:213], v[222:225], v[4:19]
	s_waitcnt vmcnt(16)
	ds_write_b128 v192, v[128:131] offset:55296
	s_waitcnt lgkmcnt(0)
	s_barrier
; #define MFMA(a, b, c) __builtin_amdgcn_mfma_f32_32x32x16_bf16((a), (b), (c), 0, 0, 0)
; template <class Epi, class ColV>
; DI void gemm_tile(const bf16_t* __restrict__ A, int lda, const bf16_t* __restrict__ Bt, int ldb, int K, int m0, int n0, unsigned char* smem, Epi epi, ColV colv, const bf16_t* __restrict__ HYT = nullptr) {
;     ...
;     auto step = [&](int kt, u32x4 (&ldset)[8], const u32x4 (&stset)[8]) {
;         const int buf = kt & 1;
;         if (kt + 2 < nk) gload(ldset, kt + 2);
;         const bf16_t* Ab = As + (buf * 128 + 64 * wr + li) * LS + 8 * lh;
;         const bf16_t* Bb = Bs + (buf * 128 + 64 * wc + li) * LS + 8 * lh;
;         bf16x8 fa[2][2], fb[2][2], ga[2][2], gb[2][2];
; #pragma unroll
;         for (int k2 = 0; k2 < 2; ++k2) { fa[k2][0] = ld8(Ab + 16 * k2); fa[k2][1] = ld8(Ab + 32 * LS + 16 * k2); fb[k2][0] = ld8(Bb + 16 * k2); fb[k2][1] = ld8(Bb + 32 * LS + 16 * k2); }
;         __builtin_amdgcn_sched_barrier(0);
; #pragma unroll
;         for (int k2 = 0; k2 < 2; ++k2) {
;             acc[0][0] = MFMA(fa[k2][0], fb[k2][0], acc[0][0]); acc[0][1] = MFMA(fa[k2][0], fb[k2][1], acc[0][1]);
;             acc[1][0] = MFMA(fa[k2][1], fb[k2][0], acc[1][0]); acc[1][1] = MFMA(fa[k2][1], fb[k2][1], acc[1][1]);
;         }
; #pragma unroll
;         for (int k2 = 0; k2 < 2; ++k2) { const int ks = 2 + k2; ga[k2][0] = ld8(Ab + 16 * ks); ga[k2][1] = ld8(Ab + 32 * LS + 16 * ks); gb[k2][0] = ld8(Bb + 16 * ks); gb[k2][1] = ld8(Bb + 32 * LS + 16 * ks); }
; #pragma unroll
;         for (int k2 = 0; k2 < 2; ++k2) {
;             acc[0][0] = MFMA(ga[k2][0], gb[k2][0], acc[0][0]); acc[0][1] = MFMA(ga[k2][0], gb[k2][1], acc[0][1]);
;             acc[1][0] = MFMA(ga[k2][1], gb[k2][0], acc[1][0]); acc[1][1] = MFMA(ga[k2][1], gb[k2][1], acc[1][1]);
;         }
;         if (kt + 1 < nk) sstore(stset, buf ^ 1, kt + 1);
; #pragma unroll
;         for (int i = 0; i < 8; ++i) { __builtin_amdgcn_sched_group_barrier(0x008, 1, 0); __builtin_amdgcn_sched_group_barrier(0x100, 1, 0); }
; #pragma unroll
;         for (int i = 0; i < 8; ++i) { __builtin_amdgcn_sched_group_barrier(0x008, 1, 0); __builtin_amdgcn_sched_group_barrier(0x200, 1, 0); }
;         __builtin_amdgcn_sched_barrier(0);
;         __syncthreads();
;     };
	s_setprio 1
	ds_read_b128 v[174:177], v196
	ds_read_b128 v[210:213], v197 offset:36864
	ds_read_b128 v[218:221], v197 offset:41472
	ds_read_b128 v[202:205], v196 offset:4608
	ds_read_b128 v[178:181], v196 offset:32
	ds_read_b128 v[222:225], v197 offset:41504
	ds_read_b128 v[206:209], v196 offset:4640
	ds_read_b128 v[214:217], v197 offset:36896
	s_waitcnt lgkmcnt(6)
	v_mfma_f32_32x32x16_bf16 v[52:67], v[174:177], v[210:213], v[52:67]
	s_waitcnt lgkmcnt(5)
	v_mfma_f32_32x32x16_bf16 v[36:51], v[174:177], v[218:221], v[36:51]
	s_waitcnt lgkmcnt(4)
	v_mfma_f32_32x32x16_bf16 v[4:19], v[202:205], v[218:221], v[4:19]
	s_waitcnt lgkmcnt(2)
	v_mfma_f32_32x32x16_bf16 v[36:51], v[178:181], v[222:225], v[36:51]
	s_waitcnt lgkmcnt(1)
	v_mfma_f32_32x32x16_bf16 v[4:19], v[206:209], v[222:225], v[4:19]
	ds_read_b128 v[222:225], v197 offset:41568
	ds_read_b128 v[174:177], v196 offset:4672
	v_mfma_f32_32x32x16_bf16 v[20:35], v[202:205], v[210:213], v[20:35]
	ds_read_b128 v[210:213], v196 offset:4704
	ds_read_b128 v[202:205], v196 offset:64
	s_waitcnt lgkmcnt(4)
	v_mfma_f32_32x32x16_bf16 v[52:67], v[178:181], v[214:217], v[52:67]
	ds_read_b128 v[218:221], v197 offset:36960
	ds_read_b128 v[178:181], v197 offset:41536
	v_mfma_f32_32x32x16_bf16 v[20:35], v[206:209], v[214:217], v[20:35]
	s_setprio 0
	ds_read_b128 v[214:217], v197 offset:36928
	ds_read_b128 v[206:209], v196 offset:96
	s_waitcnt lgkmcnt(1)
	v_mfma_f32_32x32x16_bf16 v[52:67], v[202:205], v[214:217], v[52:67]
	s_waitcnt vmcnt(15)
	ds_write_b128 v167, v[132:135]
	v_mfma_f32_32x32x16_bf16 v[36:51], v[202:205], v[178:181], v[36:51]
	s_waitcnt vmcnt(14)
	ds_write_b128 v167, v[136:139] offset:36864
	v_mfma_f32_32x32x16_bf16 v[20:35], v[174:177], v[214:217], v[20:35]
	s_waitcnt vmcnt(13)
	ds_write_b128 v190, v[140:143]
	v_mfma_f32_32x32x16_bf16 v[4:19], v[174:177], v[178:181], v[4:19]
	s_waitcnt vmcnt(12)
	ds_write_b128 v190, v[198:201] offset:36864
	s_waitcnt lgkmcnt(4)
	v_mfma_f32_32x32x16_bf16 v[52:67], v[206:209], v[218:221], v[52:67]
	s_waitcnt vmcnt(11)
	ds_write_b128 v191, v[226:229]
	v_mfma_f32_32x32x16_bf16 v[36:51], v[206:209], v[222:225], v[36:51]
	s_waitcnt vmcnt(10)
	ds_write_b128 v191, v[230:233] offset:36864
	v_mfma_f32_32x32x16_bf16 v[20:35], v[210:213], v[218:221], v[20:35]
	s_waitcnt vmcnt(9)
	ds_write_b128 v192, v[242:245]
	v_mfma_f32_32x32x16_bf16 v[4:19], v[210:213], v[222:225], v[4:19]
	s_waitcnt vmcnt(8)
	ds_write_b128 v192, v[246:249] offset:36864
	s_waitcnt lgkmcnt(0)
	s_barrier
; template <class Epi, class ColV>
; DI void gemm_tile(const bf16_t* __restrict__ A, int lda, const bf16_t* __restrict__ Bt, int ldb, int K, int m0, int n0, unsigned char* smem, Epi epi, ColV colv, const bf16_t* __restrict__ HYT = nullptr) {
;     ...
;     auto step = [&](int kt, u32x4 (&ldset)[8], const u32x4 (&stset)[8]) {
;         const int buf = kt & 1;
;         if (kt + 2 < nk) gload(ldset, kt + 2);
;         const bf16_t* Ab = As + (buf * 128 + 64 * wr + li) * LS + 8 * lh;
;         const bf16_t* Bb = Bs + (buf * 128 + 64 * wc + li) * LS + 8 * lh;
;         bf16x8 fa[2][2], fb[2][2], ga[2][2], gb[2][2];
; #pragma unroll
;         for (int k2 = 0; k2 < 2; ++k2) { fa[k2][0] = ld8(Ab + 16 * k2); fa[k2][1] = ld8(Ab + 32 * LS + 16 * k2); fb[k2][0] = ld8(Bb + 16 * k2); fb[k2][1] = ld8(Bb + 32 * LS + 16 * k2); }
;         __builtin_amdgcn_sched_barrier(0);
; #pragma unroll
;         for (int k2 = 0; k2 < 2; ++k2) {
;             acc[0][0] = MFMA(fa[k2][0], fb[k2][0], acc[0][0]); acc[0][1] = MFMA(fa[k2][0], fb[k2][1], acc[0][1]);
;             acc[1][0] = MFMA(fa[k2][1], fb[k2][0], acc[1][0]); acc[1][1] = MFMA(fa[k2][1], fb[k2][1], acc[1][1]);
;         }
; #pragma unroll
;         for (int k2 = 0; k2 < 2; ++k2) { const int ks = 2 + k2; ga[k2][0] = ld8(Ab + 16 * ks); ga[k2][1] = ld8(Ab + 32 * LS + 16 * ks); gb[k2][0] = ld8(Bb + 16 * ks); gb[k2][1] = ld8(Bb + 32 * LS + 16 * ks); }
; #pragma unroll
;         for (int k2 = 0; k2 < 2; ++k2) {
;             acc[0][0] = MFMA(ga[k2][0], gb[k2][0], acc[0][0]); acc[0][1] = MFMA(ga[k2][0], gb[k2][1], acc[0][1]);
;             acc[1][0] = MFMA(ga[k2][1], gb[k2][0], acc[1][0]); acc[1][1] = MFMA(ga[k2][1], gb[k2][1], acc[1][1]);
;         }
;         if (kt + 1 < nk) sstore(stset, buf ^ 1, kt + 1);
; #pragma unroll
;         for (int i = 0; i < 8; ++i) { __builtin_amdgcn_sched_group_barrier(0x008, 1, 0); __builtin_amdgcn_sched_group_barrier(0x100, 1, 0); }
; #pragma unroll
;         for (int i = 0; i < 8; ++i) { __builtin_amdgcn_sched_group_barrier(0x008, 1, 0); __builtin_amdgcn_sched_group_barrier(0x200, 1, 0); }
;         __builtin_amdgcn_sched_barrier(0);
;         __syncthreads();
;     };
;     gload(R0, 0); gload(R1, 1);
;     sstore(R0, 0, 0); __syncthreads();
;     for (int kt = 0; kt < nk; kt += 2) {
;         step(kt, R0, R1);
;         if (kt + 1 < nk) step(kt + 1, R1, R0);
;     }
	s_setprio 1
	ds_read_b128 v[174:177], v194
	ds_read_b128 v[210:213], v195 offset:36864
	ds_read_b128 v[218:221], v195 offset:41472
	ds_read_b128 v[202:205], v194 offset:4608
	ds_read_b128 v[178:181], v194 offset:32
	ds_read_b128 v[222:225], v195 offset:41504
	ds_read_b128 v[206:209], v194 offset:4640
	ds_read_b128 v[214:217], v195 offset:36896
	s_waitcnt lgkmcnt(6)
	v_mfma_f32_32x32x16_bf16 v[52:67], v[174:177], v[210:213], v[52:67]
	s_waitcnt lgkmcnt(5)
	v_mfma_f32_32x32x16_bf16 v[36:51], v[174:177], v[218:221], v[36:51]
	s_waitcnt lgkmcnt(4)
	v_mfma_f32_32x32x16_bf16 v[4:19], v[202:205], v[218:221], v[4:19]
	s_waitcnt lgkmcnt(2)
	v_mfma_f32_32x32x16_bf16 v[36:51], v[178:181], v[222:225], v[36:51]
	s_waitcnt lgkmcnt(1)
	v_mfma_f32_32x32x16_bf16 v[4:19], v[206:209], v[222:225], v[4:19]
	ds_read_b128 v[222:225], v195 offset:41568
	ds_read_b128 v[174:177], v194 offset:4672
	v_mfma_f32_32x32x16_bf16 v[20:35], v[202:205], v[210:213], v[20:35]
	ds_read_b128 v[210:213], v194 offset:4704
	ds_read_b128 v[202:205], v194 offset:64
	s_waitcnt lgkmcnt(4)
	v_mfma_f32_32x32x16_bf16 v[52:67], v[178:181], v[214:217], v[52:67]
	ds_read_b128 v[218:221], v195 offset:36960
	ds_read_b128 v[178:181], v195 offset:41536
	v_mfma_f32_32x32x16_bf16 v[20:35], v[206:209], v[214:217], v[20:35]
	s_setprio 0
	ds_read_b128 v[214:217], v195 offset:36928
	ds_read_b128 v[206:209], v194 offset:96
	s_waitcnt lgkmcnt(1)
	v_mfma_f32_32x32x16_bf16 v[52:67], v[202:205], v[214:217], v[52:67]
	s_waitcnt vmcnt(7)
	ds_write_b128 v167, v[68:71] offset:18432
	v_mfma_f32_32x32x16_bf16 v[36:51], v[202:205], v[178:181], v[36:51]
	s_waitcnt vmcnt(6)
	ds_write_b128 v167, v[72:75] offset:55296
	v_mfma_f32_32x32x16_bf16 v[20:35], v[174:177], v[214:217], v[20:35]
	s_waitcnt vmcnt(5)
	ds_write_b128 v190, v[76:79] offset:18432
	v_mfma_f32_32x32x16_bf16 v[4:19], v[174:177], v[178:181], v[4:19]
	s_waitcnt vmcnt(4)
	ds_write_b128 v190, v[80:83] offset:55296
	s_waitcnt lgkmcnt(4)
	v_mfma_f32_32x32x16_bf16 v[52:67], v[206:209], v[218:221], v[52:67]
	s_waitcnt vmcnt(3)
	ds_write_b128 v191, v[84:87] offset:18432
	v_mfma_f32_32x32x16_bf16 v[36:51], v[206:209], v[222:225], v[36:51]
	s_waitcnt vmcnt(2)
	ds_write_b128 v191, v[92:95] offset:55296
	v_mfma_f32_32x32x16_bf16 v[20:35], v[210:213], v[218:221], v[20:35]
	s_waitcnt vmcnt(1)
	ds_write_b128 v192, v[104:107] offset:18432
	v_mfma_f32_32x32x16_bf16 v[4:19], v[210:213], v[222:225], v[4:19]
	s_waitcnt vmcnt(0)
	ds_write_b128 v192, v[112:115] offset:55296
	s_waitcnt lgkmcnt(0)
	s_barrier
	s_setprio 1
	ds_read_b128 v[174:177], v196
	ds_read_b128 v[210:213], v197 offset:36864
	ds_read_b128 v[218:221], v197 offset:41472
	ds_read_b128 v[202:205], v196 offset:4608
	ds_read_b128 v[178:181], v196 offset:32
	ds_read_b128 v[222:225], v197 offset:41504
	ds_read_b128 v[206:209], v196 offset:4640
	ds_read_b128 v[214:217], v197 offset:36896
	s_waitcnt lgkmcnt(6)
	v_mfma_f32_32x32x16_bf16 v[52:67], v[174:177], v[210:213], v[52:67]
	s_waitcnt lgkmcnt(5)
	v_mfma_f32_32x32x16_bf16 v[36:51], v[174:177], v[218:221], v[36:51]
	s_waitcnt lgkmcnt(4)
	v_mfma_f32_32x32x16_bf16 v[4:19], v[202:205], v[218:221], v[4:19]
	s_waitcnt lgkmcnt(2)
	v_mfma_f32_32x32x16_bf16 v[36:51], v[178:181], v[222:225], v[36:51]
	s_waitcnt lgkmcnt(1)
	v_mfma_f32_32x32x16_bf16 v[4:19], v[206:209], v[222:225], v[4:19]
	ds_read_b128 v[222:225], v197 offset:41568
	ds_read_b128 v[174:177], v196 offset:4672
	v_mfma_f32_32x32x16_bf16 v[20:35], v[202:205], v[210:213], v[20:35]
	ds_read_b128 v[210:213], v196 offset:4704
	ds_read_b128 v[202:205], v196 offset:64
	s_waitcnt lgkmcnt(4)
	v_mfma_f32_32x32x16_bf16 v[52:67], v[178:181], v[214:217], v[52:67]
	ds_read_b128 v[218:221], v197 offset:36960
	ds_read_b128 v[178:181], v197 offset:41536
	v_mfma_f32_32x32x16_bf16 v[20:35], v[206:209], v[214:217], v[20:35]
	s_setprio 0
	ds_read_b128 v[214:217], v197 offset:36928
	ds_read_b128 v[206:209], v196 offset:96
	s_waitcnt lgkmcnt(1)
	v_mfma_f32_32x32x16_bf16 v[52:67], v[202:205], v[214:217], v[52:67]
	v_mfma_f32_32x32x16_bf16 v[36:51], v[202:205], v[178:181], v[36:51]
	v_mfma_f32_32x32x16_bf16 v[20:35], v[174:177], v[214:217], v[20:35]
	v_mfma_f32_32x32x16_bf16 v[4:19], v[174:177], v[178:181], v[4:19]
	s_waitcnt lgkmcnt(0)
	v_mfma_f32_32x32x16_bf16 v[52:67], v[206:209], v[218:221], v[52:67]
	v_mfma_f32_32x32x16_bf16 v[36:51], v[206:209], v[222:225], v[36:51]
	v_mfma_f32_32x32x16_bf16 v[20:35], v[210:213], v[218:221], v[20:35]
	v_mfma_f32_32x32x16_bf16 v[4:19], v[210:213], v[222:225], v[4:19]
	s_waitcnt lgkmcnt(0)
	s_barrier
	s_setprio 1
	s_nop 7
	s_nop 3
	s_branch .LBB0_53

; template <class Epi, class ColV>
; DI void gemm_tile(const bf16_t* __restrict__ A, int lda, const bf16_t* __restrict__ Bt, int ldb, int K, int m0, int n0, unsigned char* smem, Epi epi, ColV colv, const bf16_t* __restrict__ HYT = nullptr) {
;     ...
;     auto step = [&](int kt, u32x4 (&ldset)[8], const u32x4 (&stset)[8]) {
;         const int buf = kt & 1;
;         if (kt + 2 < nk) gload(ldset, kt + 2);
;         const bf16_t* Ab = As + (buf * 128 + 64 * wr + li) * LS + 8 * lh;
;         const bf16_t* Bb = Bs + (buf * 128 + 64 * wc + li) * LS + 8 * lh;
;         bf16x8 fa[2][2], fb[2][2], ga[2][2], gb[2][2];
; #pragma unroll
;         for (int k2 = 0; k2 < 2; ++k2) { fa[k2][0] = ld8(Ab + 16 * k2); fa[k2][1] = ld8(Ab + 32 * LS + 16 * k2); fb[k2][0] = ld8(Bb + 16 * k2); fb[k2][1] = ld8(Bb + 32 * LS + 16 * k2); }
;         __builtin_amdgcn_sched_barrier(0);
; #pragma unroll
;         for (int k2 = 0; k2 < 2; ++k2) {
;             acc[0][0] = MFMA(fa[k2][0], fb[k2][0], acc[0][0]); acc[0][1] = MFMA(fa[k2][0], fb[k2][1], acc[0][1]);
;             acc[1][0] = MFMA(fa[k2][1], fb[k2][0], acc[1][0]); acc[1][1] = MFMA(fa[k2][1], fb[k2][1], acc[1][1]);
;         }
; #pragma unroll
;         for (int k2 = 0; k2 < 2; ++k2) { const int ks = 2 + k2; ga[k2][0] = ld8(Ab + 16 * ks); ga[k2][1] = ld8(Ab + 32 * LS + 16 * ks); gb[k2][0] = ld8(Bb + 16 * ks); gb[k2][1] = ld8(Bb + 32 * LS + 16 * ks); }
; #pragma unroll
;         for (int k2 = 0; k2 < 2; ++k2) {
;             acc[0][0] = MFMA(ga[k2][0], gb[k2][0], acc[0][0]); acc[0][1] = MFMA(ga[k2][0], gb[k2][1], acc[0][1]);
;             acc[1][0] = MFMA(ga[k2][1], gb[k2][0], acc[1][0]); acc[1][1] = MFMA(ga[k2][1], gb[k2][1], acc[1][1]);
;         }
;         if (kt + 1 < nk) sstore(stset, buf ^ 1, kt + 1);
; #pragma unroll
;         for (int i = 0; i < 8; ++i) { __builtin_amdgcn_sched_group_barrier(0x008, 1, 0); __builtin_amdgcn_sched_group_barrier(0x100, 1, 0); }
; #pragma unroll
;         for (int i = 0; i < 8; ++i) { __builtin_amdgcn_sched_group_barrier(0x008, 1, 0); __builtin_amdgcn_sched_group_barrier(0x200, 1, 0); }
;         __builtin_amdgcn_sched_barrier(0);
;         __syncthreads();
;     };
;     ...
;         XCD_TILE_LOOP(NT / 128, INP / 128, tm, tn) gemm_tile((const bf16_t*)(p.ws + WS_H), 1024, (const bf16_t*)(p.ws + wbase(layer) + W_IN), 1024, 1024, tm * 128, tn * 128, smem, epi, nocol);
.LBB0_1558:
	s_cmp_lt_u32 s19, 14
	s_cselect_b64 s[12:13], -1, 0
	s_cmp_gt_u32 s19, 13
	s_cselect_b64 s[10:11], -1, 0
	s_and_b64 vcc, exec, s[10:11]
	v_lshl_add_u64 v[164:165], v[144:145], 0, v[2:3]
	v_lshl_add_u64 v[162:163], v[0:1], 0, v[2:3]
	v_lshl_add_u64 v[160:161], v[142:143], 0, v[2:3]
	v_lshl_add_u64 v[158:159], v[132:133], 0, v[2:3]
	v_lshl_add_u64 v[156:157], v[140:141], 0, v[2:3]
	v_lshl_add_u64 v[154:155], v[134:135], 0, v[2:3]
	v_lshl_add_u64 v[152:153], v[138:139], 0, v[2:3]
	v_lshl_add_u64 v[146:147], v[136:137], 0, v[2:3]
	s_mov_b32 s100, 0x26ca000
	s_mov_b32 s101, 0
	v_lshl_add_u64 v[164:165], v[164:165], 0, s[100:101]
	v_lshl_add_u64 v[160:161], v[160:161], 0, s[100:101]
	v_lshl_add_u64 v[156:157], v[156:157], 0, s[100:101]
	v_lshl_add_u64 v[152:153], v[152:153], 0, s[100:101]
	ds_read_b128 v[202:205], v194
	ds_read_b128 v[218:221], v195 offset:36864
	ds_read_b128 v[226:229], v195 offset:41472
	ds_read_b128 v[210:213], v194 offset:4608
	ds_read_b128 v[206:209], v194 offset:32
	ds_read_b128 v[230:233], v195 offset:41504
	ds_read_b128 v[214:217], v194 offset:4640
	ds_read_b128 v[222:225], v195 offset:36896
	s_waitcnt lgkmcnt(6)
	v_mfma_f32_32x32x16_bf16 v[52:67], v[202:205], v[218:221], v[52:67]
	global_load_dwordx4 v[132:135], v[164:165], off offset:256
	global_load_dwordx4 v[136:139], v[162:163], off offset:256
	s_waitcnt lgkmcnt(5)
	v_mfma_f32_32x32x16_bf16 v[36:51], v[202:205], v[226:229], v[36:51]
	global_load_dwordx4 v[140:143], v[160:161], off offset:256
	global_load_dwordx4 v[198:201], v[158:159], off offset:256
	s_waitcnt lgkmcnt(4)
	v_mfma_f32_32x32x16_bf16 v[4:19], v[210:213], v[226:229], v[4:19]
	global_load_dwordx4 v[174:177], v[156:157], off offset:256
	global_load_dwordx4 v[178:181], v[154:155], off offset:256
	s_waitcnt lgkmcnt(2)
	v_mfma_f32_32x32x16_bf16 v[36:51], v[206:209], v[230:233], v[36:51]
	global_load_dwordx4 v[242:245], v[152:153], off offset:256
	global_load_dwordx4 v[246:249], v[146:147], off offset:256
	s_waitcnt lgkmcnt(1)
	v_mfma_f32_32x32x16_bf16 v[4:19], v[214:217], v[230:233], v[4:19]
	global_load_dwordx4 v[68:71], v[164:165], off offset:384
	global_load_dwordx4 v[72:75], v[162:163], off offset:384
	ds_read_b128 v[230:233], v195 offset:41568
	ds_read_b128 v[202:205], v194 offset:4672
	v_mfma_f32_32x32x16_bf16 v[20:35], v[210:213], v[218:221], v[20:35]
	global_load_dwordx4 v[76:79], v[160:161], off offset:384
	global_load_dwordx4 v[80:83], v[158:159], off offset:384
	ds_read_b128 v[218:221], v194 offset:4704
	ds_read_b128 v[210:213], v194 offset:64
	s_waitcnt lgkmcnt(4)
	v_mfma_f32_32x32x16_bf16 v[52:67], v[206:209], v[222:225], v[52:67]
	global_load_dwordx4 v[84:87], v[156:157], off offset:384
	global_load_dwordx4 v[88:91], v[154:155], off offset:384
	ds_read_b128 v[226:229], v195 offset:36960
	ds_read_b128 v[206:209], v195 offset:41536
	v_mfma_f32_32x32x16_bf16 v[20:35], v[214:217], v[222:225], v[20:35]
	s_setprio 0
	global_load_dwordx4 v[92:95], v[152:153], off offset:384
	global_load_dwordx4 v[104:107], v[146:147], off offset:384
	ds_read_b128 v[222:225], v195 offset:36928
	ds_read_b128 v[214:217], v194 offset:96
	s_waitcnt lgkmcnt(1)
	v_mfma_f32_32x32x16_bf16 v[52:67], v[210:213], v[222:225], v[52:67]
	s_waitcnt vmcnt(16)
	ds_write_b128 v167, v[96:99] offset:18432
	v_mfma_f32_32x32x16_bf16 v[36:51], v[210:213], v[206:209], v[36:51]
	ds_write_b128 v167, v[100:103] offset:55296
	v_mfma_f32_32x32x16_bf16 v[20:35], v[202:205], v[222:225], v[20:35]
	ds_write_b128 v190, v[108:111] offset:18432
	v_mfma_f32_32x32x16_bf16 v[4:19], v[202:205], v[206:209], v[4:19]
	ds_write_b128 v190, v[112:115] offset:55296
	s_waitcnt lgkmcnt(4)
	v_mfma_f32_32x32x16_bf16 v[52:67], v[214:217], v[226:229], v[52:67]
	ds_write_b128 v191, v[116:119] offset:18432
	v_mfma_f32_32x32x16_bf16 v[36:51], v[214:217], v[230:233], v[36:51]
	ds_write_b128 v191, v[120:123] offset:55296
	v_mfma_f32_32x32x16_bf16 v[20:35], v[218:221], v[226:229], v[20:35]
	ds_write_b128 v192, v[124:127] offset:18432
	v_mfma_f32_32x32x16_bf16 v[4:19], v[218:221], v[230:233], v[4:19]
	ds_write_b128 v192, v[128:131] offset:55296
	s_waitcnt lgkmcnt(0)
	s_barrier
	s_setprio 1
	ds_read_b128 v[202:205], v196
	ds_read_b128 v[218:221], v197 offset:36864
	ds_read_b128 v[226:229], v197 offset:41472
	ds_read_b128 v[210:213], v196 offset:4608
	ds_read_b128 v[206:209], v196 offset:32
	ds_read_b128 v[230:233], v197 offset:41504
	ds_read_b128 v[214:217], v196 offset:4640
	ds_read_b128 v[222:225], v197 offset:36896
	s_waitcnt lgkmcnt(6)
	v_mfma_f32_32x32x16_bf16 v[52:67], v[202:205], v[218:221], v[52:67]
	global_load_dwordx4 v[96:99], v[164:165], off offset:512
	s_waitcnt lgkmcnt(5)
	v_mfma_f32_32x32x16_bf16 v[36:51], v[202:205], v[226:229], v[36:51]
	global_load_dwordx4 v[100:103], v[162:163], off offset:512
	s_waitcnt lgkmcnt(4)
	v_mfma_f32_32x32x16_bf16 v[4:19], v[210:213], v[226:229], v[4:19]
	global_load_dwordx4 v[108:111], v[160:161], off offset:512
	s_waitcnt lgkmcnt(2)
	v_mfma_f32_32x32x16_bf16 v[36:51], v[206:209], v[230:233], v[36:51]
	global_load_dwordx4 v[112:115], v[158:159], off offset:512
	s_waitcnt lgkmcnt(1)
	v_mfma_f32_32x32x16_bf16 v[4:19], v[214:217], v[230:233], v[4:19]
	global_load_dwordx4 v[116:119], v[156:157], off offset:512
	ds_read_b128 v[230:233], v197 offset:41568
	ds_read_b128 v[202:205], v196 offset:4672
	v_mfma_f32_32x32x16_bf16 v[20:35], v[210:213], v[218:221], v[20:35]
	global_load_dwordx4 v[120:123], v[154:155], off offset:512
	ds_read_b128 v[218:221], v196 offset:4704
	ds_read_b128 v[210:213], v196 offset:64
	s_waitcnt lgkmcnt(4)
; #define MFMA(a, b, c) __builtin_amdgcn_mfma_f32_32x32x16_bf16((a), (b), (c), 0, 0, 0)
; template <class Epi, class ColV>
; DI void gemm_tile(const bf16_t* __restrict__ A, int lda, const bf16_t* __restrict__ Bt, int ldb, int K, int m0, int n0, unsigned char* smem, Epi epi, ColV colv, const bf16_t* __restrict__ HYT = nullptr) {
;     ...
;     auto gload = [&](u32x4 (&r)[8], int kt) {
; #pragma unroll
;         for (int i = 0; i < 4; ++i) { int id = tid + 256 * i, row = id >> 3, kc = id & 7;
;             if (HYT && kt >= 12) r[i] = *(const u32x4*)(HYT + (size_t)((kt - 12) * 64 + (id >> 4)) * NT + m0 + (id & 15) * 8);
;             else r[i] = *(const u32x4*)(A + (size_t)(m0 + row) * lda + kt * 64 + kc * 8);
;             r[4 + i] = *(const u32x4*)(Bt + (size_t)(n0 + row) * ldb + kt * 64 + kc * 8); }
;     };
;     auto sstore = [&](const u32x4 (&r)[8], int buf, int kt) {
; #pragma unroll
;         for (int i = 0; i < 4; ++i) { int id = tid + 256 * i, row = id >> 3, kc = id & 7;
;             if (HYT && kt >= 12) { const int kk = id >> 4, rr = (id & 15) * 8; bf16_t* d = As + (buf * 128 + rr) * LS + kk; const bf16x8 v = __builtin_bit_cast(bf16x8, r[i]);
; #pragma unroll
;                 for (int e = 0; e < 8; ++e) d[e * LS] = (bf16_t)v[e]; }
;             else *(u32x4*)(As + (buf * 128 + row) * LS + kc * 8) = r[i];
;             *(u32x4*)(Bs + (buf * 128 + row) * LS + kc * 8) = r[4 + i]; }
;     };
;     auto step = [&](int kt, u32x4 (&ldset)[8], const u32x4 (&stset)[8]) {
;         const int buf = kt & 1;
;         if (kt + 2 < nk) gload(ldset, kt + 2);
;         const bf16_t* Ab = As + (buf * 128 + 64 * wr + li) * LS + 8 * lh;
;         const bf16_t* Bb = Bs + (buf * 128 + 64 * wc + li) * LS + 8 * lh;
;         bf16x8 fa[2][2], fb[2][2], ga[2][2], gb[2][2];
; #pragma unroll
;         for (int k2 = 0; k2 < 2; ++k2) { fa[k2][0] = ld8(Ab + 16 * k2); fa[k2][1] = ld8(Ab + 32 * LS + 16 * k2); fb[k2][0] = ld8(Bb + 16 * k2); fb[k2][1] = ld8(Bb + 32 * LS + 16 * k2); }
;         __builtin_amdgcn_sched_barrier(0);
; #pragma unroll
;         for (int k2 = 0; k2 < 2; ++k2) {
;             acc[0][0] = MFMA(fa[k2][0], fb[k2][0], acc[0][0]); acc[0][1] = MFMA(fa[k2][0], fb[k2][1], acc[0][1]);
;             acc[1][0] = MFMA(fa[k2][1], fb[k2][0], acc[1][0]); acc[1][1] = MFMA(fa[k2][1], fb[k2][1], acc[1][1]);
;         }
; #pragma unroll
	v_mfma_f32_32x32x16_bf16 v[52:67], v[206:209], v[222:225], v[52:67]
	global_load_dwordx4 v[124:127], v[152:153], off offset:512
	ds_read_b128 v[226:229], v197 offset:36960
	ds_read_b128 v[206:209], v197 offset:41536
	v_mfma_f32_32x32x16_bf16 v[20:35], v[214:217], v[222:225], v[20:35]
	s_setprio 0
	global_load_dwordx4 v[128:131], v[146:147], off offset:512
	ds_read_b128 v[222:225], v197 offset:36928
	ds_read_b128 v[214:217], v196 offset:96
	s_waitcnt lgkmcnt(1)
	v_mfma_f32_32x32x16_bf16 v[52:67], v[210:213], v[222:225], v[52:67]
	s_waitcnt vmcnt(23)
	ds_write_b128 v167, v[132:135]
	v_mfma_f32_32x32x16_bf16 v[36:51], v[210:213], v[206:209], v[36:51]
	s_waitcnt vmcnt(22)
	ds_write_b128 v167, v[136:139] offset:36864
	v_mfma_f32_32x32x16_bf16 v[20:35], v[202:205], v[222:225], v[20:35]
	s_waitcnt vmcnt(21)
	ds_write_b128 v190, v[140:143]
	v_mfma_f32_32x32x16_bf16 v[4:19], v[202:205], v[206:209], v[4:19]
	s_waitcnt vmcnt(20)
	ds_write_b128 v190, v[198:201] offset:36864
	s_waitcnt lgkmcnt(4)
	v_mfma_f32_32x32x16_bf16 v[52:67], v[214:217], v[226:229], v[52:67]
	s_waitcnt vmcnt(19)
	ds_write_b128 v191, v[174:177]
	v_mfma_f32_32x32x16_bf16 v[36:51], v[214:217], v[230:233], v[36:51]
	s_waitcnt vmcnt(18)
	ds_write_b128 v191, v[178:181] offset:36864
	v_mfma_f32_32x32x16_bf16 v[20:35], v[218:221], v[226:229], v[20:35]
	s_waitcnt vmcnt(17)
	ds_write_b128 v192, v[242:245]
	v_mfma_f32_32x32x16_bf16 v[4:19], v[218:221], v[230:233], v[4:19]
	s_waitcnt vmcnt(16)
	ds_write_b128 v192, v[246:249] offset:36864
	s_waitcnt lgkmcnt(0)
	s_barrier
	s_setprio 1
	ds_read_b128 v[202:205], v194
	ds_read_b128 v[218:221], v195 offset:36864
	ds_read_b128 v[226:229], v195 offset:41472
	ds_read_b128 v[210:213], v194 offset:4608
	ds_read_b128 v[206:209], v194 offset:32
	ds_read_b128 v[230:233], v195 offset:41504
	ds_read_b128 v[214:217], v194 offset:4640
	ds_read_b128 v[222:225], v195 offset:36896
	s_waitcnt lgkmcnt(6)
	v_mfma_f32_32x32x16_bf16 v[52:67], v[202:205], v[218:221], v[52:67]
	global_load_dwordx4 v[132:135], v[164:165], off offset:640
	s_waitcnt lgkmcnt(5)
	v_mfma_f32_32x32x16_bf16 v[36:51], v[202:205], v[226:229], v[36:51]
	global_load_dwordx4 v[136:139], v[162:163], off offset:640
	s_waitcnt lgkmcnt(4)
	v_mfma_f32_32x32x16_bf16 v[4:19], v[210:213], v[226:229], v[4:19]
	global_load_dwordx4 v[140:143], v[160:161], off offset:640
	s_waitcnt lgkmcnt(2)
	v_mfma_f32_32x32x16_bf16 v[36:51], v[206:209], v[230:233], v[36:51]
	global_load_dwordx4 v[198:201], v[158:159], off offset:640
	s_waitcnt lgkmcnt(1)
	v_mfma_f32_32x32x16_bf16 v[4:19], v[214:217], v[230:233], v[4:19]
	global_load_dwordx4 v[174:177], v[156:157], off offset:640
	ds_read_b128 v[230:233], v195 offset:41568
	ds_read_b128 v[202:205], v194 offset:4672
	v_mfma_f32_32x32x16_bf16 v[20:35], v[210:213], v[218:221], v[20:35]
	global_load_dwordx4 v[178:181], v[154:155], off offset:640
	ds_read_b128 v[218:221], v194 offset:4704
	ds_read_b128 v[210:213], v194 offset:64
	s_waitcnt lgkmcnt(4)
	v_mfma_f32_32x32x16_bf16 v[52:67], v[206:209], v[222:225], v[52:67]
	global_load_dwordx4 v[242:245], v[152:153], off offset:640
	ds_read_b128 v[226:229], v195 offset:36960
	ds_read_b128 v[206:209], v195 offset:41536
	v_mfma_f32_32x32x16_bf16 v[20:35], v[214:217], v[222:225], v[20:35]
	s_setprio 0
	global_load_dwordx4 v[246:249], v[146:147], off offset:640
	ds_read_b128 v[222:225], v195 offset:36928
	ds_read_b128 v[214:217], v194 offset:96
	s_waitcnt lgkmcnt(1)
	v_mfma_f32_32x32x16_bf16 v[52:67], v[210:213], v[222:225], v[52:67]
	s_waitcnt vmcnt(23)
	ds_write_b128 v167, v[68:71] offset:18432
	v_mfma_f32_32x32x16_bf16 v[36:51], v[210:213], v[206:209], v[36:51]
	s_waitcnt vmcnt(22)
	ds_write_b128 v167, v[72:75] offset:55296
	v_mfma_f32_32x32x16_bf16 v[20:35], v[202:205], v[222:225], v[20:35]
	s_waitcnt vmcnt(21)
	ds_write_b128 v190, v[76:79] offset:18432
	v_mfma_f32_32x32x16_bf16 v[4:19], v[202:205], v[206:209], v[4:19]
	s_waitcnt vmcnt(20)
	ds_write_b128 v190, v[80:83] offset:55296
	s_waitcnt lgkmcnt(4)
	v_mfma_f32_32x32x16_bf16 v[52:67], v[214:217], v[226:229], v[52:67]
	s_waitcnt vmcnt(19)
	ds_write_b128 v191, v[84:87] offset:18432
	v_mfma_f32_32x32x16_bf16 v[36:51], v[214:217], v[230:233], v[36:51]
	s_waitcnt vmcnt(18)
	ds_write_b128 v191, v[88:91] offset:55296
	v_mfma_f32_32x32x16_bf16 v[20:35], v[218:221], v[226:229], v[20:35]
	s_waitcnt vmcnt(17)
	ds_write_b128 v192, v[92:95] offset:18432
	v_mfma_f32_32x32x16_bf16 v[4:19], v[218:221], v[230:233], v[4:19]
	s_waitcnt vmcnt(16)
	ds_write_b128 v192, v[104:107] offset:55296
	s_waitcnt lgkmcnt(0)
	s_barrier
; #define MFMA(a, b, c) __builtin_amdgcn_mfma_f32_32x32x16_bf16((a), (b), (c), 0, 0, 0)
; template <class Epi, class ColV>
; DI void gemm_tile(const bf16_t* __restrict__ A, int lda, const bf16_t* __restrict__ Bt, int ldb, int K, int m0, int n0, unsigned char* smem, Epi epi, ColV colv, const bf16_t* __restrict__ HYT = nullptr) {
;     ...
;     auto gload = [&](u32x4 (&r)[8], int kt) {
; #pragma unroll
;         for (int i = 0; i < 4; ++i) { int id = tid + 256 * i, row = id >> 3, kc = id & 7;
;             if (HYT && kt >= 12) r[i] = *(const u32x4*)(HYT + (size_t)((kt - 12) * 64 + (id >> 4)) * NT + m0 + (id & 15) * 8);
;             else r[i] = *(const u32x4*)(A + (size_t)(m0 + row) * lda + kt * 64 + kc * 8);
;             r[4 + i] = *(const u32x4*)(Bt + (size_t)(n0 + row) * ldb + kt * 64 + kc * 8); }
;     };
;     auto sstore = [&](const u32x4 (&r)[8], int buf, int kt) {
; #pragma unroll
;         for (int i = 0; i < 4; ++i) { int id = tid + 256 * i, row = id >> 3, kc = id & 7;
;             if (HYT && kt >= 12) { const int kk = id >> 4, rr = (id & 15) * 8; bf16_t* d = As + (buf * 128 + rr) * LS + kk; const bf16x8 v = __builtin_bit_cast(bf16x8, r[i]);
; #pragma unroll
;                 for (int e = 0; e < 8; ++e) d[e * LS] = (bf16_t)v[e]; }
;             else *(u32x4*)(As + (buf * 128 + row) * LS + kc * 8) = r[i];
;             *(u32x4*)(Bs + (buf * 128 + row) * LS + kc * 8) = r[4 + i]; }
;     };
;     auto step = [&](int kt, u32x4 (&ldset)[8], const u32x4 (&stset)[8]) {
;         const int buf = kt & 1;
;         if (kt + 2 < nk) gload(ldset, kt + 2);
;         const bf16_t* Ab = As + (buf * 128 + 64 * wr + li) * LS + 8 * lh;
;         const bf16_t* Bb = Bs + (buf * 128 + 64 * wc + li) * LS + 8 * lh;
;         bf16x8 fa[2][2], fb[2][2], ga[2][2], gb[2][2];
; #pragma unroll
;         for (int k2 = 0; k2 < 2; ++k2) { fa[k2][0] = ld8(Ab + 16 * k2); fa[k2][1] = ld8(Ab + 32 * LS + 16 * k2); fb[k2][0] = ld8(Bb + 16 * k2); fb[k2][1] = ld8(Bb + 32 * LS + 16 * k2); }
;         __builtin_amdgcn_sched_barrier(0);
; #pragma unroll
;         for (int k2 = 0; k2 < 2; ++k2) {
;             acc[0][0] = MFMA(fa[k2][0], fb[k2][0], acc[0][0]); acc[0][1] = MFMA(fa[k2][0], fb[k2][1], acc[0][1]);
;             acc[1][0] = MFMA(fa[k2][1], fb[k2][0], acc[1][0]); acc[1][1] = MFMA(fa[k2][1], fb[k2][1], acc[1][1]);
;         }
; #pragma unroll
	s_setprio 1
	ds_read_b128 v[202:205], v196
	ds_read_b128 v[218:221], v197 offset:36864
	ds_read_b128 v[226:229], v197 offset:41472
	ds_read_b128 v[210:213], v196 offset:4608
	ds_read_b128 v[206:209], v196 offset:32
	ds_read_b128 v[230:233], v197 offset:41504
	ds_read_b128 v[214:217], v196 offset:4640
	ds_read_b128 v[222:225], v197 offset:36896
	s_waitcnt lgkmcnt(6)
	v_mfma_f32_32x32x16_bf16 v[52:67], v[202:205], v[218:221], v[52:67]
	global_load_dwordx4 v[68:71], v[164:165], off offset:768
	s_waitcnt lgkmcnt(5)
	v_mfma_f32_32x32x16_bf16 v[36:51], v[202:205], v[226:229], v[36:51]
	global_load_dwordx4 v[72:75], v[162:163], off offset:768
	s_waitcnt lgkmcnt(4)
	v_mfma_f32_32x32x16_bf16 v[4:19], v[210:213], v[226:229], v[4:19]
	global_load_dwordx4 v[76:79], v[160:161], off offset:768
	s_waitcnt lgkmcnt(2)
	v_mfma_f32_32x32x16_bf16 v[36:51], v[206:209], v[230:233], v[36:51]
	global_load_dwordx4 v[80:83], v[158:159], off offset:768
	s_waitcnt lgkmcnt(1)
	v_mfma_f32_32x32x16_bf16 v[4:19], v[214:217], v[230:233], v[4:19]
	global_load_dwordx4 v[84:87], v[156:157], off offset:768
	ds_read_b128 v[230:233], v197 offset:41568
	ds_read_b128 v[202:205], v196 offset:4672
	v_mfma_f32_32x32x16_bf16 v[20:35], v[210:213], v[218:221], v[20:35]
	global_load_dwordx4 v[88:91], v[154:155], off offset:768
	ds_read_b128 v[218:221], v196 offset:4704
	ds_read_b128 v[210:213], v196 offset:64
	s_waitcnt lgkmcnt(4)
	v_mfma_f32_32x32x16_bf16 v[52:67], v[206:209], v[222:225], v[52:67]
	global_load_dwordx4 v[92:95], v[152:153], off offset:768
	ds_read_b128 v[226:229], v197 offset:36960
	ds_read_b128 v[206:209], v197 offset:41536
	v_mfma_f32_32x32x16_bf16 v[20:35], v[214:217], v[222:225], v[20:35]
	s_setprio 0
	global_load_dwordx4 v[104:107], v[146:147], off offset:768
	ds_read_b128 v[222:225], v197 offset:36928
	ds_read_b128 v[214:217], v196 offset:96
	s_waitcnt lgkmcnt(1)
	v_mfma_f32_32x32x16_bf16 v[52:67], v[210:213], v[222:225], v[52:67]
	s_waitcnt vmcnt(23)
	ds_write_b128 v167, v[96:99]
	v_mfma_f32_32x32x16_bf16 v[36:51], v[210:213], v[206:209], v[36:51]
	s_waitcnt vmcnt(22)
	ds_write_b128 v167, v[100:103] offset:36864
	v_mfma_f32_32x32x16_bf16 v[20:35], v[202:205], v[222:225], v[20:35]
	s_waitcnt vmcnt(21)
	ds_write_b128 v190, v[108:111]
	v_mfma_f32_32x32x16_bf16 v[4:19], v[202:205], v[206:209], v[4:19]
	s_waitcnt vmcnt(20)
	ds_write_b128 v190, v[112:115] offset:36864
	s_waitcnt lgkmcnt(4)
	v_mfma_f32_32x32x16_bf16 v[52:67], v[214:217], v[226:229], v[52:67]
	s_waitcnt vmcnt(19)
	ds_write_b128 v191, v[116:119]
	v_mfma_f32_32x32x16_bf16 v[36:51], v[214:217], v[230:233], v[36:51]
	s_waitcnt vmcnt(18)
	ds_write_b128 v191, v[120:123] offset:36864
	v_mfma_f32_32x32x16_bf16 v[20:35], v[218:221], v[226:229], v[20:35]
	s_waitcnt vmcnt(17)
	ds_write_b128 v192, v[124:127]
	v_mfma_f32_32x32x16_bf16 v[4:19], v[218:221], v[230:233], v[4:19]
	s_waitcnt vmcnt(16)
	ds_write_b128 v192, v[128:131] offset:36864
	s_waitcnt lgkmcnt(0)
	s_barrier
	s_setprio 1
	ds_read_b128 v[202:205], v194
	ds_read_b128 v[218:221], v195 offset:36864
	ds_read_b128 v[226:229], v195 offset:41472
	ds_read_b128 v[210:213], v194 offset:4608
	ds_read_b128 v[206:209], v194 offset:32
	ds_read_b128 v[230:233], v195 offset:41504
	ds_read_b128 v[214:217], v194 offset:4640
	ds_read_b128 v[222:225], v195 offset:36896
	s_waitcnt lgkmcnt(6)
	v_mfma_f32_32x32x16_bf16 v[52:67], v[202:205], v[218:221], v[52:67]
	global_load_dwordx4 v[96:99], v[164:165], off offset:896
	s_waitcnt lgkmcnt(5)
	v_mfma_f32_32x32x16_bf16 v[36:51], v[202:205], v[226:229], v[36:51]
	global_load_dwordx4 v[100:103], v[162:163], off offset:896
	s_waitcnt lgkmcnt(4)
	v_mfma_f32_32x32x16_bf16 v[4:19], v[210:213], v[226:229], v[4:19]
	global_load_dwordx4 v[108:111], v[160:161], off offset:896
	s_waitcnt lgkmcnt(2)
	v_mfma_f32_32x32x16_bf16 v[36:51], v[206:209], v[230:233], v[36:51]
	global_load_dwordx4 v[112:115], v[158:159], off offset:896
	s_waitcnt lgkmcnt(1)
	v_mfma_f32_32x32x16_bf16 v[4:19], v[214:217], v[230:233], v[4:19]
	global_load_dwordx4 v[116:119], v[156:157], off offset:896
	ds_read_b128 v[230:233], v195 offset:41568
	ds_read_b128 v[202:205], v194 offset:4672
	v_mfma_f32_32x32x16_bf16 v[20:35], v[210:213], v[218:221], v[20:35]
	global_load_dwordx4 v[120:123], v[154:155], off offset:896
	ds_read_b128 v[218:221], v194 offset:4704
	ds_read_b128 v[210:213], v194 offset:64
	s_waitcnt lgkmcnt(4)
	v_mfma_f32_32x32x16_bf16 v[52:67], v[206:209], v[222:225], v[52:67]
	global_load_dwordx4 v[124:127], v[152:153], off offset:896
	ds_read_b128 v[226:229], v195 offset:36960
	ds_read_b128 v[206:209], v195 offset:41536
	v_mfma_f32_32x32x16_bf16 v[20:35], v[214:217], v[222:225], v[20:35]
	s_setprio 0
	global_load_dwordx4 v[128:131], v[146:147], off offset:896
	ds_read_b128 v[222:225], v195 offset:36928
	ds_read_b128 v[214:217], v194 offset:96
	s_waitcnt lgkmcnt(1)
	v_mfma_f32_32x32x16_bf16 v[52:67], v[210:213], v[222:225], v[52:67]
	s_waitcnt vmcnt(23)
	ds_write_b128 v167, v[132:135] offset:18432
	v_mfma_f32_32x32x16_bf16 v[36:51], v[210:213], v[206:209], v[36:51]
	s_waitcnt vmcnt(22)
	ds_write_b128 v167, v[136:139] offset:55296
	v_mfma_f32_32x32x16_bf16 v[20:35], v[202:205], v[222:225], v[20:35]
	s_waitcnt vmcnt(21)
	ds_write_b128 v190, v[140:143] offset:18432
	v_mfma_f32_32x32x16_bf16 v[4:19], v[202:205], v[206:209], v[4:19]
	s_waitcnt vmcnt(20)
	ds_write_b128 v190, v[198:201] offset:55296
	s_waitcnt lgkmcnt(4)
	v_mfma_f32_32x32x16_bf16 v[52:67], v[214:217], v[226:229], v[52:67]
	s_waitcnt vmcnt(19)
	ds_write_b128 v191, v[174:177] offset:18432
	v_mfma_f32_32x32x16_bf16 v[36:51], v[214:217], v[230:233], v[36:51]
	s_waitcnt vmcnt(18)
	ds_write_b128 v191, v[178:181] offset:55296
	v_mfma_f32_32x32x16_bf16 v[20:35], v[218:221], v[226:229], v[20:35]
	s_waitcnt vmcnt(17)
	ds_write_b128 v192, v[242:245] offset:18432
	v_mfma_f32_32x32x16_bf16 v[4:19], v[218:221], v[230:233], v[4:19]
	s_waitcnt vmcnt(16)
	ds_write_b128 v192, v[246:249] offset:55296
	s_waitcnt lgkmcnt(0)
	s_barrier
; #define MFMA(a, b, c) __builtin_amdgcn_mfma_f32_32x32x16_bf16((a), (b), (c), 0, 0, 0)
; template <class Epi, class ColV>
; DI void gemm_tile(const bf16_t* __restrict__ A, int lda, const bf16_t* __restrict__ Bt, int ldb, int K, int m0, int n0, unsigned char* smem, Epi epi, ColV colv, const bf16_t* __restrict__ HYT = nullptr) {
;     ...
;     auto gload = [&](u32x4 (&r)[8], int kt) {
; #pragma unroll
;         for (int i = 0; i < 4; ++i) { int id = tid + 256 * i, row = id >> 3, kc = id & 7;
;             if (HYT && kt >= 12) r[i] = *(const u32x4*)(HYT + (size_t)((kt - 12) * 64 + (id >> 4)) * NT + m0 + (id & 15) * 8);
;             else r[i] = *(const u32x4*)(A + (size_t)(m0 + row) * lda + kt * 64 + kc * 8);
;             r[4 + i] = *(const u32x4*)(Bt + (size_t)(n0 + row) * ldb + kt * 64 + kc * 8); }
;     };
;     auto sstore = [&](const u32x4 (&r)[8], int buf, int kt) {
; #pragma unroll
;         for (int i = 0; i < 4; ++i) { int id = tid + 256 * i, row = id >> 3, kc = id & 7;
;             if (HYT && kt >= 12) { const int kk = id >> 4, rr = (id & 15) * 8; bf16_t* d = As + (buf * 128 + rr) * LS + kk; const bf16x8 v = __builtin_bit_cast(bf16x8, r[i]);
; #pragma unroll
;                 for (int e = 0; e < 8; ++e) d[e * LS] = (bf16_t)v[e]; }
;             else *(u32x4*)(As + (buf * 128 + row) * LS + kc * 8) = r[i];
;             *(u32x4*)(Bs + (buf * 128 + row) * LS + kc * 8) = r[4 + i]; }
;     };
;     auto step = [&](int kt, u32x4 (&ldset)[8], const u32x4 (&stset)[8]) {
;         const int buf = kt & 1;
;         if (kt + 2 < nk) gload(ldset, kt + 2);
;         const bf16_t* Ab = As + (buf * 128 + 64 * wr + li) * LS + 8 * lh;
;         const bf16_t* Bb = Bs + (buf * 128 + 64 * wc + li) * LS + 8 * lh;
;         bf16x8 fa[2][2], fb[2][2], ga[2][2], gb[2][2];
; #pragma unroll
;         for (int k2 = 0; k2 < 2; ++k2) { fa[k2][0] = ld8(Ab + 16 * k2); fa[k2][1] = ld8(Ab + 32 * LS + 16 * k2); fb[k2][0] = ld8(Bb + 16 * k2); fb[k2][1] = ld8(Bb + 32 * LS + 16 * k2); }
;         __builtin_amdgcn_sched_barrier(0);
; #pragma unroll
;         for (int k2 = 0; k2 < 2; ++k2) {
;             acc[0][0] = MFMA(fa[k2][0], fb[k2][0], acc[0][0]); acc[0][1] = MFMA(fa[k2][0], fb[k2][1], acc[0][1]);
;             acc[1][0] = MFMA(fa[k2][1], fb[k2][0], acc[1][0]); acc[1][1] = MFMA(fa[k2][1], fb[k2][1], acc[1][1]);
;         }
; #pragma unroll
	s_setprio 1
	ds_read_b128 v[202:205], v196
	ds_read_b128 v[218:221], v197 offset:36864
	ds_read_b128 v[226:229], v197 offset:41472
	ds_read_b128 v[210:213], v196 offset:4608
	ds_read_b128 v[206:209], v196 offset:32
	ds_read_b128 v[230:233], v197 offset:41504
	ds_read_b128 v[214:217], v196 offset:4640
	ds_read_b128 v[222:225], v197 offset:36896
	s_waitcnt lgkmcnt(6)
	v_mfma_f32_32x32x16_bf16 v[52:67], v[202:205], v[218:221], v[52:67]
	global_load_dwordx4 v[132:135], v[164:165], off offset:1024
	s_waitcnt lgkmcnt(5)
	v_mfma_f32_32x32x16_bf16 v[36:51], v[202:205], v[226:229], v[36:51]
	global_load_dwordx4 v[136:139], v[162:163], off offset:1024
	s_waitcnt lgkmcnt(4)
	v_mfma_f32_32x32x16_bf16 v[4:19], v[210:213], v[226:229], v[4:19]
	global_load_dwordx4 v[140:143], v[160:161], off offset:1024
	s_waitcnt lgkmcnt(2)
	v_mfma_f32_32x32x16_bf16 v[36:51], v[206:209], v[230:233], v[36:51]
	global_load_dwordx4 v[198:201], v[158:159], off offset:1024
	s_waitcnt lgkmcnt(1)
	v_mfma_f32_32x32x16_bf16 v[4:19], v[214:217], v[230:233], v[4:19]
	global_load_dwordx4 v[174:177], v[156:157], off offset:1024
	ds_read_b128 v[230:233], v197 offset:41568
	ds_read_b128 v[202:205], v196 offset:4672
	v_mfma_f32_32x32x16_bf16 v[20:35], v[210:213], v[218:221], v[20:35]
	global_load_dwordx4 v[178:181], v[154:155], off offset:1024
	ds_read_b128 v[218:221], v196 offset:4704
	ds_read_b128 v[210:213], v196 offset:64
	s_waitcnt lgkmcnt(4)
	v_mfma_f32_32x32x16_bf16 v[52:67], v[206:209], v[222:225], v[52:67]
	global_load_dwordx4 v[242:245], v[152:153], off offset:1024
	ds_read_b128 v[226:229], v197 offset:36960
	ds_read_b128 v[206:209], v197 offset:41536
	v_mfma_f32_32x32x16_bf16 v[20:35], v[214:217], v[222:225], v[20:35]
	s_setprio 0
	global_load_dwordx4 v[246:249], v[146:147], off offset:1024
	ds_read_b128 v[222:225], v197 offset:36928
	ds_read_b128 v[214:217], v196 offset:96
	s_waitcnt lgkmcnt(1)
	v_mfma_f32_32x32x16_bf16 v[52:67], v[210:213], v[222:225], v[52:67]
	s_waitcnt vmcnt(23)
	ds_write_b128 v167, v[68:71]
	v_mfma_f32_32x32x16_bf16 v[36:51], v[210:213], v[206:209], v[36:51]
	s_waitcnt vmcnt(22)
	ds_write_b128 v167, v[72:75] offset:36864
	v_mfma_f32_32x32x16_bf16 v[20:35], v[202:205], v[222:225], v[20:35]
	s_waitcnt vmcnt(21)
	ds_write_b128 v190, v[76:79]
	v_mfma_f32_32x32x16_bf16 v[4:19], v[202:205], v[206:209], v[4:19]
	s_waitcnt vmcnt(20)
	ds_write_b128 v190, v[80:83] offset:36864
	s_waitcnt lgkmcnt(4)
	v_mfma_f32_32x32x16_bf16 v[52:67], v[214:217], v[226:229], v[52:67]
	s_waitcnt vmcnt(19)
	ds_write_b128 v191, v[84:87]
	v_mfma_f32_32x32x16_bf16 v[36:51], v[214:217], v[230:233], v[36:51]
	s_waitcnt vmcnt(18)
	ds_write_b128 v191, v[88:91] offset:36864
	v_mfma_f32_32x32x16_bf16 v[20:35], v[218:221], v[226:229], v[20:35]
	s_waitcnt vmcnt(17)
	ds_write_b128 v192, v[92:95]
	v_mfma_f32_32x32x16_bf16 v[4:19], v[218:221], v[230:233], v[4:19]
	s_waitcnt vmcnt(16)
	ds_write_b128 v192, v[104:107] offset:36864
	s_waitcnt lgkmcnt(0)
	s_barrier
	s_setprio 1
	ds_read_b128 v[202:205], v194
	ds_read_b128 v[218:221], v195 offset:36864
	ds_read_b128 v[226:229], v195 offset:41472
	ds_read_b128 v[210:213], v194 offset:4608
	ds_read_b128 v[206:209], v194 offset:32
	ds_read_b128 v[230:233], v195 offset:41504
	ds_read_b128 v[214:217], v194 offset:4640
	ds_read_b128 v[222:225], v195 offset:36896
	s_waitcnt lgkmcnt(6)
	v_mfma_f32_32x32x16_bf16 v[52:67], v[202:205], v[218:221], v[52:67]
	global_load_dwordx4 v[68:71], v[164:165], off offset:1152
	s_waitcnt lgkmcnt(5)
	v_mfma_f32_32x32x16_bf16 v[36:51], v[202:205], v[226:229], v[36:51]
	global_load_dwordx4 v[72:75], v[162:163], off offset:1152
	s_waitcnt lgkmcnt(4)
	v_mfma_f32_32x32x16_bf16 v[4:19], v[210:213], v[226:229], v[4:19]
	global_load_dwordx4 v[76:79], v[160:161], off offset:1152
	s_waitcnt lgkmcnt(2)
	v_mfma_f32_32x32x16_bf16 v[36:51], v[206:209], v[230:233], v[36:51]
	global_load_dwordx4 v[80:83], v[158:159], off offset:1152
	s_waitcnt lgkmcnt(1)
	v_mfma_f32_32x32x16_bf16 v[4:19], v[214:217], v[230:233], v[4:19]
	global_load_dwordx4 v[84:87], v[156:157], off offset:1152
	ds_read_b128 v[230:233], v195 offset:41568
	ds_read_b128 v[202:205], v194 offset:4672
	v_mfma_f32_32x32x16_bf16 v[20:35], v[210:213], v[218:221], v[20:35]
	global_load_dwordx4 v[88:91], v[154:155], off offset:1152
	ds_read_b128 v[218:221], v194 offset:4704
	ds_read_b128 v[210:213], v194 offset:64
	s_waitcnt lgkmcnt(4)
	v_mfma_f32_32x32x16_bf16 v[52:67], v[206:209], v[222:225], v[52:67]
	global_load_dwordx4 v[92:95], v[152:153], off offset:1152
	ds_read_b128 v[226:229], v195 offset:36960
	ds_read_b128 v[206:209], v195 offset:41536
	v_mfma_f32_32x32x16_bf16 v[20:35], v[214:217], v[222:225], v[20:35]
	s_setprio 0
	global_load_dwordx4 v[104:107], v[146:147], off offset:1152
	ds_read_b128 v[222:225], v195 offset:36928
	ds_read_b128 v[214:217], v194 offset:96
	s_waitcnt lgkmcnt(1)
	v_mfma_f32_32x32x16_bf16 v[52:67], v[210:213], v[222:225], v[52:67]
	s_waitcnt vmcnt(23)
	ds_write_b128 v167, v[96:99] offset:18432
	v_mfma_f32_32x32x16_bf16 v[36:51], v[210:213], v[206:209], v[36:51]
	s_waitcnt vmcnt(22)
	ds_write_b128 v167, v[100:103] offset:55296
	v_mfma_f32_32x32x16_bf16 v[20:35], v[202:205], v[222:225], v[20:35]
	s_waitcnt vmcnt(21)
	ds_write_b128 v190, v[108:111] offset:18432
	v_mfma_f32_32x32x16_bf16 v[4:19], v[202:205], v[206:209], v[4:19]
	s_waitcnt vmcnt(20)
	ds_write_b128 v190, v[112:115] offset:55296
	s_waitcnt lgkmcnt(4)
	v_mfma_f32_32x32x16_bf16 v[52:67], v[214:217], v[226:229], v[52:67]
	s_waitcnt vmcnt(19)
	ds_write_b128 v191, v[116:119] offset:18432
	v_mfma_f32_32x32x16_bf16 v[36:51], v[214:217], v[230:233], v[36:51]
	s_waitcnt vmcnt(18)
	ds_write_b128 v191, v[120:123] offset:55296
	v_mfma_f32_32x32x16_bf16 v[20:35], v[218:221], v[226:229], v[20:35]
	s_waitcnt vmcnt(17)
	ds_write_b128 v192, v[124:127] offset:18432
	v_mfma_f32_32x32x16_bf16 v[4:19], v[218:221], v[230:233], v[4:19]
	s_waitcnt vmcnt(16)
	ds_write_b128 v192, v[128:131] offset:55296
	s_waitcnt lgkmcnt(0)
	s_barrier
; #define MFMA(a, b, c) __builtin_amdgcn_mfma_f32_32x32x16_bf16((a), (b), (c), 0, 0, 0)
; template <class Epi, class ColV>
; DI void gemm_tile(const bf16_t* __restrict__ A, int lda, const bf16_t* __restrict__ Bt, int ldb, int K, int m0, int n0, unsigned char* smem, Epi epi, ColV colv, const bf16_t* __restrict__ HYT = nullptr) {
;     ...
;     auto gload = [&](u32x4 (&r)[8], int kt) {
; #pragma unroll
;         for (int i = 0; i < 4; ++i) { int id = tid + 256 * i, row = id >> 3, kc = id & 7;
;             if (HYT && kt >= 12) r[i] = *(const u32x4*)(HYT + (size_t)((kt - 12) * 64 + (id >> 4)) * NT + m0 + (id & 15) * 8);
;             else r[i] = *(const u32x4*)(A + (size_t)(m0 + row) * lda + kt * 64 + kc * 8);
;             r[4 + i] = *(const u32x4*)(Bt + (size_t)(n0 + row) * ldb + kt * 64 + kc * 8); }
;     };
;     auto sstore = [&](const u32x4 (&r)[8], int buf, int kt) {
; #pragma unroll
;         for (int i = 0; i < 4; ++i) { int id = tid + 256 * i, row = id >> 3, kc = id & 7;
;             if (HYT && kt >= 12) { const int kk = id >> 4, rr = (id & 15) * 8; bf16_t* d = As + (buf * 128 + rr) * LS + kk; const bf16x8 v = __builtin_bit_cast(bf16x8, r[i]);
; #pragma unroll
;                 for (int e = 0; e < 8; ++e) d[e * LS] = (bf16_t)v[e]; }
;             else *(u32x4*)(As + (buf * 128 + row) * LS + kc * 8) = r[i];
;             *(u32x4*)(Bs + (buf * 128 + row) * LS + kc * 8) = r[4 + i]; }
;     };
;     auto step = [&](int kt, u32x4 (&ldset)[8], const u32x4 (&stset)[8]) {
;         const int buf = kt & 1;
;         if (kt + 2 < nk) gload(ldset, kt + 2);
;         const bf16_t* Ab = As + (buf * 128 + 64 * wr + li) * LS + 8 * lh;
;         const bf16_t* Bb = Bs + (buf * 128 + 64 * wc + li) * LS + 8 * lh;
;         bf16x8 fa[2][2], fb[2][2], ga[2][2], gb[2][2];
; #pragma unroll
;         for (int k2 = 0; k2 < 2; ++k2) { fa[k2][0] = ld8(Ab + 16 * k2); fa[k2][1] = ld8(Ab + 32 * LS + 16 * k2); fb[k2][0] = ld8(Bb + 16 * k2); fb[k2][1] = ld8(Bb + 32 * LS + 16 * k2); }
;         __builtin_amdgcn_sched_barrier(0);
; #pragma unroll
;         for (int k2 = 0; k2 < 2; ++k2) {
;             acc[0][0] = MFMA(fa[k2][0], fb[k2][0], acc[0][0]); acc[0][1] = MFMA(fa[k2][0], fb[k2][1], acc[0][1]);
;             acc[1][0] = MFMA(fa[k2][1], fb[k2][0], acc[1][0]); acc[1][1] = MFMA(fa[k2][1], fb[k2][1], acc[1][1]);
;         }
; #pragma unroll
	s_setprio 1
	ds_read_b128 v[202:205], v196
	ds_read_b128 v[218:221], v197 offset:36864
	ds_read_b128 v[226:229], v197 offset:41472
	ds_read_b128 v[210:213], v196 offset:4608
	ds_read_b128 v[206:209], v196 offset:32
	ds_read_b128 v[230:233], v197 offset:41504
	ds_read_b128 v[214:217], v196 offset:4640
	ds_read_b128 v[222:225], v197 offset:36896
	s_waitcnt lgkmcnt(6)
	v_mfma_f32_32x32x16_bf16 v[52:67], v[202:205], v[218:221], v[52:67]
	global_load_dwordx4 v[96:99], v[164:165], off offset:1280
	s_waitcnt lgkmcnt(5)
	v_mfma_f32_32x32x16_bf16 v[36:51], v[202:205], v[226:229], v[36:51]
	global_load_dwordx4 v[100:103], v[162:163], off offset:1280
	s_waitcnt lgkmcnt(4)
	v_mfma_f32_32x32x16_bf16 v[4:19], v[210:213], v[226:229], v[4:19]
	global_load_dwordx4 v[108:111], v[160:161], off offset:1280
	s_waitcnt lgkmcnt(2)
	v_mfma_f32_32x32x16_bf16 v[36:51], v[206:209], v[230:233], v[36:51]
	global_load_dwordx4 v[112:115], v[158:159], off offset:1280
	s_waitcnt lgkmcnt(1)
	v_mfma_f32_32x32x16_bf16 v[4:19], v[214:217], v[230:233], v[4:19]
	global_load_dwordx4 v[116:119], v[156:157], off offset:1280
	ds_read_b128 v[230:233], v197 offset:41568
	ds_read_b128 v[202:205], v196 offset:4672
	v_mfma_f32_32x32x16_bf16 v[20:35], v[210:213], v[218:221], v[20:35]
	global_load_dwordx4 v[120:123], v[154:155], off offset:1280
	ds_read_b128 v[218:221], v196 offset:4704
	ds_read_b128 v[210:213], v196 offset:64
	s_waitcnt lgkmcnt(4)
	v_mfma_f32_32x32x16_bf16 v[52:67], v[206:209], v[222:225], v[52:67]
	global_load_dwordx4 v[124:127], v[152:153], off offset:1280
	ds_read_b128 v[226:229], v197 offset:36960
	ds_read_b128 v[206:209], v197 offset:41536
	v_mfma_f32_32x32x16_bf16 v[20:35], v[214:217], v[222:225], v[20:35]
	s_setprio 0
	global_load_dwordx4 v[128:131], v[146:147], off offset:1280
	ds_read_b128 v[222:225], v197 offset:36928
	ds_read_b128 v[214:217], v196 offset:96
	s_waitcnt lgkmcnt(1)
	v_mfma_f32_32x32x16_bf16 v[52:67], v[210:213], v[222:225], v[52:67]
	s_waitcnt vmcnt(23)
	ds_write_b128 v167, v[132:135]
	v_mfma_f32_32x32x16_bf16 v[36:51], v[210:213], v[206:209], v[36:51]
	s_waitcnt vmcnt(22)
	ds_write_b128 v167, v[136:139] offset:36864
	v_mfma_f32_32x32x16_bf16 v[20:35], v[202:205], v[222:225], v[20:35]
	s_waitcnt vmcnt(21)
	ds_write_b128 v190, v[140:143]
	v_mfma_f32_32x32x16_bf16 v[4:19], v[202:205], v[206:209], v[4:19]
	s_waitcnt vmcnt(20)
	ds_write_b128 v190, v[198:201] offset:36864
	s_waitcnt lgkmcnt(4)
	v_mfma_f32_32x32x16_bf16 v[52:67], v[214:217], v[226:229], v[52:67]
	s_waitcnt vmcnt(19)
	ds_write_b128 v191, v[174:177]
	v_mfma_f32_32x32x16_bf16 v[36:51], v[214:217], v[230:233], v[36:51]
	s_waitcnt vmcnt(18)
	ds_write_b128 v191, v[178:181] offset:36864
	v_mfma_f32_32x32x16_bf16 v[20:35], v[218:221], v[226:229], v[20:35]
	s_waitcnt vmcnt(17)
	ds_write_b128 v192, v[242:245]
	v_mfma_f32_32x32x16_bf16 v[4:19], v[218:221], v[230:233], v[4:19]
	s_waitcnt vmcnt(16)
	ds_write_b128 v192, v[246:249] offset:36864
	s_waitcnt lgkmcnt(0)
	s_barrier
	s_setprio 1
	ds_read_b128 v[202:205], v194
	ds_read_b128 v[218:221], v195 offset:36864
	ds_read_b128 v[226:229], v195 offset:41472
	ds_read_b128 v[210:213], v194 offset:4608
	ds_read_b128 v[206:209], v194 offset:32
	ds_read_b128 v[230:233], v195 offset:41504
	ds_read_b128 v[214:217], v194 offset:4640
	ds_read_b128 v[222:225], v195 offset:36896
	s_waitcnt lgkmcnt(6)
	v_mfma_f32_32x32x16_bf16 v[52:67], v[202:205], v[218:221], v[52:67]
	global_load_dwordx4 v[132:135], v[164:165], off offset:1408
	s_waitcnt lgkmcnt(5)
	v_mfma_f32_32x32x16_bf16 v[36:51], v[202:205], v[226:229], v[36:51]
	global_load_dwordx4 v[136:139], v[162:163], off offset:1408
	s_waitcnt lgkmcnt(4)
	v_mfma_f32_32x32x16_bf16 v[4:19], v[210:213], v[226:229], v[4:19]
	global_load_dwordx4 v[140:143], v[160:161], off offset:1408
	s_waitcnt lgkmcnt(2)
	v_mfma_f32_32x32x16_bf16 v[36:51], v[206:209], v[230:233], v[36:51]
	global_load_dwordx4 v[198:201], v[158:159], off offset:1408
	s_waitcnt lgkmcnt(1)
	v_mfma_f32_32x32x16_bf16 v[4:19], v[214:217], v[230:233], v[4:19]
	global_load_dwordx4 v[174:177], v[156:157], off offset:1408
	ds_read_b128 v[230:233], v195 offset:41568
	ds_read_b128 v[202:205], v194 offset:4672
	v_mfma_f32_32x32x16_bf16 v[20:35], v[210:213], v[218:221], v[20:35]
	global_load_dwordx4 v[178:181], v[154:155], off offset:1408
	ds_read_b128 v[218:221], v194 offset:4704
	ds_read_b128 v[210:213], v194 offset:64
	s_waitcnt lgkmcnt(4)
	v_mfma_f32_32x32x16_bf16 v[52:67], v[206:209], v[222:225], v[52:67]
	global_load_dwordx4 v[242:245], v[152:153], off offset:1408
	ds_read_b128 v[226:229], v195 offset:36960
	ds_read_b128 v[206:209], v195 offset:41536
	v_mfma_f32_32x32x16_bf16 v[20:35], v[214:217], v[222:225], v[20:35]
	s_setprio 0
	global_load_dwordx4 v[246:249], v[146:147], off offset:1408
	ds_read_b128 v[222:225], v195 offset:36928
	ds_read_b128 v[214:217], v194 offset:96
	s_waitcnt lgkmcnt(1)
	v_mfma_f32_32x32x16_bf16 v[52:67], v[210:213], v[222:225], v[52:67]
	s_waitcnt vmcnt(23)
	ds_write_b128 v167, v[68:71] offset:18432
	v_mfma_f32_32x32x16_bf16 v[36:51], v[210:213], v[206:209], v[36:51]
	s_waitcnt vmcnt(22)
	ds_write_b128 v167, v[72:75] offset:55296
	v_mfma_f32_32x32x16_bf16 v[20:35], v[202:205], v[222:225], v[20:35]
	s_waitcnt vmcnt(21)
	ds_write_b128 v190, v[76:79] offset:18432
	v_mfma_f32_32x32x16_bf16 v[4:19], v[202:205], v[206:209], v[4:19]
	s_waitcnt vmcnt(20)
	ds_write_b128 v190, v[80:83] offset:55296
	s_waitcnt lgkmcnt(4)
	v_mfma_f32_32x32x16_bf16 v[52:67], v[214:217], v[226:229], v[52:67]
	s_waitcnt vmcnt(19)
	ds_write_b128 v191, v[84:87] offset:18432
	v_mfma_f32_32x32x16_bf16 v[36:51], v[214:217], v[230:233], v[36:51]
	s_waitcnt vmcnt(18)
	ds_write_b128 v191, v[88:91] offset:55296
	v_mfma_f32_32x32x16_bf16 v[20:35], v[218:221], v[226:229], v[20:35]
	s_waitcnt vmcnt(17)
	ds_write_b128 v192, v[92:95] offset:18432
	v_mfma_f32_32x32x16_bf16 v[4:19], v[218:221], v[230:233], v[4:19]
	s_waitcnt vmcnt(16)
	ds_write_b128 v192, v[104:107] offset:55296
	s_waitcnt lgkmcnt(0)
	s_barrier
; #define MFMA(a, b, c) __builtin_amdgcn_mfma_f32_32x32x16_bf16((a), (b), (c), 0, 0, 0)
; template <class Epi, class ColV>
; DI void gemm_tile(const bf16_t* __restrict__ A, int lda, const bf16_t* __restrict__ Bt, int ldb, int K, int m0, int n0, unsigned char* smem, Epi epi, ColV colv, const bf16_t* __restrict__ HYT = nullptr) {
;     ...
;     auto gload = [&](u32x4 (&r)[8], int kt) {
; #pragma unroll
;         for (int i = 0; i < 4; ++i) { int id = tid + 256 * i, row = id >> 3, kc = id & 7;
;             if (HYT && kt >= 12) r[i] = *(const u32x4*)(HYT + (size_t)((kt - 12) * 64 + (id >> 4)) * NT + m0 + (id & 15) * 8);
;             else r[i] = *(const u32x4*)(A + (size_t)(m0 + row) * lda + kt * 64 + kc * 8);
;             r[4 + i] = *(const u32x4*)(Bt + (size_t)(n0 + row) * ldb + kt * 64 + kc * 8); }
;     };
;     auto sstore = [&](const u32x4 (&r)[8], int buf, int kt) {
; #pragma unroll
;         for (int i = 0; i < 4; ++i) { int id = tid + 256 * i, row = id >> 3, kc = id & 7;
;             if (HYT && kt >= 12) { const int kk = id >> 4, rr = (id & 15) * 8; bf16_t* d = As + (buf * 128 + rr) * LS + kk; const bf16x8 v = __builtin_bit_cast(bf16x8, r[i]);
; #pragma unroll
;                 for (int e = 0; e < 8; ++e) d[e * LS] = (bf16_t)v[e]; }
;             else *(u32x4*)(As + (buf * 128 + row) * LS + kc * 8) = r[i];
;             *(u32x4*)(Bs + (buf * 128 + row) * LS + kc * 8) = r[4 + i]; }
;     };
;     auto step = [&](int kt, u32x4 (&ldset)[8], const u32x4 (&stset)[8]) {
;         const int buf = kt & 1;
;         if (kt + 2 < nk) gload(ldset, kt + 2);
;         const bf16_t* Ab = As + (buf * 128 + 64 * wr + li) * LS + 8 * lh;
;         const bf16_t* Bb = Bs + (buf * 128 + 64 * wc + li) * LS + 8 * lh;
;         bf16x8 fa[2][2], fb[2][2], ga[2][2], gb[2][2];
; #pragma unroll
;         for (int k2 = 0; k2 < 2; ++k2) { fa[k2][0] = ld8(Ab + 16 * k2); fa[k2][1] = ld8(Ab + 32 * LS + 16 * k2); fb[k2][0] = ld8(Bb + 16 * k2); fb[k2][1] = ld8(Bb + 32 * LS + 16 * k2); }
;         __builtin_amdgcn_sched_barrier(0);
; #pragma unroll
;         for (int k2 = 0; k2 < 2; ++k2) {
;             acc[0][0] = MFMA(fa[k2][0], fb[k2][0], acc[0][0]); acc[0][1] = MFMA(fa[k2][0], fb[k2][1], acc[0][1]);
;             acc[1][0] = MFMA(fa[k2][1], fb[k2][0], acc[1][0]); acc[1][1] = MFMA(fa[k2][1], fb[k2][1], acc[1][1]);
;         }
; #pragma unroll
	s_setprio 1
	ds_read_b128 v[202:205], v196
	ds_read_b128 v[218:221], v197 offset:36864
	ds_read_b128 v[226:229], v197 offset:41472
	ds_read_b128 v[210:213], v196 offset:4608
	ds_read_b128 v[206:209], v196 offset:32
	ds_read_b128 v[230:233], v197 offset:41504
	ds_read_b128 v[214:217], v196 offset:4640
	ds_read_b128 v[222:225], v197 offset:36896
	s_waitcnt lgkmcnt(6)
	v_mfma_f32_32x32x16_bf16 v[52:67], v[202:205], v[218:221], v[52:67]
	global_load_dwordx4 v[68:71], v[164:165], off offset:1536
	s_waitcnt lgkmcnt(5)
	v_mfma_f32_32x32x16_bf16 v[36:51], v[202:205], v[226:229], v[36:51]
	global_load_dwordx4 v[72:75], v[162:163], off offset:1536
	s_waitcnt lgkmcnt(4)
	v_mfma_f32_32x32x16_bf16 v[4:19], v[210:213], v[226:229], v[4:19]
	global_load_dwordx4 v[76:79], v[160:161], off offset:1536
	s_waitcnt lgkmcnt(2)
	v_mfma_f32_32x32x16_bf16 v[36:51], v[206:209], v[230:233], v[36:51]
	global_load_dwordx4 v[80:83], v[158:159], off offset:1536
	s_waitcnt lgkmcnt(1)
	v_mfma_f32_32x32x16_bf16 v[4:19], v[214:217], v[230:233], v[4:19]
	global_load_dwordx4 v[84:87], v[156:157], off offset:1536
	ds_read_b128 v[230:233], v197 offset:41568
	ds_read_b128 v[202:205], v196 offset:4672
	v_mfma_f32_32x32x16_bf16 v[20:35], v[210:213], v[218:221], v[20:35]
	global_load_dwordx4 v[88:91], v[154:155], off offset:1536
	ds_read_b128 v[218:221], v196 offset:4704
	ds_read_b128 v[210:213], v196 offset:64
	s_waitcnt lgkmcnt(4)
	v_mfma_f32_32x32x16_bf16 v[52:67], v[206:209], v[222:225], v[52:67]
	global_load_dwordx4 v[92:95], v[152:153], off offset:1536
	ds_read_b128 v[226:229], v197 offset:36960
	ds_read_b128 v[206:209], v197 offset:41536
	v_mfma_f32_32x32x16_bf16 v[20:35], v[214:217], v[222:225], v[20:35]
	s_setprio 0
	global_load_dwordx4 v[104:107], v[146:147], off offset:1536
	ds_read_b128 v[222:225], v197 offset:36928
	ds_read_b128 v[214:217], v196 offset:96
	s_waitcnt lgkmcnt(1)
	v_mfma_f32_32x32x16_bf16 v[52:67], v[210:213], v[222:225], v[52:67]
	s_waitcnt vmcnt(23)
	ds_write_b128 v167, v[96:99]
	v_mfma_f32_32x32x16_bf16 v[36:51], v[210:213], v[206:209], v[36:51]
	s_waitcnt vmcnt(22)
	ds_write_b128 v167, v[100:103] offset:36864
	v_mfma_f32_32x32x16_bf16 v[20:35], v[202:205], v[222:225], v[20:35]
	s_waitcnt vmcnt(21)
	ds_write_b128 v190, v[108:111]
	v_mfma_f32_32x32x16_bf16 v[4:19], v[202:205], v[206:209], v[4:19]
	s_waitcnt vmcnt(20)
	ds_write_b128 v190, v[112:115] offset:36864
	s_waitcnt lgkmcnt(4)
	v_mfma_f32_32x32x16_bf16 v[52:67], v[214:217], v[226:229], v[52:67]
	s_waitcnt vmcnt(19)
	ds_write_b128 v191, v[116:119]
	v_mfma_f32_32x32x16_bf16 v[36:51], v[214:217], v[230:233], v[36:51]
	s_waitcnt vmcnt(18)
	ds_write_b128 v191, v[120:123] offset:36864
	v_mfma_f32_32x32x16_bf16 v[20:35], v[218:221], v[226:229], v[20:35]
	s_waitcnt vmcnt(17)
	ds_write_b128 v192, v[124:127]
	v_mfma_f32_32x32x16_bf16 v[4:19], v[218:221], v[230:233], v[4:19]
	s_waitcnt vmcnt(16)
	ds_write_b128 v192, v[128:131] offset:36864
	s_waitcnt lgkmcnt(0)
	s_barrier
	s_setprio 1
	ds_read_b128 v[202:205], v194
	ds_read_b128 v[218:221], v195 offset:36864
	ds_read_b128 v[226:229], v195 offset:41472
	ds_read_b128 v[210:213], v194 offset:4608
	ds_read_b128 v[206:209], v194 offset:32
	ds_read_b128 v[230:233], v195 offset:41504
	ds_read_b128 v[214:217], v194 offset:4640
	ds_read_b128 v[222:225], v195 offset:36896
	s_waitcnt lgkmcnt(6)
	v_mfma_f32_32x32x16_bf16 v[52:67], v[202:205], v[218:221], v[52:67]
	global_load_dwordx4 v[96:99], v[164:165], off offset:1664
	s_waitcnt lgkmcnt(5)
	v_mfma_f32_32x32x16_bf16 v[36:51], v[202:205], v[226:229], v[36:51]
	global_load_dwordx4 v[100:103], v[162:163], off offset:1664
	s_waitcnt lgkmcnt(4)
	v_mfma_f32_32x32x16_bf16 v[4:19], v[210:213], v[226:229], v[4:19]
	global_load_dwordx4 v[108:111], v[160:161], off offset:1664
	s_waitcnt lgkmcnt(2)
	v_mfma_f32_32x32x16_bf16 v[36:51], v[206:209], v[230:233], v[36:51]
	global_load_dwordx4 v[112:115], v[158:159], off offset:1664
	s_waitcnt lgkmcnt(1)
	v_mfma_f32_32x32x16_bf16 v[4:19], v[214:217], v[230:233], v[4:19]
	global_load_dwordx4 v[116:119], v[156:157], off offset:1664
	ds_read_b128 v[230:233], v195 offset:41568
	ds_read_b128 v[202:205], v194 offset:4672
	v_mfma_f32_32x32x16_bf16 v[20:35], v[210:213], v[218:221], v[20:35]
	global_load_dwordx4 v[120:123], v[154:155], off offset:1664
	ds_read_b128 v[218:221], v194 offset:4704
	ds_read_b128 v[210:213], v194 offset:64
	s_waitcnt lgkmcnt(4)
	v_mfma_f32_32x32x16_bf16 v[52:67], v[206:209], v[222:225], v[52:67]
	global_load_dwordx4 v[124:127], v[152:153], off offset:1664
	ds_read_b128 v[226:229], v195 offset:36960
	ds_read_b128 v[206:209], v195 offset:41536
	v_mfma_f32_32x32x16_bf16 v[20:35], v[214:217], v[222:225], v[20:35]
	s_setprio 0
	global_load_dwordx4 v[128:131], v[146:147], off offset:1664
	ds_read_b128 v[222:225], v195 offset:36928
	ds_read_b128 v[214:217], v194 offset:96
	s_waitcnt lgkmcnt(1)
	v_mfma_f32_32x32x16_bf16 v[52:67], v[210:213], v[222:225], v[52:67]
	s_waitcnt vmcnt(23)
	ds_write_b128 v167, v[132:135] offset:18432
	v_mfma_f32_32x32x16_bf16 v[36:51], v[210:213], v[206:209], v[36:51]
	s_waitcnt vmcnt(22)
	ds_write_b128 v167, v[136:139] offset:55296
	v_mfma_f32_32x32x16_bf16 v[20:35], v[202:205], v[222:225], v[20:35]
	s_waitcnt vmcnt(21)
	ds_write_b128 v190, v[140:143] offset:18432
	v_mfma_f32_32x32x16_bf16 v[4:19], v[202:205], v[206:209], v[4:19]
	s_waitcnt vmcnt(20)
	ds_write_b128 v190, v[198:201] offset:55296
	s_waitcnt lgkmcnt(4)
	v_mfma_f32_32x32x16_bf16 v[52:67], v[214:217], v[226:229], v[52:67]
	s_waitcnt vmcnt(19)
	ds_write_b128 v191, v[174:177] offset:18432
	v_mfma_f32_32x32x16_bf16 v[36:51], v[214:217], v[230:233], v[36:51]
	s_waitcnt vmcnt(18)
	ds_write_b128 v191, v[178:181] offset:55296
	v_mfma_f32_32x32x16_bf16 v[20:35], v[218:221], v[226:229], v[20:35]
	s_waitcnt vmcnt(17)
	ds_write_b128 v192, v[242:245] offset:18432
	v_mfma_f32_32x32x16_bf16 v[4:19], v[218:221], v[230:233], v[4:19]
	s_waitcnt vmcnt(16)
	ds_write_b128 v192, v[246:249] offset:55296
	s_waitcnt lgkmcnt(0)
	s_barrier
; #define MFMA(a, b, c) __builtin_amdgcn_mfma_f32_32x32x16_bf16((a), (b), (c), 0, 0, 0)
; template <class Epi, class ColV>
; DI void gemm_tile(const bf16_t* __restrict__ A, int lda, const bf16_t* __restrict__ Bt, int ldb, int K, int m0, int n0, unsigned char* smem, Epi epi, ColV colv, const bf16_t* __restrict__ HYT = nullptr) {
;     ...
;     auto gload = [&](u32x4 (&r)[8], int kt) {
; #pragma unroll
;         for (int i = 0; i < 4; ++i) { int id = tid + 256 * i, row = id >> 3, kc = id & 7;
;             if (HYT && kt >= 12) r[i] = *(const u32x4*)(HYT + (size_t)((kt - 12) * 64 + (id >> 4)) * NT + m0 + (id & 15) * 8);
;             else r[i] = *(const u32x4*)(A + (size_t)(m0 + row) * lda + kt * 64 + kc * 8);
;             r[4 + i] = *(const u32x4*)(Bt + (size_t)(n0 + row) * ldb + kt * 64 + kc * 8); }
;     };
;     auto sstore = [&](const u32x4 (&r)[8], int buf, int kt) {
; #pragma unroll
;         for (int i = 0; i < 4; ++i) { int id = tid + 256 * i, row = id >> 3, kc = id & 7;
;             if (HYT && kt >= 12) { const int kk = id >> 4, rr = (id & 15) * 8; bf16_t* d = As + (buf * 128 + rr) * LS + kk; const bf16x8 v = __builtin_bit_cast(bf16x8, r[i]);
; #pragma unroll
;                 for (int e = 0; e < 8; ++e) d[e * LS] = (bf16_t)v[e]; }
;             else *(u32x4*)(As + (buf * 128 + row) * LS + kc * 8) = r[i];
;             *(u32x4*)(Bs + (buf * 128 + row) * LS + kc * 8) = r[4 + i]; }
;     };
;     auto step = [&](int kt, u32x4 (&ldset)[8], const u32x4 (&stset)[8]) {
;         const int buf = kt & 1;
;         if (kt + 2 < nk) gload(ldset, kt + 2);
;         const bf16_t* Ab = As + (buf * 128 + 64 * wr + li) * LS + 8 * lh;
;         const bf16_t* Bb = Bs + (buf * 128 + 64 * wc + li) * LS + 8 * lh;
;         bf16x8 fa[2][2], fb[2][2], ga[2][2], gb[2][2];
; #pragma unroll
;         for (int k2 = 0; k2 < 2; ++k2) { fa[k2][0] = ld8(Ab + 16 * k2); fa[k2][1] = ld8(Ab + 32 * LS + 16 * k2); fb[k2][0] = ld8(Bb + 16 * k2); fb[k2][1] = ld8(Bb + 32 * LS + 16 * k2); }
;         __builtin_amdgcn_sched_barrier(0);
; #pragma unroll
;         for (int k2 = 0; k2 < 2; ++k2) {
;             acc[0][0] = MFMA(fa[k2][0], fb[k2][0], acc[0][0]); acc[0][1] = MFMA(fa[k2][0], fb[k2][1], acc[0][1]);
;             acc[1][0] = MFMA(fa[k2][1], fb[k2][0], acc[1][0]); acc[1][1] = MFMA(fa[k2][1], fb[k2][1], acc[1][1]);
;         }
; #pragma unroll
	s_setprio 1
	ds_read_b128 v[202:205], v196
	ds_read_b128 v[218:221], v197 offset:36864
	ds_read_b128 v[226:229], v197 offset:41472
	ds_read_b128 v[210:213], v196 offset:4608
	ds_read_b128 v[206:209], v196 offset:32
	ds_read_b128 v[230:233], v197 offset:41504
	ds_read_b128 v[214:217], v196 offset:4640
	ds_read_b128 v[222:225], v197 offset:36896
	s_waitcnt lgkmcnt(6)
	v_mfma_f32_32x32x16_bf16 v[52:67], v[202:205], v[218:221], v[52:67]
	global_load_dwordx4 v[132:135], v[164:165], off offset:1792
	s_waitcnt lgkmcnt(5)
	v_mfma_f32_32x32x16_bf16 v[36:51], v[202:205], v[226:229], v[36:51]
	global_load_dwordx4 v[136:139], v[162:163], off offset:1792
	s_waitcnt lgkmcnt(4)
	v_mfma_f32_32x32x16_bf16 v[4:19], v[210:213], v[226:229], v[4:19]
	global_load_dwordx4 v[140:143], v[160:161], off offset:1792
	s_waitcnt lgkmcnt(2)
	v_mfma_f32_32x32x16_bf16 v[36:51], v[206:209], v[230:233], v[36:51]
	global_load_dwordx4 v[198:201], v[158:159], off offset:1792
	s_waitcnt lgkmcnt(1)
	v_mfma_f32_32x32x16_bf16 v[4:19], v[214:217], v[230:233], v[4:19]
	global_load_dwordx4 v[174:177], v[156:157], off offset:1792
	ds_read_b128 v[230:233], v197 offset:41568
	ds_read_b128 v[202:205], v196 offset:4672
	v_mfma_f32_32x32x16_bf16 v[20:35], v[210:213], v[218:221], v[20:35]
	global_load_dwordx4 v[178:181], v[154:155], off offset:1792
	ds_read_b128 v[218:221], v196 offset:4704
	ds_read_b128 v[210:213], v196 offset:64
	s_waitcnt lgkmcnt(4)
	v_mfma_f32_32x32x16_bf16 v[52:67], v[206:209], v[222:225], v[52:67]
	global_load_dwordx4 v[242:245], v[152:153], off offset:1792
	ds_read_b128 v[226:229], v197 offset:36960
	ds_read_b128 v[206:209], v197 offset:41536
	v_mfma_f32_32x32x16_bf16 v[20:35], v[214:217], v[222:225], v[20:35]
	s_setprio 0
	global_load_dwordx4 v[246:249], v[146:147], off offset:1792
	ds_read_b128 v[222:225], v197 offset:36928
	ds_read_b128 v[214:217], v196 offset:96
	s_waitcnt lgkmcnt(1)
	v_mfma_f32_32x32x16_bf16 v[52:67], v[210:213], v[222:225], v[52:67]
	s_waitcnt vmcnt(23)
	ds_write_b128 v167, v[68:71]
	v_mfma_f32_32x32x16_bf16 v[36:51], v[210:213], v[206:209], v[36:51]
	s_waitcnt vmcnt(22)
	ds_write_b128 v167, v[72:75] offset:36864
	v_mfma_f32_32x32x16_bf16 v[20:35], v[202:205], v[222:225], v[20:35]
	s_waitcnt vmcnt(21)
	ds_write_b128 v190, v[76:79]
	v_mfma_f32_32x32x16_bf16 v[4:19], v[202:205], v[206:209], v[4:19]
	s_waitcnt vmcnt(20)
	ds_write_b128 v190, v[80:83] offset:36864
	s_waitcnt lgkmcnt(4)
	v_mfma_f32_32x32x16_bf16 v[52:67], v[214:217], v[226:229], v[52:67]
	s_waitcnt vmcnt(19)
	ds_write_b128 v191, v[84:87]
	v_mfma_f32_32x32x16_bf16 v[36:51], v[214:217], v[230:233], v[36:51]
	s_waitcnt vmcnt(18)
	ds_write_b128 v191, v[88:91] offset:36864
	v_mfma_f32_32x32x16_bf16 v[20:35], v[218:221], v[226:229], v[20:35]
	s_waitcnt vmcnt(17)
	ds_write_b128 v192, v[92:95]
	v_mfma_f32_32x32x16_bf16 v[4:19], v[218:221], v[230:233], v[4:19]
	s_waitcnt vmcnt(16)
	ds_write_b128 v192, v[104:107] offset:36864
	s_waitcnt lgkmcnt(0)
	s_barrier
	s_setprio 1
	ds_read_b128 v[202:205], v194
	ds_read_b128 v[218:221], v195 offset:36864
	ds_read_b128 v[226:229], v195 offset:41472
	ds_read_b128 v[210:213], v194 offset:4608
	ds_read_b128 v[206:209], v194 offset:32
	ds_read_b128 v[230:233], v195 offset:41504
	ds_read_b128 v[214:217], v194 offset:4640
	ds_read_b128 v[222:225], v195 offset:36896
	s_waitcnt lgkmcnt(6)
	v_mfma_f32_32x32x16_bf16 v[52:67], v[202:205], v[218:221], v[52:67]
	global_load_dwordx4 v[68:71], v[164:165], off offset:1920
	s_waitcnt lgkmcnt(5)
	v_mfma_f32_32x32x16_bf16 v[36:51], v[202:205], v[226:229], v[36:51]
	global_load_dwordx4 v[72:75], v[162:163], off offset:1920
	s_waitcnt lgkmcnt(4)
	v_mfma_f32_32x32x16_bf16 v[4:19], v[210:213], v[226:229], v[4:19]
	global_load_dwordx4 v[76:79], v[160:161], off offset:1920
	s_waitcnt lgkmcnt(2)
	v_mfma_f32_32x32x16_bf16 v[36:51], v[206:209], v[230:233], v[36:51]
	global_load_dwordx4 v[80:83], v[158:159], off offset:1920
	s_waitcnt lgkmcnt(1)
	v_mfma_f32_32x32x16_bf16 v[4:19], v[214:217], v[230:233], v[4:19]
	global_load_dwordx4 v[84:87], v[156:157], off offset:1920
	ds_read_b128 v[230:233], v195 offset:41568
	ds_read_b128 v[202:205], v194 offset:4672
	v_mfma_f32_32x32x16_bf16 v[20:35], v[210:213], v[218:221], v[20:35]
	global_load_dwordx4 v[88:91], v[154:155], off offset:1920
	ds_read_b128 v[218:221], v194 offset:4704
	ds_read_b128 v[210:213], v194 offset:64
	s_waitcnt lgkmcnt(4)
	v_mfma_f32_32x32x16_bf16 v[52:67], v[206:209], v[222:225], v[52:67]
	global_load_dwordx4 v[92:95], v[152:153], off offset:1920
	ds_read_b128 v[226:229], v195 offset:36960
	ds_read_b128 v[206:209], v195 offset:41536
	v_mfma_f32_32x32x16_bf16 v[20:35], v[214:217], v[222:225], v[20:35]
	s_setprio 0
	global_load_dwordx4 v[104:107], v[146:147], off offset:1920
	ds_read_b128 v[222:225], v195 offset:36928
	ds_read_b128 v[214:217], v194 offset:96
	s_waitcnt lgkmcnt(1)
	v_mfma_f32_32x32x16_bf16 v[52:67], v[210:213], v[222:225], v[52:67]
	s_waitcnt vmcnt(23)
	ds_write_b128 v167, v[96:99] offset:18432
	v_mfma_f32_32x32x16_bf16 v[36:51], v[210:213], v[206:209], v[36:51]
	s_waitcnt vmcnt(22)
	ds_write_b128 v167, v[100:103] offset:55296
	v_mfma_f32_32x32x16_bf16 v[20:35], v[202:205], v[222:225], v[20:35]
	s_waitcnt vmcnt(21)
	ds_write_b128 v190, v[108:111] offset:18432
	v_mfma_f32_32x32x16_bf16 v[4:19], v[202:205], v[206:209], v[4:19]
	s_waitcnt vmcnt(20)
	ds_write_b128 v190, v[112:115] offset:55296
	s_waitcnt lgkmcnt(4)
	v_mfma_f32_32x32x16_bf16 v[52:67], v[214:217], v[226:229], v[52:67]
	s_waitcnt vmcnt(19)
	ds_write_b128 v191, v[116:119] offset:18432
	v_mfma_f32_32x32x16_bf16 v[36:51], v[214:217], v[230:233], v[36:51]
	s_waitcnt vmcnt(18)
	ds_write_b128 v191, v[120:123] offset:55296
	v_mfma_f32_32x32x16_bf16 v[20:35], v[218:221], v[226:229], v[20:35]
	s_waitcnt vmcnt(17)
	ds_write_b128 v192, v[124:127] offset:18432
	v_mfma_f32_32x32x16_bf16 v[4:19], v[218:221], v[230:233], v[4:19]
	s_waitcnt vmcnt(16)
	ds_write_b128 v192, v[128:131] offset:55296
	s_waitcnt lgkmcnt(0)
	s_barrier
; #define MFMA(a, b, c) __builtin_amdgcn_mfma_f32_32x32x16_bf16((a), (b), (c), 0, 0, 0)
; template <class Epi, class ColV>
; DI void gemm_tile(const bf16_t* __restrict__ A, int lda, const bf16_t* __restrict__ Bt, int ldb, int K, int m0, int n0, unsigned char* smem, Epi epi, ColV colv, const bf16_t* __restrict__ HYT = nullptr) {
;     ...
;     auto step = [&](int kt, u32x4 (&ldset)[8], const u32x4 (&stset)[8]) {
;         const int buf = kt & 1;
;         if (kt + 2 < nk) gload(ldset, kt + 2);
;         const bf16_t* Ab = As + (buf * 128 + 64 * wr + li) * LS + 8 * lh;
;         const bf16_t* Bb = Bs + (buf * 128 + 64 * wc + li) * LS + 8 * lh;
;         bf16x8 fa[2][2], fb[2][2], ga[2][2], gb[2][2];
; #pragma unroll
;         for (int k2 = 0; k2 < 2; ++k2) { fa[k2][0] = ld8(Ab + 16 * k2); fa[k2][1] = ld8(Ab + 32 * LS + 16 * k2); fb[k2][0] = ld8(Bb + 16 * k2); fb[k2][1] = ld8(Bb + 32 * LS + 16 * k2); }
;         __builtin_amdgcn_sched_barrier(0);
; #pragma unroll
;         for (int k2 = 0; k2 < 2; ++k2) {
;             acc[0][0] = MFMA(fa[k2][0], fb[k2][0], acc[0][0]); acc[0][1] = MFMA(fa[k2][0], fb[k2][1], acc[0][1]);
;             acc[1][0] = MFMA(fa[k2][1], fb[k2][0], acc[1][0]); acc[1][1] = MFMA(fa[k2][1], fb[k2][1], acc[1][1]);
;         }
; #pragma unroll
;         for (int k2 = 0; k2 < 2; ++k2) { const int ks = 2 + k2; ga[k2][0] = ld8(Ab + 16 * ks); ga[k2][1] = ld8(Ab + 32 * LS + 16 * ks); gb[k2][0] = ld8(Bb + 16 * ks); gb[k2][1] = ld8(Bb + 32 * LS + 16 * ks); }
; #pragma unroll
;         for (int k2 = 0; k2 < 2; ++k2) {
;             acc[0][0] = MFMA(ga[k2][0], gb[k2][0], acc[0][0]); acc[0][1] = MFMA(ga[k2][0], gb[k2][1], acc[0][1]);
;             acc[1][0] = MFMA(ga[k2][1], gb[k2][0], acc[1][0]); acc[1][1] = MFMA(ga[k2][1], gb[k2][1], acc[1][1]);
;         }
;         if (kt + 1 < nk) sstore(stset, buf ^ 1, kt + 1);
; #pragma unroll
;         for (int i = 0; i < 8; ++i) { __builtin_amdgcn_sched_group_barrier(0x008, 1, 0); __builtin_amdgcn_sched_group_barrier(0x100, 1, 0); }
; #pragma unroll
;         for (int i = 0; i < 8; ++i) { __builtin_amdgcn_sched_group_barrier(0x008, 1, 0); __builtin_amdgcn_sched_group_barrier(0x200, 1, 0); }
;         __builtin_amdgcn_sched_barrier(0);
;         __syncthreads();
;     };
	s_setprio 1
	ds_read_b128 v[202:205], v196
	ds_read_b128 v[218:221], v197 offset:36864
	ds_read_b128 v[226:229], v197 offset:41472
	ds_read_b128 v[210:213], v196 offset:4608
	ds_read_b128 v[206:209], v196 offset:32
	ds_read_b128 v[230:233], v197 offset:41504
	ds_read_b128 v[214:217], v196 offset:4640
	ds_read_b128 v[222:225], v197 offset:36896
	s_waitcnt lgkmcnt(6)
	v_mfma_f32_32x32x16_bf16 v[52:67], v[202:205], v[218:221], v[52:67]
	s_waitcnt lgkmcnt(5)
	v_mfma_f32_32x32x16_bf16 v[36:51], v[202:205], v[226:229], v[36:51]
	s_waitcnt lgkmcnt(4)
	v_mfma_f32_32x32x16_bf16 v[4:19], v[210:213], v[226:229], v[4:19]
	s_waitcnt lgkmcnt(2)
	v_mfma_f32_32x32x16_bf16 v[36:51], v[206:209], v[230:233], v[36:51]
	s_waitcnt lgkmcnt(1)
	v_mfma_f32_32x32x16_bf16 v[4:19], v[214:217], v[230:233], v[4:19]
	ds_read_b128 v[230:233], v197 offset:41568
	ds_read_b128 v[202:205], v196 offset:4672
	v_mfma_f32_32x32x16_bf16 v[20:35], v[210:213], v[218:221], v[20:35]
	ds_read_b128 v[218:221], v196 offset:4704
	ds_read_b128 v[210:213], v196 offset:64
	s_waitcnt lgkmcnt(4)
	v_mfma_f32_32x32x16_bf16 v[52:67], v[206:209], v[222:225], v[52:67]
	ds_read_b128 v[226:229], v197 offset:36960
	ds_read_b128 v[206:209], v197 offset:41536
	v_mfma_f32_32x32x16_bf16 v[20:35], v[214:217], v[222:225], v[20:35]
	s_setprio 0
	ds_read_b128 v[222:225], v197 offset:36928
	ds_read_b128 v[214:217], v196 offset:96
	s_waitcnt lgkmcnt(1)
	v_mfma_f32_32x32x16_bf16 v[52:67], v[210:213], v[222:225], v[52:67]
	s_waitcnt vmcnt(15)
	ds_write_b128 v167, v[132:135]
	v_mfma_f32_32x32x16_bf16 v[36:51], v[210:213], v[206:209], v[36:51]
	s_waitcnt vmcnt(14)
	ds_write_b128 v167, v[136:139] offset:36864
	v_mfma_f32_32x32x16_bf16 v[20:35], v[202:205], v[222:225], v[20:35]
	s_waitcnt vmcnt(13)
	ds_write_b128 v190, v[140:143]
	v_mfma_f32_32x32x16_bf16 v[4:19], v[202:205], v[206:209], v[4:19]
	s_waitcnt vmcnt(12)
	ds_write_b128 v190, v[198:201] offset:36864
	s_waitcnt lgkmcnt(4)
	v_mfma_f32_32x32x16_bf16 v[52:67], v[214:217], v[226:229], v[52:67]
	s_waitcnt vmcnt(11)
	ds_write_b128 v191, v[174:177]
	v_mfma_f32_32x32x16_bf16 v[36:51], v[214:217], v[230:233], v[36:51]
	s_waitcnt vmcnt(10)
	ds_write_b128 v191, v[178:181] offset:36864
	v_mfma_f32_32x32x16_bf16 v[20:35], v[218:221], v[226:229], v[20:35]
	s_waitcnt vmcnt(9)
	ds_write_b128 v192, v[242:245]
	v_mfma_f32_32x32x16_bf16 v[4:19], v[218:221], v[230:233], v[4:19]
	s_waitcnt vmcnt(8)
	ds_write_b128 v192, v[246:249] offset:36864
	s_waitcnt lgkmcnt(0)
	s_barrier
; template <class Epi, class ColV>
; DI void gemm_tile(const bf16_t* __restrict__ A, int lda, const bf16_t* __restrict__ Bt, int ldb, int K, int m0, int n0, unsigned char* smem, Epi epi, ColV colv, const bf16_t* __restrict__ HYT = nullptr) {
;     ...
;     auto step = [&](int kt, u32x4 (&ldset)[8], const u32x4 (&stset)[8]) {
;         const int buf = kt & 1;
;         if (kt + 2 < nk) gload(ldset, kt + 2);
;         const bf16_t* Ab = As + (buf * 128 + 64 * wr + li) * LS + 8 * lh;
;         const bf16_t* Bb = Bs + (buf * 128 + 64 * wc + li) * LS + 8 * lh;
;         bf16x8 fa[2][2], fb[2][2], ga[2][2], gb[2][2];
; #pragma unroll
;         for (int k2 = 0; k2 < 2; ++k2) { fa[k2][0] = ld8(Ab + 16 * k2); fa[k2][1] = ld8(Ab + 32 * LS + 16 * k2); fb[k2][0] = ld8(Bb + 16 * k2); fb[k2][1] = ld8(Bb + 32 * LS + 16 * k2); }
;         __builtin_amdgcn_sched_barrier(0);
; #pragma unroll
;         for (int k2 = 0; k2 < 2; ++k2) {
;             acc[0][0] = MFMA(fa[k2][0], fb[k2][0], acc[0][0]); acc[0][1] = MFMA(fa[k2][0], fb[k2][1], acc[0][1]);
;             acc[1][0] = MFMA(fa[k2][1], fb[k2][0], acc[1][0]); acc[1][1] = MFMA(fa[k2][1], fb[k2][1], acc[1][1]);
;         }
; #pragma unroll
;         for (int k2 = 0; k2 < 2; ++k2) { const int ks = 2 + k2; ga[k2][0] = ld8(Ab + 16 * ks); ga[k2][1] = ld8(Ab + 32 * LS + 16 * ks); gb[k2][0] = ld8(Bb + 16 * ks); gb[k2][1] = ld8(Bb + 32 * LS + 16 * ks); }
; #pragma unroll
;         for (int k2 = 0; k2 < 2; ++k2) {
;             acc[0][0] = MFMA(ga[k2][0], gb[k2][0], acc[0][0]); acc[0][1] = MFMA(ga[k2][0], gb[k2][1], acc[0][1]);
;             acc[1][0] = MFMA(ga[k2][1], gb[k2][0], acc[1][0]); acc[1][1] = MFMA(ga[k2][1], gb[k2][1], acc[1][1]);
;         }
;         if (kt + 1 < nk) sstore(stset, buf ^ 1, kt + 1);
; #pragma unroll
;         for (int i = 0; i < 8; ++i) { __builtin_amdgcn_sched_group_barrier(0x008, 1, 0); __builtin_amdgcn_sched_group_barrier(0x100, 1, 0); }
; #pragma unroll
;         for (int i = 0; i < 8; ++i) { __builtin_amdgcn_sched_group_barrier(0x008, 1, 0); __builtin_amdgcn_sched_group_barrier(0x200, 1, 0); }
;         __builtin_amdgcn_sched_barrier(0);
;         __syncthreads();
;     };
;     gload(R0, 0); gload(R1, 1);
;     sstore(R0, 0, 0); __syncthreads();
;     for (int kt = 0; kt < nk; kt += 2) {
;         step(kt, R0, R1);
;         if (kt + 1 < nk) step(kt + 1, R1, R0);
;     }
	s_setprio 1
	ds_read_b128 v[202:205], v194
	ds_read_b128 v[218:221], v195 offset:36864
	ds_read_b128 v[226:229], v195 offset:41472
	ds_read_b128 v[210:213], v194 offset:4608
	ds_read_b128 v[206:209], v194 offset:32
	ds_read_b128 v[230:233], v195 offset:41504
	ds_read_b128 v[214:217], v194 offset:4640
	ds_read_b128 v[222:225], v195 offset:36896
	s_waitcnt lgkmcnt(6)
	v_mfma_f32_32x32x16_bf16 v[52:67], v[202:205], v[218:221], v[52:67]
	s_waitcnt lgkmcnt(5)
	v_mfma_f32_32x32x16_bf16 v[36:51], v[202:205], v[226:229], v[36:51]
	s_waitcnt lgkmcnt(4)
	v_mfma_f32_32x32x16_bf16 v[4:19], v[210:213], v[226:229], v[4:19]
	s_waitcnt lgkmcnt(2)
	v_mfma_f32_32x32x16_bf16 v[36:51], v[206:209], v[230:233], v[36:51]
	s_waitcnt lgkmcnt(1)
	v_mfma_f32_32x32x16_bf16 v[4:19], v[214:217], v[230:233], v[4:19]
	ds_read_b128 v[230:233], v195 offset:41568
	ds_read_b128 v[202:205], v194 offset:4672
	v_mfma_f32_32x32x16_bf16 v[20:35], v[210:213], v[218:221], v[20:35]
	ds_read_b128 v[218:221], v194 offset:4704
	ds_read_b128 v[210:213], v194 offset:64
	s_waitcnt lgkmcnt(4)
	v_mfma_f32_32x32x16_bf16 v[52:67], v[206:209], v[222:225], v[52:67]
	ds_read_b128 v[226:229], v195 offset:36960
	ds_read_b128 v[206:209], v195 offset:41536
	v_mfma_f32_32x32x16_bf16 v[20:35], v[214:217], v[222:225], v[20:35]
	s_setprio 0
	ds_read_b128 v[222:225], v195 offset:36928
	ds_read_b128 v[214:217], v194 offset:96
	s_waitcnt lgkmcnt(1)
	v_mfma_f32_32x32x16_bf16 v[52:67], v[210:213], v[222:225], v[52:67]
	s_waitcnt vmcnt(7)
	ds_write_b128 v167, v[68:71] offset:18432
	v_mfma_f32_32x32x16_bf16 v[36:51], v[210:213], v[206:209], v[36:51]
	s_waitcnt vmcnt(6)
	ds_write_b128 v167, v[72:75] offset:55296
	v_mfma_f32_32x32x16_bf16 v[20:35], v[202:205], v[222:225], v[20:35]
	s_waitcnt vmcnt(5)
	ds_write_b128 v190, v[76:79] offset:18432
	v_mfma_f32_32x32x16_bf16 v[4:19], v[202:205], v[206:209], v[4:19]
	s_waitcnt vmcnt(4)
	ds_write_b128 v190, v[80:83] offset:55296
	s_waitcnt lgkmcnt(4)
	v_mfma_f32_32x32x16_bf16 v[52:67], v[214:217], v[226:229], v[52:67]
	s_waitcnt vmcnt(3)
	ds_write_b128 v191, v[84:87] offset:18432
	v_mfma_f32_32x32x16_bf16 v[36:51], v[214:217], v[230:233], v[36:51]
	s_waitcnt vmcnt(2)
	ds_write_b128 v191, v[88:91] offset:55296
	v_mfma_f32_32x32x16_bf16 v[20:35], v[218:221], v[226:229], v[20:35]
	s_waitcnt vmcnt(1)
	ds_write_b128 v192, v[92:95] offset:18432
	v_mfma_f32_32x32x16_bf16 v[4:19], v[218:221], v[230:233], v[4:19]
	s_waitcnt vmcnt(0)
	ds_write_b128 v192, v[104:107] offset:55296
	s_waitcnt lgkmcnt(0)
	s_barrier
	s_setprio 1
	ds_read_b128 v[202:205], v196
	ds_read_b128 v[218:221], v197 offset:36864
	ds_read_b128 v[226:229], v197 offset:41472
	ds_read_b128 v[210:213], v196 offset:4608
	ds_read_b128 v[206:209], v196 offset:32
	ds_read_b128 v[230:233], v197 offset:41504
	ds_read_b128 v[214:217], v196 offset:4640
	ds_read_b128 v[222:225], v197 offset:36896
	s_waitcnt lgkmcnt(6)
	v_mfma_f32_32x32x16_bf16 v[52:67], v[202:205], v[218:221], v[52:67]
	s_waitcnt lgkmcnt(5)
	v_mfma_f32_32x32x16_bf16 v[36:51], v[202:205], v[226:229], v[36:51]
	s_waitcnt lgkmcnt(4)
	v_mfma_f32_32x32x16_bf16 v[4:19], v[210:213], v[226:229], v[4:19]
	s_waitcnt lgkmcnt(2)
	v_mfma_f32_32x32x16_bf16 v[36:51], v[206:209], v[230:233], v[36:51]
	s_waitcnt lgkmcnt(1)
	v_mfma_f32_32x32x16_bf16 v[4:19], v[214:217], v[230:233], v[4:19]
	ds_read_b128 v[230:233], v197 offset:41568
	ds_read_b128 v[202:205], v196 offset:4672
	v_mfma_f32_32x32x16_bf16 v[20:35], v[210:213], v[218:221], v[20:35]
	ds_read_b128 v[218:221], v196 offset:4704
	ds_read_b128 v[210:213], v196 offset:64
	s_waitcnt lgkmcnt(4)
	v_mfma_f32_32x32x16_bf16 v[52:67], v[206:209], v[222:225], v[52:67]
	ds_read_b128 v[226:229], v197 offset:36960
	ds_read_b128 v[206:209], v197 offset:41536
	v_mfma_f32_32x32x16_bf16 v[20:35], v[214:217], v[222:225], v[20:35]
	s_setprio 0
	ds_read_b128 v[222:225], v197 offset:36928
	ds_read_b128 v[214:217], v196 offset:96
	s_waitcnt lgkmcnt(1)
	v_mfma_f32_32x32x16_bf16 v[52:67], v[210:213], v[222:225], v[52:67]
	v_mfma_f32_32x32x16_bf16 v[36:51], v[210:213], v[206:209], v[36:51]
	v_mfma_f32_32x32x16_bf16 v[20:35], v[202:205], v[222:225], v[20:35]
	v_mfma_f32_32x32x16_bf16 v[4:19], v[202:205], v[206:209], v[4:19]
	s_waitcnt lgkmcnt(0)
	v_mfma_f32_32x32x16_bf16 v[52:67], v[214:217], v[226:229], v[52:67]
	v_mfma_f32_32x32x16_bf16 v[36:51], v[214:217], v[230:233], v[36:51]
	v_mfma_f32_32x32x16_bf16 v[20:35], v[218:221], v[226:229], v[20:35]
	v_mfma_f32_32x32x16_bf16 v[4:19], v[218:221], v[230:233], v[4:19]
	s_waitcnt lgkmcnt(0)
	s_barrier
	s_setprio 1
	s_nop 7
	s_nop 3
	s_branch .LBB0_1555
